# LRU scan carries: in-row broadcasts via DPP row_newbcast instead of ds_bpermute LDS round trips (both passes), lgkmcnt waits recounted
# speedup vs baseline: 1.0042x; 1.0042x over previous
; #define LAS __attribute__((address_space(3)))
; template <int PASS> __device__ __forceinline__ void phase_lru(LAS unsigned char* lds, const bf16_t* Z, const bf16_t* WL, float* LSUM, const float* LCAR, bf16_t* RNN,
;                                                               int S, int tid, int lane, int wave, int G) {
;     ...
;                 for (int t = 0; t < 4; ++t) {
;                     f32x4 gr = (f32x4){0.f, 0.f, 0.f, 0.f}, gi = gr;
; #pragma unroll
;                     for (int s = 0; s < 4; ++s) { const bf16x8 bfr = *(const LAS bf16x8*)(lds + LRU_XC + off_b(16 * t + c, 4 * s + g4));
;                         gr = __builtin_amdgcn_mfma_f32_16x16x32_bf16(wf[0][s], bfr, gr, 0, 0, 0); gi = __builtin_amdgcn_mfma_f32_16x16x32_bf16(wf[1][s], bfr, gi, 0, 0, 0); }
;                     const f32x4 kba = kc[0 * 64 + lane], kbx = kc[1 * 64 + lane], ksp = kc[2 * 64 + lane];
;                     f32x4 av, hv;
; #pragma unroll
;                     for (int j = 0; j < 4; ++j) {
;                         const float rg = __builtin_amdgcn_rcpf(1.0f + __builtin_amdgcn_exp2f(fmaf(gr[j], -LOG2E, kba[j])));
;                         const float ig = __builtin_amdgcn_rcpf(1.0f + __builtin_amdgcn_exp2f(fmaf(gi[j], -LOG2E, kbx[j])));
;                         const float a_ = __builtin_amdgcn_exp2f(rg * ksp[j]);
;                         av[j] = a_; hv[j] = __builtin_amdgcn_sqrtf(fmaf(-a_, a_, 1.0f)) * (ig * xc[t][j]);
;                     }
;                     lru_scan4_fwd(av, hv);
.LBB0_182:
	ds_read_b128 v[92:95], v222 offset:18432
	ds_read_b128 v[100:103], v223 offset:18432
	s_waitcnt lgkmcnt(1)
	v_mfma_f32_16x16x32_bf16 v[96:99], v[4:7], v[92:95], 0
	v_mfma_f32_16x16x32_bf16 v[92:95], v[20:23], v[92:95], 0
	s_waitcnt lgkmcnt(0)
	v_mfma_f32_16x16x32_bf16 v[96:99], v[8:11], v[100:103], v[96:99]
	v_mfma_f32_16x16x32_bf16 v[92:95], v[24:27], v[100:103], v[92:95]
	ds_read_b128 v[100:103], v224 offset:18432
	s_waitcnt lgkmcnt(0)
	v_mfma_f32_16x16x32_bf16 v[96:99], v[12:15], v[100:103], v[96:99]
	v_mfma_f32_16x16x32_bf16 v[92:95], v[28:31], v[100:103], v[92:95]
	ds_read_b128 v[100:103], v225 offset:18432
	ds_read_b128 v[164:167], v203 offset:36864
	ds_read_b128 v[168:171], v203 offset:37888
	s_waitcnt lgkmcnt(2)
	v_mfma_f32_16x16x32_bf16 v[96:99], v[16:19], v[100:103], v[96:99]
	v_mfma_f32_16x16x32_bf16 v[92:95], v[32:35], v[100:103], v[92:95]
	s_waitcnt lgkmcnt(1)
	s_nop 5
	v_fmamk_f32 v1, v96, 0xbfb8aa3b, v164
	v_exp_f32_e32 v1, v1
	v_fmamk_f32 v96, v97, 0xbfb8aa3b, v165
	ds_read_b128 v[100:103], v203 offset:38912
	v_exp_f32_e32 v96, v96
	v_add_f32_e32 v1, 1.0, v1
	v_rcp_f32_e32 v1, v1
	s_waitcnt lgkmcnt(1)
	v_fmamk_f32 v92, v92, 0xbfb8aa3b, v168
	v_add_f32_e32 v96, 1.0, v96
	v_exp_f32_e32 v92, v92
	v_rcp_f32_e32 v96, v96
	s_waitcnt lgkmcnt(0)
	v_mul_f32_e32 v1, v100, v1
	v_exp_f32_e32 v1, v1
	v_add_f32_e32 v92, 1.0, v92
	v_mul_f32_e32 v96, v101, v96
	v_rcp_f32_e32 v92, v92
	v_exp_f32_e32 v101, v96
	v_fma_f32 v96, -v1, v1, 1.0
	v_fmamk_f32 v93, v93, 0xbfb8aa3b, v169
	v_sqrt_f32_e32 v96, v96
	v_exp_f32_e32 v93, v93
	v_mul_f32_e32 v92, v148, v92
	v_fma_f32 v97, -v101, v101, 1.0
	v_mul_f32_e32 v104, v92, v96
	v_fmamk_f32 v92, v98, 0xbfb8aa3b, v166
	v_add_f32_e32 v93, 1.0, v93
	v_exp_f32_e32 v92, v92
	v_rcp_f32_e32 v93, v93
	v_fmamk_f32 v94, v94, 0xbfb8aa3b, v170
	v_sqrt_f32_e32 v97, v97
	v_exp_f32_e32 v94, v94
	v_add_f32_e32 v92, 1.0, v92
	v_mul_f32_e32 v93, v149, v93
	v_rcp_f32_e32 v92, v92
	v_fmac_f32_e32 v167, 0xbfb8aa3b, v99
	v_mul_f32_e32 v107, v93, v97
	v_add_f32_e32 v93, 1.0, v94
	v_exp_f32_e32 v94, v167
	v_mul_f32_e32 v92, v102, v92
	v_exp_f32_e32 v105, v92
	v_rcp_f32_e32 v92, v93
	v_add_f32_e32 v93, 1.0, v94
	v_rcp_f32_e32 v93, v93
	v_fmac_f32_e32 v171, 0xbfb8aa3b, v95
	v_exp_f32_e32 v95, v171
	v_fma_f32 v94, -v105, v105, 1.0
	v_mul_f32_e32 v93, v103, v93
	v_exp_f32_e32 v106, v93
	v_sqrt_f32_e32 v93, v94
	v_add_f32_e32 v94, 1.0, v95
	v_rcp_f32_e32 v94, v94
	v_fma_f32 v95, -v106, v106, 1.0
	v_sqrt_f32_e32 v95, v95
	v_mul_f32_e32 v92, v146, v92
	v_mul_f32_e32 v100, v92, v93
	v_mul_f32_e32 v92, v147, v94
	v_mul_f32_e32 v103, v92, v95
	v_or_b32_e32 v92, v202, v193
	s_nop 1
	v_fmac_f32_dpp v104, v104, v1 row_shr:1 row_mask:0xf bank_mask:0xf
	v_fmac_f32_dpp v107, v107, v101 row_shr:1 row_mask:0xf bank_mask:0xf
	v_fmac_f32_dpp v100, v100, v105 row_shr:1 row_mask:0xf bank_mask:0xf
	v_fmac_f32_dpp v103, v103, v106 row_shr:1 row_mask:0xf bank_mask:0xf
	v_mul_f32_dpp v1, v1, v1 row_shr:1 row_mask:0xf bank_mask:0xf
	v_mul_f32_dpp v101, v101, v101 row_shr:1 row_mask:0xf bank_mask:0xf
	v_mul_f32_dpp v105, v105, v105 row_shr:1 row_mask:0xf bank_mask:0xf
	v_mul_f32_dpp v106, v106, v106 row_shr:1 row_mask:0xf bank_mask:0xf
	v_fmac_f32_dpp v104, v104, v1 row_shr:2 row_mask:0xf bank_mask:0xf
	v_fmac_f32_dpp v107, v107, v101 row_shr:2 row_mask:0xf bank_mask:0xf
	v_fmac_f32_dpp v100, v100, v105 row_shr:2 row_mask:0xf bank_mask:0xf
	v_fmac_f32_dpp v103, v103, v106 row_shr:2 row_mask:0xf bank_mask:0xf
	v_mul_f32_dpp v1, v1, v1 row_shr:2 row_mask:0xf bank_mask:0xf
	v_mul_f32_dpp v101, v101, v101 row_shr:2 row_mask:0xf bank_mask:0xf
	v_mul_f32_dpp v105, v105, v105 row_shr:2 row_mask:0xf bank_mask:0xf
	v_mul_f32_dpp v106, v106, v106 row_shr:2 row_mask:0xf bank_mask:0xf
	v_fmac_f32_dpp v104, v104, v1 row_shr:4 row_mask:0xf bank_mask:0xf
	v_fmac_f32_dpp v107, v107, v101 row_shr:4 row_mask:0xf bank_mask:0xf
	v_fmac_f32_dpp v100, v100, v105 row_shr:4 row_mask:0xf bank_mask:0xf
	v_fmac_f32_dpp v103, v103, v106 row_shr:4 row_mask:0xf bank_mask:0xf
	v_mul_f32_dpp v1, v1, v1 row_shr:4 row_mask:0xf bank_mask:0xf
	v_mul_f32_dpp v101, v101, v101 row_shr:4 row_mask:0xf bank_mask:0xf
	v_mul_f32_dpp v105, v105, v105 row_shr:4 row_mask:0xf bank_mask:0xf
	v_mul_f32_dpp v106, v106, v106 row_shr:4 row_mask:0xf bank_mask:0xf
	v_fmac_f32_dpp v104, v104, v1 row_shr:8 row_mask:0xf bank_mask:0xf
	v_fmac_f32_dpp v107, v107, v101 row_shr:8 row_mask:0xf bank_mask:0xf
	v_fmac_f32_dpp v100, v100, v105 row_shr:8 row_mask:0xf bank_mask:0xf
	v_fmac_f32_dpp v103, v103, v106 row_shr:8 row_mask:0xf bank_mask:0xf
	v_mul_f32_dpp v1, v1, v1 row_shr:8 row_mask:0xf bank_mask:0xf
	v_mul_f32_dpp v101, v101, v101 row_shr:8 row_mask:0xf bank_mask:0xf
	v_mul_f32_dpp v105, v105, v105 row_shr:8 row_mask:0xf bank_mask:0xf
	v_mul_f32_dpp v106, v106, v106 row_shr:8 row_mask:0xf bank_mask:0xf
	s_nop 1
	v_lshl_or_b32 v102, v92, 2, 60
	ds_read_b128 v[92:95], v222 offset:22528
	ds_read_b128 v[164:167], v223 offset:22528
	s_waitcnt lgkmcnt(1)
	v_mfma_f32_16x16x32_bf16 v[96:99], v[4:7], v[92:95], 0
	v_mfma_f32_16x16x32_bf16 v[92:95], v[20:23], v[92:95], 0
	s_waitcnt lgkmcnt(0)
	v_mfma_f32_16x16x32_bf16 v[96:99], v[8:11], v[164:167], v[96:99]
	v_mfma_f32_16x16x32_bf16 v[92:95], v[24:27], v[164:167], v[92:95]
	ds_read_b128 v[164:167], v224 offset:22528
	s_waitcnt lgkmcnt(0)
	v_mfma_f32_16x16x32_bf16 v[96:99], v[12:15], v[164:167], v[96:99]
	v_mfma_f32_16x16x32_bf16 v[92:95], v[28:31], v[164:167], v[92:95]
	ds_read_b128 v[164:167], v225 offset:22528
	ds_read_b128 v[168:171], v203 offset:36864
	ds_read_b128 v[172:175], v203 offset:37888
	ds_read_b128 v[176:179], v203 offset:38912
	s_waitcnt lgkmcnt(3)
; #define LAS __attribute__((address_space(3)))
; template <int PASS> __device__ __forceinline__ void phase_lru(LAS unsigned char* lds, const bf16_t* Z, const bf16_t* WL, float* LSUM, const float* LCAR, bf16_t* RNN,
;                                                               int S, int tid, int lane, int wave, int G) {
;     ...
;                 for (int t = 0; t < 4; ++t) {
;                     f32x4 gr = (f32x4){0.f, 0.f, 0.f, 0.f}, gi = gr;
; #pragma unroll
;                     for (int s = 0; s < 4; ++s) { const bf16x8 bfr = *(const LAS bf16x8*)(lds + LRU_XC + off_b(16 * t + c, 4 * s + g4));
;                         gr = __builtin_amdgcn_mfma_f32_16x16x32_bf16(wf[0][s], bfr, gr, 0, 0, 0); gi = __builtin_amdgcn_mfma_f32_16x16x32_bf16(wf[1][s], bfr, gi, 0, 0, 0); }
;                     const f32x4 kba = kc[0 * 64 + lane], kbx = kc[1 * 64 + lane], ksp = kc[2 * 64 + lane];
;                     f32x4 av, hv;
; #pragma unroll
;                     for (int j = 0; j < 4; ++j) {
;                         const float rg = __builtin_amdgcn_rcpf(1.0f + __builtin_amdgcn_exp2f(fmaf(gr[j], -LOG2E, kba[j])));
;                         const float ig = __builtin_amdgcn_rcpf(1.0f + __builtin_amdgcn_exp2f(fmaf(gi[j], -LOG2E, kbx[j])));
;                         const float a_ = __builtin_amdgcn_exp2f(rg * ksp[j]);
;                         av[j] = a_; hv[j] = __builtin_amdgcn_sqrtf(fmaf(-a_, a_, 1.0f)) * (ig * xc[t][j]);
;                     }
;                     lru_scan4_fwd(av, hv);
	v_mfma_f32_16x16x32_bf16 v[96:99], v[16:19], v[164:167], v[96:99]
	v_mfma_f32_16x16x32_bf16 v[164:167], v[32:35], v[164:167], v[92:95]
	s_waitcnt lgkmcnt(2)
	s_nop 5
	v_fmamk_f32 v96, v96, 0xbfb8aa3b, v168
	v_exp_f32_e32 v96, v96
	v_fmac_f32_e32 v171, 0xbfb8aa3b, v99
	v_fmamk_f32 v94, v97, 0xbfb8aa3b, v169
	v_exp_f32_e32 v94, v94
	s_waitcnt lgkmcnt(1)
	v_fmamk_f32 v92, v164, 0xbfb8aa3b, v172
	v_exp_f32_e32 v92, v92
	v_fmamk_f32 v95, v165, 0xbfb8aa3b, v173
	v_add_f32_e32 v93, 1.0, v96
	v_exp_f32_e32 v95, v95
	v_rcp_f32_e32 v93, v93
	v_add_f32_e32 v92, 1.0, v92
	v_rcp_f32_e32 v96, v92
	v_add_f32_e32 v92, 1.0, v94
	v_rcp_f32_e32 v94, v92
	v_add_f32_e32 v92, 1.0, v95
	v_rcp_f32_e32 v95, v92
	s_waitcnt lgkmcnt(0)
	v_mul_f32_e32 v92, v176, v93
	v_exp_f32_e32 v92, v92
	v_mul_f32_e32 v93, v177, v94
	v_exp_f32_e32 v93, v93
	v_mul_f32_e32 v96, v152, v96
	v_fma_f32 v94, -v92, v92, 1.0
	v_sqrt_f32_e32 v94, v94
	v_fma_f32 v97, -v93, v93, 1.0
	v_sqrt_f32_e32 v97, v97
	v_mul_f32_e32 v95, v153, v95
	v_mul_f32_e32 v94, v96, v94
	v_fmamk_f32 v96, v98, 0xbfb8aa3b, v170
	v_fmamk_f32 v98, v166, 0xbfb8aa3b, v174
	v_exp_f32_e32 v98, v98
	v_exp_f32_e32 v96, v96
	v_mul_f32_e32 v95, v95, v97
	v_fmac_f32_e32 v175, 0xbfb8aa3b, v167
	v_add_f32_e32 v97, 1.0, v98
	v_exp_f32_e32 v98, v171
	v_add_f32_e32 v96, 1.0, v96
	v_rcp_f32_e32 v96, v96
	v_rcp_f32_e32 v99, v97
	v_add_f32_e32 v97, 1.0, v98
	v_rcp_f32_e32 v97, v97
	v_mul_f32_e32 v96, v178, v96
	v_exp_f32_e32 v96, v96
	v_exp_f32_e32 v164, v175
	v_mul_f32_e32 v97, v179, v97
	v_exp_f32_e32 v97, v97
	v_fma_f32 v98, -v96, v96, 1.0
	v_add_f32_e32 v164, 1.0, v164
	v_sqrt_f32_e32 v98, v98
	v_rcp_f32_e32 v164, v164
	v_fma_f32 v165, -v97, v97, 1.0
	v_sqrt_f32_e32 v165, v165
	v_mul_f32_e32 v99, v150, v99
	v_mul_f32_e32 v98, v99, v98
	v_mul_f32_e32 v99, v151, v164
	v_mul_f32_e32 v99, v99, v165
	s_nop 1
	v_fmac_f32_dpp v94, v94, v92 row_shr:1 row_mask:0xf bank_mask:0xf
	v_fmac_f32_dpp v95, v95, v93 row_shr:1 row_mask:0xf bank_mask:0xf
	v_fmac_f32_dpp v98, v98, v96 row_shr:1 row_mask:0xf bank_mask:0xf
	v_fmac_f32_dpp v99, v99, v97 row_shr:1 row_mask:0xf bank_mask:0xf
	v_mul_f32_dpp v92, v92, v92 row_shr:1 row_mask:0xf bank_mask:0xf
	v_mul_f32_dpp v93, v93, v93 row_shr:1 row_mask:0xf bank_mask:0xf
	v_mul_f32_dpp v96, v96, v96 row_shr:1 row_mask:0xf bank_mask:0xf
	v_mul_f32_dpp v97, v97, v97 row_shr:1 row_mask:0xf bank_mask:0xf
	v_fmac_f32_dpp v94, v94, v92 row_shr:2 row_mask:0xf bank_mask:0xf
	v_fmac_f32_dpp v95, v95, v93 row_shr:2 row_mask:0xf bank_mask:0xf
	v_fmac_f32_dpp v98, v98, v96 row_shr:2 row_mask:0xf bank_mask:0xf
	v_fmac_f32_dpp v99, v99, v97 row_shr:2 row_mask:0xf bank_mask:0xf
	v_mul_f32_dpp v92, v92, v92 row_shr:2 row_mask:0xf bank_mask:0xf
	v_mul_f32_dpp v93, v93, v93 row_shr:2 row_mask:0xf bank_mask:0xf
	v_mul_f32_dpp v96, v96, v96 row_shr:2 row_mask:0xf bank_mask:0xf
	v_mul_f32_dpp v97, v97, v97 row_shr:2 row_mask:0xf bank_mask:0xf
	v_fmac_f32_dpp v94, v94, v92 row_shr:4 row_mask:0xf bank_mask:0xf
	v_fmac_f32_dpp v95, v95, v93 row_shr:4 row_mask:0xf bank_mask:0xf
	v_fmac_f32_dpp v98, v98, v96 row_shr:4 row_mask:0xf bank_mask:0xf
	v_fmac_f32_dpp v99, v99, v97 row_shr:4 row_mask:0xf bank_mask:0xf
	v_mul_f32_dpp v92, v92, v92 row_shr:4 row_mask:0xf bank_mask:0xf
	v_mul_f32_dpp v93, v93, v93 row_shr:4 row_mask:0xf bank_mask:0xf
	v_mul_f32_dpp v96, v96, v96 row_shr:4 row_mask:0xf bank_mask:0xf
	v_mul_f32_dpp v97, v97, v97 row_shr:4 row_mask:0xf bank_mask:0xf
	v_fmac_f32_dpp v94, v94, v92 row_shr:8 row_mask:0xf bank_mask:0xf
	v_fmac_f32_dpp v95, v95, v93 row_shr:8 row_mask:0xf bank_mask:0xf
	v_fmac_f32_dpp v98, v98, v96 row_shr:8 row_mask:0xf bank_mask:0xf
	v_fmac_f32_dpp v99, v99, v97 row_shr:8 row_mask:0xf bank_mask:0xf
	v_mul_f32_dpp v92, v92, v92 row_shr:8 row_mask:0xf bank_mask:0xf
	v_mul_f32_dpp v93, v93, v93 row_shr:8 row_mask:0xf bank_mask:0xf
	v_mul_f32_dpp v96, v96, v96 row_shr:8 row_mask:0xf bank_mask:0xf
	v_mul_f32_dpp v97, v97, v97 row_shr:8 row_mask:0xf bank_mask:0xf
	s_nop 1
	ds_read_b128 v[164:167], v222 offset:26624
	ds_read_b128 v[172:175], v223 offset:26624
	s_waitcnt lgkmcnt(1)
	v_mfma_f32_16x16x32_bf16 v[168:171], v[4:7], v[164:167], 0
	v_mfma_f32_16x16x32_bf16 v[164:167], v[20:23], v[164:167], 0
	s_waitcnt lgkmcnt(0)
	v_mfma_f32_16x16x32_bf16 v[168:171], v[8:11], v[172:175], v[168:171]
	v_mfma_f32_16x16x32_bf16 v[164:167], v[24:27], v[172:175], v[164:167]
	ds_read_b128 v[172:175], v224 offset:26624
	s_waitcnt lgkmcnt(0)
	v_mfma_f32_16x16x32_bf16 v[168:171], v[12:15], v[172:175], v[168:171]
	v_mfma_f32_16x16x32_bf16 v[164:167], v[28:31], v[172:175], v[164:167]
	ds_read_b128 v[172:175], v225 offset:26624
	ds_read_b128 v[176:179], v203 offset:36864
	ds_read_b128 v[180:183], v203 offset:37888
	ds_read_b128 v[184:187], v203 offset:38912
	s_waitcnt lgkmcnt(3)
	v_mfma_f32_16x16x32_bf16 v[168:171], v[16:19], v[172:175], v[168:171]
	v_mfma_f32_16x16x32_bf16 v[172:175], v[32:35], v[172:175], v[164:167]
	s_waitcnt lgkmcnt(2)
	s_nop 5
	v_fmamk_f32 v168, v168, 0xbfb8aa3b, v176
	v_exp_f32_e32 v168, v168
	v_fmac_f32_e32 v179, 0xbfb8aa3b, v171
	v_fmamk_f32 v166, v169, 0xbfb8aa3b, v177
	v_exp_f32_e32 v166, v166
	s_waitcnt lgkmcnt(1)
	v_fmamk_f32 v164, v172, 0xbfb8aa3b, v180
	v_exp_f32_e32 v164, v164
	v_fmamk_f32 v167, v173, 0xbfb8aa3b, v181
	v_add_f32_e32 v165, 1.0, v168
	v_exp_f32_e32 v167, v167
	v_rcp_f32_e32 v165, v165
	v_add_f32_e32 v164, 1.0, v164
	v_rcp_f32_e32 v168, v164
	v_add_f32_e32 v164, 1.0, v166
	v_rcp_f32_e32 v166, v164
	v_add_f32_e32 v164, 1.0, v167
	v_rcp_f32_e32 v167, v164
	s_waitcnt lgkmcnt(0)
; #define LAS __attribute__((address_space(3)))
; template <int PASS> __device__ __forceinline__ void phase_lru(LAS unsigned char* lds, const bf16_t* Z, const bf16_t* WL, float* LSUM, const float* LCAR, bf16_t* RNN,
;                                                               int S, int tid, int lane, int wave, int G) {
;     ...
;                 for (int t = 0; t < 4; ++t) {
;                     f32x4 gr = (f32x4){0.f, 0.f, 0.f, 0.f}, gi = gr;
; #pragma unroll
;                     for (int s = 0; s < 4; ++s) { const bf16x8 bfr = *(const LAS bf16x8*)(lds + LRU_XC + off_b(16 * t + c, 4 * s + g4));
;                         gr = __builtin_amdgcn_mfma_f32_16x16x32_bf16(wf[0][s], bfr, gr, 0, 0, 0); gi = __builtin_amdgcn_mfma_f32_16x16x32_bf16(wf[1][s], bfr, gi, 0, 0, 0); }
;                     const f32x4 kba = kc[0 * 64 + lane], kbx = kc[1 * 64 + lane], ksp = kc[2 * 64 + lane];
;                     f32x4 av, hv;
; #pragma unroll
;                     for (int j = 0; j < 4; ++j) {
;                         const float rg = __builtin_amdgcn_rcpf(1.0f + __builtin_amdgcn_exp2f(fmaf(gr[j], -LOG2E, kba[j])));
;                         const float ig = __builtin_amdgcn_rcpf(1.0f + __builtin_amdgcn_exp2f(fmaf(gi[j], -LOG2E, kbx[j])));
;                         const float a_ = __builtin_amdgcn_exp2f(rg * ksp[j]);
;                         av[j] = a_; hv[j] = __builtin_amdgcn_sqrtf(fmaf(-a_, a_, 1.0f)) * (ig * xc[t][j]);
;                     }
;                     lru_scan4_fwd(av, hv);
	v_mul_f32_e32 v164, v184, v165
	v_exp_f32_e32 v164, v164
	v_mul_f32_e32 v165, v185, v166
	v_exp_f32_e32 v165, v165
	v_mul_f32_e32 v168, v158, v168
	v_fma_f32 v166, -v164, v164, 1.0
	v_sqrt_f32_e32 v166, v166
	v_fma_f32 v169, -v165, v165, 1.0
	v_sqrt_f32_e32 v169, v169
	v_mul_f32_e32 v167, v159, v167
	v_mul_f32_e32 v166, v168, v166
	v_fmamk_f32 v168, v170, 0xbfb8aa3b, v178
	v_fmamk_f32 v170, v174, 0xbfb8aa3b, v182
	v_exp_f32_e32 v170, v170
	v_exp_f32_e32 v168, v168
	v_mul_f32_e32 v167, v167, v169
	v_fmac_f32_e32 v183, 0xbfb8aa3b, v175
	v_add_f32_e32 v169, 1.0, v170
	v_exp_f32_e32 v170, v179
	v_add_f32_e32 v168, 1.0, v168
	v_rcp_f32_e32 v168, v168
	v_rcp_f32_e32 v171, v169
	v_add_f32_e32 v169, 1.0, v170
	v_rcp_f32_e32 v169, v169
	v_mul_f32_e32 v168, v186, v168
	v_exp_f32_e32 v168, v168
	v_exp_f32_e32 v172, v183
	v_mul_f32_e32 v169, v187, v169
	v_exp_f32_e32 v169, v169
	v_fma_f32 v170, -v168, v168, 1.0
	v_add_f32_e32 v172, 1.0, v172
	v_sqrt_f32_e32 v170, v170
	v_rcp_f32_e32 v172, v172
	v_fma_f32 v173, -v169, v169, 1.0
	v_sqrt_f32_e32 v173, v173
	v_mul_f32_e32 v171, v154, v171
	v_mul_f32_e32 v170, v171, v170
	v_mul_f32_e32 v171, v155, v172
	v_mul_f32_e32 v171, v171, v173
	s_nop 1
	v_fmac_f32_dpp v166, v166, v164 row_shr:1 row_mask:0xf bank_mask:0xf
	v_fmac_f32_dpp v167, v167, v165 row_shr:1 row_mask:0xf bank_mask:0xf
	v_fmac_f32_dpp v170, v170, v168 row_shr:1 row_mask:0xf bank_mask:0xf
	v_fmac_f32_dpp v171, v171, v169 row_shr:1 row_mask:0xf bank_mask:0xf
	v_mul_f32_dpp v164, v164, v164 row_shr:1 row_mask:0xf bank_mask:0xf
	v_mul_f32_dpp v165, v165, v165 row_shr:1 row_mask:0xf bank_mask:0xf
	v_mul_f32_dpp v168, v168, v168 row_shr:1 row_mask:0xf bank_mask:0xf
	v_mul_f32_dpp v169, v169, v169 row_shr:1 row_mask:0xf bank_mask:0xf
	v_fmac_f32_dpp v166, v166, v164 row_shr:2 row_mask:0xf bank_mask:0xf
	v_fmac_f32_dpp v167, v167, v165 row_shr:2 row_mask:0xf bank_mask:0xf
	v_fmac_f32_dpp v170, v170, v168 row_shr:2 row_mask:0xf bank_mask:0xf
	v_fmac_f32_dpp v171, v171, v169 row_shr:2 row_mask:0xf bank_mask:0xf
	v_mul_f32_dpp v164, v164, v164 row_shr:2 row_mask:0xf bank_mask:0xf
	v_mul_f32_dpp v165, v165, v165 row_shr:2 row_mask:0xf bank_mask:0xf
	v_mul_f32_dpp v168, v168, v168 row_shr:2 row_mask:0xf bank_mask:0xf
	v_mul_f32_dpp v169, v169, v169 row_shr:2 row_mask:0xf bank_mask:0xf
	v_fmac_f32_dpp v166, v166, v164 row_shr:4 row_mask:0xf bank_mask:0xf
	v_fmac_f32_dpp v167, v167, v165 row_shr:4 row_mask:0xf bank_mask:0xf
	v_fmac_f32_dpp v170, v170, v168 row_shr:4 row_mask:0xf bank_mask:0xf
	v_fmac_f32_dpp v171, v171, v169 row_shr:4 row_mask:0xf bank_mask:0xf
	v_mul_f32_dpp v164, v164, v164 row_shr:4 row_mask:0xf bank_mask:0xf
	v_mul_f32_dpp v165, v165, v165 row_shr:4 row_mask:0xf bank_mask:0xf
	v_mul_f32_dpp v168, v168, v168 row_shr:4 row_mask:0xf bank_mask:0xf
	v_mul_f32_dpp v169, v169, v169 row_shr:4 row_mask:0xf bank_mask:0xf
	v_fmac_f32_dpp v166, v166, v164 row_shr:8 row_mask:0xf bank_mask:0xf
	v_fmac_f32_dpp v167, v167, v165 row_shr:8 row_mask:0xf bank_mask:0xf
	v_fmac_f32_dpp v170, v170, v168 row_shr:8 row_mask:0xf bank_mask:0xf
	v_fmac_f32_dpp v171, v171, v169 row_shr:8 row_mask:0xf bank_mask:0xf
	v_mul_f32_dpp v164, v164, v164 row_shr:8 row_mask:0xf bank_mask:0xf
	v_mul_f32_dpp v165, v165, v165 row_shr:8 row_mask:0xf bank_mask:0xf
	v_mul_f32_dpp v168, v168, v168 row_shr:8 row_mask:0xf bank_mask:0xf
	v_mul_f32_dpp v169, v169, v169 row_shr:8 row_mask:0xf bank_mask:0xf
	s_nop 1
	ds_read_b128 v[172:175], v222 offset:30720
	ds_read_b128 v[180:183], v223 offset:30720
	s_waitcnt lgkmcnt(1)
	v_mfma_f32_16x16x32_bf16 v[176:179], v[4:7], v[172:175], 0
	v_mfma_f32_16x16x32_bf16 v[172:175], v[20:23], v[172:175], 0
	s_waitcnt lgkmcnt(0)
	v_mfma_f32_16x16x32_bf16 v[176:179], v[8:11], v[180:183], v[176:179]
	v_mfma_f32_16x16x32_bf16 v[172:175], v[24:27], v[180:183], v[172:175]
	ds_read_b128 v[180:183], v224 offset:30720
	s_waitcnt lgkmcnt(0)
	v_mfma_f32_16x16x32_bf16 v[176:179], v[12:15], v[180:183], v[176:179]
	v_mfma_f32_16x16x32_bf16 v[172:175], v[28:31], v[180:183], v[172:175]
	ds_read_b128 v[180:183], v225 offset:30720
	ds_read_b128 v[184:187], v203 offset:36864
	ds_read_b128 v[226:229], v203 offset:37888
	ds_read_b128 v[230:233], v203 offset:38912
	s_waitcnt lgkmcnt(3)
	v_mfma_f32_16x16x32_bf16 v[176:179], v[16:19], v[180:183], v[176:179]
	v_mfma_f32_16x16x32_bf16 v[180:183], v[32:35], v[180:183], v[172:175]
	s_waitcnt lgkmcnt(2)
	s_nop 5
	v_fmamk_f32 v176, v176, 0xbfb8aa3b, v184
	v_exp_f32_e32 v176, v176
	v_fmac_f32_e32 v187, 0xbfb8aa3b, v179
	v_fmamk_f32 v174, v177, 0xbfb8aa3b, v185
	v_exp_f32_e32 v174, v174
	s_waitcnt lgkmcnt(1)
	v_fmamk_f32 v172, v180, 0xbfb8aa3b, v226
	v_exp_f32_e32 v172, v172
	v_fmamk_f32 v175, v181, 0xbfb8aa3b, v227
	v_add_f32_e32 v173, 1.0, v176
	v_exp_f32_e32 v175, v175
	v_rcp_f32_e32 v173, v173
	v_add_f32_e32 v172, 1.0, v172
	v_rcp_f32_e32 v176, v172
	v_add_f32_e32 v172, 1.0, v174
	v_rcp_f32_e32 v174, v172
	v_add_f32_e32 v172, 1.0, v175
	v_rcp_f32_e32 v175, v172
	s_waitcnt lgkmcnt(0)
; template <int PASS> __device__ __forceinline__ void phase_lru(LAS unsigned char* lds, const bf16_t* Z, const bf16_t* WL, float* LSUM, const float* LCAR, bf16_t* RNN,
;                                                               int S, int tid, int lane, int wave, int G) {
;     ...
;                     for (int j = 0; j < 4; ++j) {
;                         const float rg = __builtin_amdgcn_rcpf(1.0f + __builtin_amdgcn_exp2f(fmaf(gr[j], -LOG2E, kba[j])));
;                         const float ig = __builtin_amdgcn_rcpf(1.0f + __builtin_amdgcn_exp2f(fmaf(gi[j], -LOG2E, kbx[j])));
;                         const float a_ = __builtin_amdgcn_exp2f(rg * ksp[j]);
;                         av[j] = a_; hv[j] = __builtin_amdgcn_sqrtf(fmaf(-a_, a_, 1.0f)) * (ig * xc[t][j]);
;                     }
;                     lru_scan4_fwd(av, hv);
; #pragma unroll
;                     for (int j = 0; j < 4; ++j) {
;                         const float hfull = fmaf(av[j], Hc[j], hv[j]);
;                         if (PASS == 1) hf[t][j] = hfull;
;                         Hc[j] = __shfl(hfull, (lane & 48) | 15);
;                         if (PASS == 0) Ac[j] *= __shfl(av[j], (lane & 48) | 15);
;                     }
;     ...
;                 for (int tt = 0; tt < 4; ++tt) { const int t = 3 - tt;
;                     f32x4 gr = (f32x4){0.f, 0.f, 0.f, 0.f}, gi = gr;
; #pragma unroll
;                     for (int s = 0; s < 4; ++s) { const bf16x8 bfr = *(const LAS bf16x8*)(lds + LRU_XC + off_b(16 * t + c, 4 * s + g4));
;                         gr = __builtin_amdgcn_mfma_f32_16x16x32_bf16(wf[2][s], bfr, gr, 0, 0, 0); gi = __builtin_amdgcn_mfma_f32_16x16x32_bf16(wf[3][s], bfr, gi, 0, 0, 0); }
;                     f32x4 ov;
;                     const f32x4 kba = kc[3 * 64 + lane], kbx = kc[4 * 64 + lane], ksp = kc[5 * 64 + lane];
;                     f32x4 av, hv;
; #pragma unroll
;                     for (int j = 0; j < 4; ++j) {
;                         const float rg = __builtin_amdgcn_rcpf(1.0f + __builtin_amdgcn_exp2f(fmaf(gr[j], -LOG2E, kba[j])));
;                         const float ig = __builtin_amdgcn_rcpf(1.0f + __builtin_amdgcn_exp2f(fmaf(gi[j], -LOG2E, kbx[j])));
;                         const float a_ = __builtin_amdgcn_exp2f(rg * ksp[j]);
;                         av[j] = a_; hv[j] = __builtin_amdgcn_sqrtf(fmaf(-a_, a_, 1.0f)) * (ig * xc[t][j]);
	v_mul_f32_e32 v172, v230, v173
	v_exp_f32_e32 v172, v172
	v_mul_f32_e32 v173, v231, v174
	v_exp_f32_e32 v173, v173
	v_mul_f32_e32 v176, v88, v176
	v_fma_f32 v174, -v172, v172, 1.0
	v_sqrt_f32_e32 v174, v174
	v_fma_f32 v177, -v173, v173, 1.0
	v_sqrt_f32_e32 v177, v177
	v_mul_f32_e32 v175, v89, v175
	v_mul_f32_e32 v174, v176, v174
	v_fmamk_f32 v176, v178, 0xbfb8aa3b, v186
	v_fmamk_f32 v178, v182, 0xbfb8aa3b, v228
	v_exp_f32_e32 v178, v178
	v_exp_f32_e32 v176, v176
	v_mul_f32_e32 v175, v175, v177
	v_fmac_f32_e32 v229, 0xbfb8aa3b, v183
	v_add_f32_e32 v177, 1.0, v178
	v_exp_f32_e32 v178, v187
	v_add_f32_e32 v176, 1.0, v176
	v_rcp_f32_e32 v176, v176
	v_rcp_f32_e32 v179, v177
	v_add_f32_e32 v177, 1.0, v178
	v_rcp_f32_e32 v177, v177
	v_mul_f32_e32 v176, v232, v176
	v_exp_f32_e32 v176, v176
	v_exp_f32_e32 v180, v229
	v_mul_f32_e32 v177, v233, v177
	v_exp_f32_e32 v177, v177
	v_fma_f32 v178, -v176, v176, 1.0
	v_add_f32_e32 v180, 1.0, v180
	v_sqrt_f32_e32 v178, v178
	v_rcp_f32_e32 v180, v180
	v_fma_f32 v181, -v177, v177, 1.0
	v_sqrt_f32_e32 v181, v181
	v_mul_f32_e32 v179, v90, v179
	v_mul_f32_e32 v178, v179, v178
	v_mul_f32_e32 v179, v91, v180
	v_mul_f32_e32 v179, v179, v181
	s_nop 1
	v_fmac_f32_dpp v174, v174, v172 row_shr:1 row_mask:0xf bank_mask:0xf
	v_fmac_f32_dpp v175, v175, v173 row_shr:1 row_mask:0xf bank_mask:0xf
	v_fmac_f32_dpp v178, v178, v176 row_shr:1 row_mask:0xf bank_mask:0xf
	v_fmac_f32_dpp v179, v179, v177 row_shr:1 row_mask:0xf bank_mask:0xf
	v_mul_f32_dpp v172, v172, v172 row_shr:1 row_mask:0xf bank_mask:0xf
	v_mul_f32_dpp v173, v173, v173 row_shr:1 row_mask:0xf bank_mask:0xf
	v_mul_f32_dpp v176, v176, v176 row_shr:1 row_mask:0xf bank_mask:0xf
	v_mul_f32_dpp v177, v177, v177 row_shr:1 row_mask:0xf bank_mask:0xf
	v_fmac_f32_dpp v174, v174, v172 row_shr:2 row_mask:0xf bank_mask:0xf
	v_fmac_f32_dpp v175, v175, v173 row_shr:2 row_mask:0xf bank_mask:0xf
	v_fmac_f32_dpp v178, v178, v176 row_shr:2 row_mask:0xf bank_mask:0xf
	v_fmac_f32_dpp v179, v179, v177 row_shr:2 row_mask:0xf bank_mask:0xf
	v_mul_f32_dpp v172, v172, v172 row_shr:2 row_mask:0xf bank_mask:0xf
	v_mul_f32_dpp v173, v173, v173 row_shr:2 row_mask:0xf bank_mask:0xf
	v_mul_f32_dpp v176, v176, v176 row_shr:2 row_mask:0xf bank_mask:0xf
	v_mul_f32_dpp v177, v177, v177 row_shr:2 row_mask:0xf bank_mask:0xf
	v_fmac_f32_dpp v174, v174, v172 row_shr:4 row_mask:0xf bank_mask:0xf
	v_fmac_f32_dpp v175, v175, v173 row_shr:4 row_mask:0xf bank_mask:0xf
	v_fmac_f32_dpp v178, v178, v176 row_shr:4 row_mask:0xf bank_mask:0xf
	v_fmac_f32_dpp v179, v179, v177 row_shr:4 row_mask:0xf bank_mask:0xf
	v_mul_f32_dpp v172, v172, v172 row_shr:4 row_mask:0xf bank_mask:0xf
	v_mul_f32_dpp v173, v173, v173 row_shr:4 row_mask:0xf bank_mask:0xf
	v_mul_f32_dpp v176, v176, v176 row_shr:4 row_mask:0xf bank_mask:0xf
	v_mul_f32_dpp v177, v177, v177 row_shr:4 row_mask:0xf bank_mask:0xf
	v_fmac_f32_dpp v174, v174, v172 row_shr:8 row_mask:0xf bank_mask:0xf
	v_fmac_f32_dpp v175, v175, v173 row_shr:8 row_mask:0xf bank_mask:0xf
	v_fmac_f32_dpp v178, v178, v176 row_shr:8 row_mask:0xf bank_mask:0xf
	v_fmac_f32_dpp v179, v179, v177 row_shr:8 row_mask:0xf bank_mask:0xf
	v_mul_f32_dpp v172, v172, v172 row_shr:8 row_mask:0xf bank_mask:0xf
	v_mul_f32_dpp v173, v173, v173 row_shr:8 row_mask:0xf bank_mask:0xf
	v_mul_f32_dpp v176, v176, v176 row_shr:8 row_mask:0xf bank_mask:0xf
	v_mul_f32_dpp v177, v177, v177 row_shr:8 row_mask:0xf bank_mask:0xf
	s_nop 1
	ds_read_b128 v[180:183], v222 offset:30720
	ds_read_b128 v[226:229], v223 offset:30720
	s_waitcnt vmcnt(1)
	v_fmac_f32_e32 v100, v105, v82
	v_fmac_f32_e32 v103, v106, v83
	s_nop 1
	v_mov_b32_dpp v238, v100 row_newbcast:15 row_mask:0xf bank_mask:0xf
	s_waitcnt lgkmcnt(1)
	v_mfma_f32_16x16x32_bf16 v[184:187], v[36:39], v[180:183], 0
	v_mov_b32_dpp v239, v103 row_newbcast:15 row_mask:0xf bank_mask:0xf
	v_fmac_f32_e32 v104, v1, v80
	v_fmac_f32_e32 v107, v101, v81
	v_mfma_f32_16x16x32_bf16 v[180:183], v[52:55], v[180:183], 0
	v_lshl_add_u64 v[80:81], s[88:89], 0, v[114:115]
	s_waitcnt lgkmcnt(0)
	v_mfma_f32_16x16x32_bf16 v[184:187], v[40:43], v[226:229], v[184:187]
	v_mfma_f32_16x16x32_bf16 v[180:183], v[56:59], v[226:229], v[180:183]
	ds_read_b128 v[226:229], v224 offset:30720
	s_waitcnt lgkmcnt(0)
	v_mfma_f32_16x16x32_bf16 v[184:187], v[44:47], v[226:229], v[184:187]
	v_mfma_f32_16x16x32_bf16 v[180:183], v[60:63], v[226:229], v[180:183]
	ds_read_b128 v[226:229], v225 offset:30720
	ds_read_b128 v[230:233], v203 offset:39936
	ds_read_b128 v[234:237], v203 offset:40960
	s_waitcnt lgkmcnt(2)
	v_mfma_f32_16x16x32_bf16 v[184:187], v[48:51], v[226:229], v[184:187]
	v_mfma_f32_16x16x32_bf16 v[180:183], v[64:67], v[226:229], v[180:183]
	s_waitcnt lgkmcnt(1)
	s_nop 5
	v_fmamk_f32 v184, v184, 0xbfb8aa3b, v230
	v_exp_f32_e32 v184, v184
	ds_read_b128 v[226:229], v203 offset:41984
	v_fmamk_f32 v185, v185, 0xbfb8aa3b, v231
	v_exp_f32_e32 v185, v185
	s_waitcnt lgkmcnt(1)
	v_fmamk_f32 v180, v180, 0xbfb8aa3b, v234
	v_exp_f32_e32 v180, v180
	v_fmamk_f32 v181, v181, 0xbfb8aa3b, v235
	v_add_f32_e32 v184, 1.0, v184
	v_exp_f32_e32 v181, v181
	v_rcp_f32_e32 v184, v184
	v_add_f32_e32 v180, 1.0, v180
	v_rcp_f32_e32 v230, v180
	v_add_f32_e32 v180, 1.0, v185
	v_rcp_f32_e32 v185, v180
	v_add_f32_e32 v180, 1.0, v181
	v_rcp_f32_e32 v231, v180
	s_waitcnt lgkmcnt(0)
; __device__ __forceinline__ float bflo(unsigned w) { return __uint_as_float(w << 16); }
; __device__ __forceinline__ float bfhi(unsigned w) { return __uint_as_float(w & 0xffff0000u); }
; template <int PASS> __device__ __forceinline__ void phase_lru(LAS unsigned char* lds, const bf16_t* Z, const bf16_t* WL, float* LSUM, const float* LCAR, bf16_t* RNN,
;                                                               int S, int tid, int lane, int wave, int G) {
;     ...
;                     for (int j = 0; j < 4; ++j) {
;                         const float rg = __builtin_amdgcn_rcpf(1.0f + __builtin_amdgcn_exp2f(fmaf(gr[j], -LOG2E, kba[j])));
;                         const float ig = __builtin_amdgcn_rcpf(1.0f + __builtin_amdgcn_exp2f(fmaf(gi[j], -LOG2E, kbx[j])));
;                         const float a_ = __builtin_amdgcn_exp2f(rg * ksp[j]);
;                         av[j] = a_; hv[j] = __builtin_amdgcn_sqrtf(fmaf(-a_, a_, 1.0f)) * (ig * xc[t][j]);
;                     }
;                     lru_scan4_bwd(av, hv);
; #pragma unroll
;                     for (int j = 0; j < 4; ++j) {
;                         const float hfull = fmaf(av[j], Hc[j], hv[j]);
;                         Hc[j] = __shfl(hfull, lane & 48);
;                         if (PASS == 0) Ac[j] *= __shfl(av[j], lane & 48);
;                         if (PASS == 1) { const unsigned rw = j < 2 ? ryr[t].x : ryr[t].y; const float y = (j & 1) ? bfhi(rw) : bflo(rw);
;                             const float ge = y * __builtin_amdgcn_rcpf(1.0f + __builtin_amdgcn_exp2f((-2.3022082f * y) * fmaf(0.044715f * y, y, 1.0f)));
;                             ov[j] = (hf[t][j] + hfull) * ge; }
	v_mul_f32_e32 v180, v226, v184
	v_exp_f32_e32 v180, v180
	v_mul_f32_e32 v88, v88, v230
	v_mul_f32_e32 v181, v227, v185
	v_exp_f32_e32 v181, v181
	v_fma_f32 v184, -v180, v180, 1.0
	v_sqrt_f32_e32 v184, v184
	v_fmamk_f32 v182, v182, 0xbfb8aa3b, v236
	v_fma_f32 v185, -v181, v181, 1.0
	v_sqrt_f32_e32 v185, v185
	v_mul_f32_e32 v88, v88, v184
	v_fmamk_f32 v184, v186, 0xbfb8aa3b, v232
	v_exp_f32_e32 v184, v184
	v_exp_f32_e32 v182, v182
	v_fmac_f32_e32 v233, 0xbfb8aa3b, v187
	v_exp_f32_e32 v186, v233
	v_add_f32_e32 v184, 1.0, v184
	v_rcp_f32_e32 v184, v184
	v_mul_f32_e32 v89, v89, v231
	v_mul_f32_e32 v89, v89, v185
	v_add_f32_e32 v185, 1.0, v182
	v_mul_f32_e32 v182, v228, v184
	v_rcp_f32_e32 v184, v185
	v_add_f32_e32 v185, 1.0, v186
	v_rcp_f32_e32 v185, v185
	v_exp_f32_e32 v182, v182
	v_fmac_f32_e32 v237, 0xbfb8aa3b, v183
	v_exp_f32_e32 v187, v237
	v_mul_f32_e32 v183, v229, v185
	v_exp_f32_e32 v183, v183
	v_fma_f32 v186, -v182, v182, 1.0
	v_sqrt_f32_e32 v185, v186
	v_add_f32_e32 v186, 1.0, v187
	v_rcp_f32_e32 v186, v186
	v_fma_f32 v187, -v183, v183, 1.0
	v_sqrt_f32_e32 v187, v187
	v_mul_f32_e32 v90, v90, v184
	v_mul_f32_e32 v228, v90, v185
	v_mul_f32_e32 v90, v91, v186
	v_mul_f32_e32 v229, v90, v187
	s_nop 1
	v_fmac_f32_dpp v88, v88, v180 row_shl:1 row_mask:0xf bank_mask:0xf
	v_fmac_f32_dpp v89, v89, v181 row_shl:1 row_mask:0xf bank_mask:0xf
	v_fmac_f32_dpp v228, v228, v182 row_shl:1 row_mask:0xf bank_mask:0xf
	v_fmac_f32_dpp v229, v229, v183 row_shl:1 row_mask:0xf bank_mask:0xf
	v_mul_f32_dpp v180, v180, v180 row_shl:1 row_mask:0xf bank_mask:0xf
	v_mul_f32_dpp v181, v181, v181 row_shl:1 row_mask:0xf bank_mask:0xf
	v_mul_f32_dpp v182, v182, v182 row_shl:1 row_mask:0xf bank_mask:0xf
	v_mul_f32_dpp v183, v183, v183 row_shl:1 row_mask:0xf bank_mask:0xf
	v_fmac_f32_dpp v88, v88, v180 row_shl:2 row_mask:0xf bank_mask:0xf
	v_fmac_f32_dpp v89, v89, v181 row_shl:2 row_mask:0xf bank_mask:0xf
	v_fmac_f32_dpp v228, v228, v182 row_shl:2 row_mask:0xf bank_mask:0xf
	v_fmac_f32_dpp v229, v229, v183 row_shl:2 row_mask:0xf bank_mask:0xf
	v_mul_f32_dpp v180, v180, v180 row_shl:2 row_mask:0xf bank_mask:0xf
	v_mul_f32_dpp v181, v181, v181 row_shl:2 row_mask:0xf bank_mask:0xf
	v_mul_f32_dpp v182, v182, v182 row_shl:2 row_mask:0xf bank_mask:0xf
	v_mul_f32_dpp v183, v183, v183 row_shl:2 row_mask:0xf bank_mask:0xf
	v_fmac_f32_dpp v88, v88, v180 row_shl:4 row_mask:0xf bank_mask:0xf
	v_fmac_f32_dpp v89, v89, v181 row_shl:4 row_mask:0xf bank_mask:0xf
	v_fmac_f32_dpp v228, v228, v182 row_shl:4 row_mask:0xf bank_mask:0xf
	v_fmac_f32_dpp v229, v229, v183 row_shl:4 row_mask:0xf bank_mask:0xf
	v_mul_f32_dpp v180, v180, v180 row_shl:4 row_mask:0xf bank_mask:0xf
	v_mul_f32_dpp v181, v181, v181 row_shl:4 row_mask:0xf bank_mask:0xf
	v_mul_f32_dpp v182, v182, v182 row_shl:4 row_mask:0xf bank_mask:0xf
	v_mul_f32_dpp v183, v183, v183 row_shl:4 row_mask:0xf bank_mask:0xf
	v_fmac_f32_dpp v88, v88, v180 row_shl:8 row_mask:0xf bank_mask:0xf
	v_fmac_f32_dpp v89, v89, v181 row_shl:8 row_mask:0xf bank_mask:0xf
	v_fmac_f32_dpp v228, v228, v182 row_shl:8 row_mask:0xf bank_mask:0xf
	v_fmac_f32_dpp v229, v229, v183 row_shl:8 row_mask:0xf bank_mask:0xf
	v_mul_f32_dpp v180, v180, v180 row_shl:8 row_mask:0xf bank_mask:0xf
	v_mul_f32_dpp v181, v181, v181 row_shl:8 row_mask:0xf bank_mask:0xf
	v_mul_f32_dpp v182, v182, v182 row_shl:8 row_mask:0xf bank_mask:0xf
	v_mul_f32_dpp v183, v183, v183 row_shl:8 row_mask:0xf bank_mask:0xf
	s_nop 1
	v_or_b32_e32 v90, v193, v204
	s_waitcnt vmcnt(0)
	v_pk_fma_f32 v[184:185], v[180:181], v[84:85], v[88:89]
	v_lshlrev_b32_e32 v84, 16, v162
	v_and_b32_e32 v85, 0xffff0000, v162
	v_mul_f32_e32 v89, 0x3d372713, v84
	v_lshlrev_b32_e32 v226, 2, v90
	v_mul_f32_e32 v88, 0xc0135761, v84
	v_fma_f32 v89, v89, v84, 1.0
	v_mul_f32_e32 v90, 0x3d372713, v85
	v_mul_f32_e32 v88, v88, v89
	v_mul_f32_e32 v89, 0xc0135761, v85
	v_fma_f32 v90, v90, v85, 1.0
	v_mul_f32_e32 v89, v89, v90
	v_exp_f32_e32 v88, v88
	v_exp_f32_e32 v89, v89
	v_lshlrev_b32_e32 v180, 16, v163
	v_and_b32_e32 v181, 0xffff0000, v163
	v_mul_f32_e32 v162, 0x3d372713, v180
	v_mul_f32_e32 v91, 0xc0135761, v180
	v_fma_f32 v162, v162, v180, 1.0
	v_mul_f32_e32 v163, 0x3d372713, v181
	v_mul_f32_e32 v91, v91, v162
	v_mul_f32_e32 v162, 0xc0135761, v181
	v_fma_f32 v163, v163, v181, 1.0
	v_add_f32_e32 v88, 1.0, v88
	v_add_f32_e32 v89, 1.0, v89
	v_mul_f32_e32 v162, v162, v163
	v_rcp_f32_e32 v88, v88
	v_rcp_f32_e32 v89, v89
	v_exp_f32_e32 v91, v91
	v_exp_f32_e32 v162, v162
	v_pk_fma_f32 v[228:229], v[182:183], v[86:87], v[228:229]
	v_pk_mul_f32 v[186:187], v[88:89], v[84:85]
	v_add_f32_e32 v84, 1.0, v91
	v_add_f32_e32 v85, 1.0, v162
	v_rcp_f32_e32 v84, v84
	v_rcp_f32_e32 v85, v85
	v_and_b32_e32 v89, 0xffff0000, v161
	v_lshlrev_b32_e32 v234, 16, v157
	v_and_b32_e32 v235, 0xffff0000, v157
	v_pk_mul_f32 v[230:231], v[84:85], v[180:181]
	v_lshlrev_b32_e32 v84, 16, v160
	v_and_b32_e32 v85, 0xffff0000, v160
	v_mul_f32_e32 v87, 0x3d372713, v84
	v_mul_f32_e32 v86, 0xc0135761, v84
	v_fma_f32 v87, v87, v84, 1.0
	v_mul_f32_e32 v88, 0x3d372713, v85
	v_mul_f32_e32 v86, v86, v87
	v_mul_f32_e32 v87, 0xc0135761, v85
	v_fma_f32 v88, v88, v85, 1.0
	v_mul_f32_e32 v87, v87, v88
	v_exp_f32_e32 v86, v86
	v_exp_f32_e32 v87, v87
	v_lshlrev_b32_e32 v88, 16, v161
	v_mul_f32_e32 v161, 0x3d372713, v88
	v_mul_f32_e32 v160, 0xc0135761, v88
	v_fma_f32 v161, v161, v88, 1.0
	v_add_f32_e32 v86, 1.0, v86
	v_add_f32_e32 v87, 1.0, v87
	v_mul_f32_e32 v160, v160, v161
	v_mul_f32_e32 v161, 0x3d372713, v89
	v_rcp_f32_e32 v86, v86
	v_rcp_f32_e32 v87, v87
	v_exp_f32_e32 v180, v160
	v_mul_f32_e32 v160, 0xc0135761, v89
	v_fma_f32 v161, v161, v89, 1.0
	v_mul_f32_e32 v160, v160, v161
; __device__ __forceinline__ unsigned pk2(float lo, float hi) { return pg8::cvt_pk_bf16(lo, hi); }
; __device__ __forceinline__ float bflo(unsigned w) { return __uint_as_float(w << 16); }
; __device__ __forceinline__ float bfhi(unsigned w) { return __uint_as_float(w & 0xffff0000u); }
; template <int PASS> __device__ __forceinline__ void phase_lru(LAS unsigned char* lds, const bf16_t* Z, const bf16_t* WL, float* LSUM, const float* LCAR, bf16_t* RNN,
;                                                               int S, int tid, int lane, int wave, int G) {
;     ...
;                     for (int j = 0; j < 4; ++j) {
;                         const float hfull = fmaf(av[j], Hc[j], hv[j]);
;                         if (PASS == 1) hf[t][j] = hfull;
;                         Hc[j] = __shfl(hfull, (lane & 48) | 15);
;                         if (PASS == 0) Ac[j] *= __shfl(av[j], (lane & 48) | 15);
;     ...
; #pragma unroll
;                     for (int j = 0; j < 4; ++j) {
;                         const float hfull = fmaf(av[j], Hc[j], hv[j]);
;                         Hc[j] = __shfl(hfull, lane & 48);
;                         if (PASS == 0) Ac[j] *= __shfl(av[j], lane & 48);
;                         if (PASS == 1) { const unsigned rw = j < 2 ? ryr[t].x : ryr[t].y; const float y = (j & 1) ? bfhi(rw) : bflo(rw);
;                             const float ge = y * __builtin_amdgcn_rcpf(1.0f + __builtin_amdgcn_exp2f((-2.3022082f * y) * fmaf(0.044715f * y, y, 1.0f)));
;                             ov[j] = (hf[t][j] + hfull) * ge; }
;                     }
;                     if (PASS == 1) { u32x2 w; w.x = pk2(ov[0], ov[1]); w.y = pk2(ov[2], ov[3]); *(u32x2*)(RNN + (size_t)(t0 + 16 * t + c) * LW + ch0) = w; }
	v_exp_f32_e32 v181, v160
	v_pk_mul_f32 v[160:161], v[86:87], v[84:85]
	v_lshlrev_b32_e32 v86, 16, v156
	v_add_f32_e32 v84, 1.0, v180
	v_and_b32_e32 v87, 0xffff0000, v156
	v_mul_f32_e32 v180, 0x3d372713, v86
	v_add_f32_e32 v85, 1.0, v181
	v_mul_f32_e32 v156, 0xc0135761, v86
	v_fma_f32 v180, v180, v86, 1.0
	v_mul_f32_e32 v181, 0x3d372713, v87
	v_mul_f32_e32 v156, v156, v180
	v_mul_f32_e32 v180, 0xc0135761, v87
	v_fma_f32 v181, v181, v87, 1.0
	v_mul_f32_e32 v180, v180, v181
	v_exp_f32_e32 v156, v156
	v_exp_f32_e32 v180, v180
	v_mul_f32_e32 v181, 0x3d372713, v234
	v_mul_f32_e32 v157, 0xc0135761, v234
	v_fma_f32 v181, v181, v234, 1.0
	v_mul_f32_e32 v157, v157, v181
	v_mul_f32_e32 v182, 0x3d372713, v235
	v_exp_f32_e32 v181, v157
	v_mul_f32_e32 v157, 0xc0135761, v235
	v_fma_f32 v182, v182, v235, 1.0
	v_add_f32_e32 v156, 1.0, v156
	v_add_f32_e32 v180, 1.0, v180
	v_mul_f32_e32 v157, v157, v182
	v_rcp_f32_e32 v84, v84
	v_rcp_f32_e32 v85, v85
	v_rcp_f32_e32 v156, v156
	v_exp_f32_e32 v182, v157
	v_rcp_f32_e32 v157, v180
	v_add_f32_e32 v180, 1.0, v181
	v_rcp_f32_e32 v236, v180
	v_add_f32_e32 v180, 1.0, v182
	v_pk_mul_f32 v[182:183], v[84:85], v[88:89]
	v_pk_mul_f32 v[84:85], v[156:157], v[86:87]
	v_pk_fma_f32 v[86:87], v[96:97], v[238:239], v[98:99]
	s_nop 1
	v_mov_b32_dpp v88, v86 row_newbcast:15 row_mask:0xf bank_mask:0xf
	v_mov_b32_dpp v89, v87 row_newbcast:15 row_mask:0xf bank_mask:0xf
	v_mov_b32_dpp v98, v104 row_newbcast:15 row_mask:0xf bank_mask:0xf
	v_mov_b32_dpp v99, v107 row_newbcast:15 row_mask:0xf bank_mask:0xf
	v_rcp_f32_e32 v237, v180
	v_lshl_add_u64 v[232:233], s[88:89], 0, v[118:119]
	s_waitcnt lgkmcnt(0)
	v_pk_fma_f32 v[96:97], v[168:169], v[88:89], v[170:171]
	s_nop 1
	v_mov_b32_dpp v156, v96 row_newbcast:15 row_mask:0xf bank_mask:0xf
	v_mov_b32_dpp v157, v97 row_newbcast:15 row_mask:0xf bank_mask:0xf
	s_waitcnt lgkmcnt(0)
	v_pk_fma_f32 v[88:89], v[92:93], v[98:99], v[94:95]
	s_nop 1
	v_mov_b32_dpp v92, v88 row_newbcast:15 row_mask:0xf bank_mask:0xf
	v_mov_b32_dpp v93, v89 row_newbcast:15 row_mask:0xf bank_mask:0xf
	v_mov_b32_dpp v90, v184 row_newbcast:0 row_mask:0xf bank_mask:0xf
	s_waitcnt lgkmcnt(0)
	v_pk_fma_f32 v[94:95], v[176:177], v[156:157], v[178:179]
	v_lshlrev_b32_e32 v156, 16, v144
	v_pk_add_f32 v[94:95], v[94:95], v[228:229]
	v_and_b32_e32 v157, 0xffff0000, v144
	v_pk_mul_f32 v[94:95], v[230:231], v[94:95]
	v_mul_f32_e32 v1, 0xc0135761, v156
	v_cvt_pk_bf16_f32 v95, v94, v95
	v_mul_f32_e32 v94, 0x3d372713, v156
	v_fma_f32 v94, v94, v156, 1.0
	v_mul_f32_e32 v101, 0x3d372713, v157
	v_mul_f32_e32 v1, v1, v94
	v_mul_f32_e32 v94, 0xc0135761, v157
	v_fma_f32 v101, v101, v157, 1.0
	s_waitcnt lgkmcnt(0)
	v_pk_fma_f32 v[92:93], v[164:165], v[92:93], v[166:167]
	v_exp_f32_e32 v1, v1
	v_mul_f32_e32 v94, v94, v101
	v_mov_b32_dpp v98, v92 row_newbcast:15 row_mask:0xf bank_mask:0xf
	v_mov_b32_dpp v99, v93 row_newbcast:15 row_mask:0xf bank_mask:0xf
	v_exp_f32_e32 v94, v94
	v_add_f32_e32 v1, 1.0, v1
	v_rcp_f32_e32 v164, v1
	v_mov_b32_dpp v91, v185 row_newbcast:0 row_mask:0xf bank_mask:0xf
	v_add_f32_e32 v1, 1.0, v94
	s_waitcnt lgkmcnt(0)
	v_pk_fma_f32 v[98:99], v[172:173], v[98:99], v[174:175]
	v_rcp_f32_e32 v165, v1
	v_pk_add_f32 v[98:99], v[98:99], v[184:185]
	v_mov_b32_dpp v162, v228 row_newbcast:0 row_mask:0xf bank_mask:0xf
	v_pk_mul_f32 v[98:99], v[186:187], v[98:99]
	v_mov_b32_dpp v163, v229 row_newbcast:0 row_mask:0xf bank_mask:0xf
	v_cvt_pk_bf16_f32 v94, v98, v99
	v_lshl_add_u64 v[180:181], s[88:89], 0, v[116:117]
	v_pk_mul_f32 v[82:83], v[236:237], v[234:235]
	v_pk_mul_f32 v[156:157], v[164:165], v[156:157]
	global_store_dwordx2 v[232:233], v[94:95], off
	ds_read_b128 v[164:167], v222 offset:26624
	ds_read_b128 v[172:175], v223 offset:26624
	s_waitcnt lgkmcnt(1)
	v_mfma_f32_16x16x32_bf16 v[168:171], v[36:39], v[164:167], 0
	v_mfma_f32_16x16x32_bf16 v[164:167], v[52:55], v[164:167], 0
	s_waitcnt lgkmcnt(0)
	v_mfma_f32_16x16x32_bf16 v[168:171], v[40:43], v[172:175], v[168:171]
	v_mfma_f32_16x16x32_bf16 v[164:167], v[56:59], v[172:175], v[164:167]
	ds_read_b128 v[172:175], v224 offset:26624
	s_waitcnt lgkmcnt(0)
	v_mfma_f32_16x16x32_bf16 v[168:171], v[44:47], v[172:175], v[168:171]
	v_mfma_f32_16x16x32_bf16 v[164:167], v[60:63], v[172:175], v[164:167]
	ds_read_b128 v[172:175], v225 offset:26624
	ds_read_b128 v[176:179], v203 offset:39936
	ds_read_b128 v[184:187], v203 offset:40960
	s_waitcnt lgkmcnt(2)
	v_mfma_f32_16x16x32_bf16 v[168:171], v[48:51], v[172:175], v[168:171]
	v_mfma_f32_16x16x32_bf16 v[164:167], v[64:67], v[172:175], v[164:167]
	s_waitcnt lgkmcnt(1)
	s_nop 5
	v_fmamk_f32 v1, v168, 0xbfb8aa3b, v176
	v_exp_f32_e32 v1, v1
	ds_read_b128 v[172:175], v203 offset:41984
	v_fmamk_f32 v95, v169, 0xbfb8aa3b, v177
	v_exp_f32_e32 v95, v95
	s_waitcnt lgkmcnt(1)
	v_fmamk_f32 v94, v164, 0xbfb8aa3b, v184
	v_exp_f32_e32 v94, v94
	v_add_f32_e32 v1, 1.0, v1
	v_fmamk_f32 v98, v165, 0xbfb8aa3b, v185
	v_rcp_f32_e32 v1, v1
	v_exp_f32_e32 v98, v98
	v_add_f32_e32 v94, 1.0, v94
	v_rcp_f32_e32 v99, v94
	v_add_f32_e32 v94, 1.0, v95
	v_rcp_f32_e32 v95, v94
	v_add_f32_e32 v94, 1.0, v98
	s_waitcnt lgkmcnt(0)
; #define LAS __attribute__((address_space(3)))
; template <int PASS> __device__ __forceinline__ void phase_lru(LAS unsigned char* lds, const bf16_t* Z, const bf16_t* WL, float* LSUM, const float* LCAR, bf16_t* RNN,
;                                                               int S, int tid, int lane, int wave, int G) {
;     ...
;                 for (int tt = 0; tt < 4; ++tt) { const int t = 3 - tt;
;                     f32x4 gr = (f32x4){0.f, 0.f, 0.f, 0.f}, gi = gr;
; #pragma unroll
;                     for (int s = 0; s < 4; ++s) { const bf16x8 bfr = *(const LAS bf16x8*)(lds + LRU_XC + off_b(16 * t + c, 4 * s + g4));
;                         gr = __builtin_amdgcn_mfma_f32_16x16x32_bf16(wf[2][s], bfr, gr, 0, 0, 0); gi = __builtin_amdgcn_mfma_f32_16x16x32_bf16(wf[3][s], bfr, gi, 0, 0, 0); }
;                     f32x4 ov;
;                     const f32x4 kba = kc[3 * 64 + lane], kbx = kc[4 * 64 + lane], ksp = kc[5 * 64 + lane];
;                     f32x4 av, hv;
; #pragma unroll
;                     for (int j = 0; j < 4; ++j) {
;                         const float rg = __builtin_amdgcn_rcpf(1.0f + __builtin_amdgcn_exp2f(fmaf(gr[j], -LOG2E, kba[j])));
;                         const float ig = __builtin_amdgcn_rcpf(1.0f + __builtin_amdgcn_exp2f(fmaf(gi[j], -LOG2E, kbx[j])));
;                         const float a_ = __builtin_amdgcn_exp2f(rg * ksp[j]);
;                         av[j] = a_; hv[j] = __builtin_amdgcn_sqrtf(fmaf(-a_, a_, 1.0f)) * (ig * xc[t][j]);
;                     }
;                     lru_scan4_bwd(av, hv);
; #pragma unroll
;                     for (int j = 0; j < 4; ++j) {
;                         const float hfull = fmaf(av[j], Hc[j], hv[j]);
;                         Hc[j] = __shfl(hfull, lane & 48);
;                         if (PASS == 0) Ac[j] *= __shfl(av[j], lane & 48);
;                         if (PASS == 1) { const unsigned rw = j < 2 ? ryr[t].x : ryr[t].y; const float y = (j & 1) ? bfhi(rw) : bflo(rw);
;                             const float ge = y * __builtin_amdgcn_rcpf(1.0f + __builtin_amdgcn_exp2f((-2.3022082f * y) * fmaf(0.044715f * y, y, 1.0f)));
;                             ov[j] = (hf[t][j] + hfull) * ge; }
;                     }
;                     if (PASS == 1) { u32x2 w; w.x = pk2(ov[0], ov[1]); w.y = pk2(ov[2], ov[3]); *(u32x2*)(RNN + (size_t)(t0 + 16 * t + c) * LW + ch0) = w; }
	v_mul_f32_e32 v1, v172, v1
	v_rcp_f32_e32 v98, v94
	v_exp_f32_e32 v94, v1
	v_mul_f32_e32 v95, v173, v95
	v_mul_f32_e32 v1, v158, v99
	v_exp_f32_e32 v95, v95
	v_fma_f32 v99, -v94, v94, 1.0
	v_sqrt_f32_e32 v99, v99
	v_mul_f32_e32 v101, v159, v98
	v_fma_f32 v98, -v95, v95, 1.0
	v_sqrt_f32_e32 v102, v98
	v_mul_f32_e32 v98, v1, v99
	v_fmamk_f32 v1, v170, 0xbfb8aa3b, v178
	v_exp_f32_e32 v1, v1
	v_fmamk_f32 v99, v166, 0xbfb8aa3b, v186
	v_exp_f32_e32 v105, v99
	v_fmac_f32_e32 v179, 0xbfb8aa3b, v171
	v_add_f32_e32 v1, 1.0, v1
	v_rcp_f32_e32 v1, v1
	v_mul_f32_e32 v99, v101, v102
	v_exp_f32_e32 v102, v179
	v_add_f32_e32 v101, 1.0, v105
	v_mul_f32_e32 v1, v174, v1
	v_exp_f32_e32 v158, v1
	v_rcp_f32_e32 v1, v101
	v_add_f32_e32 v101, 1.0, v102
	v_rcp_f32_e32 v101, v101
	v_fmac_f32_e32 v187, 0xbfb8aa3b, v167
	v_exp_f32_e32 v105, v187
	v_fma_f32 v102, -v158, v158, 1.0
	v_mul_f32_e32 v101, v175, v101
	v_exp_f32_e32 v159, v101
	v_sqrt_f32_e32 v101, v102
	v_add_f32_e32 v102, 1.0, v105
	v_rcp_f32_e32 v102, v102
	v_fma_f32 v105, -v159, v159, 1.0
	v_sqrt_f32_e32 v105, v105
	v_mul_f32_e32 v1, v154, v1
	v_mul_f32_e32 v154, v1, v101
	v_mul_f32_e32 v1, v155, v102
	v_mul_f32_e32 v155, v1, v105
	s_nop 1
	v_fmac_f32_dpp v98, v98, v94 row_shl:1 row_mask:0xf bank_mask:0xf
	v_fmac_f32_dpp v99, v99, v95 row_shl:1 row_mask:0xf bank_mask:0xf
	v_fmac_f32_dpp v154, v154, v158 row_shl:1 row_mask:0xf bank_mask:0xf
	v_fmac_f32_dpp v155, v155, v159 row_shl:1 row_mask:0xf bank_mask:0xf
	v_mul_f32_dpp v94, v94, v94 row_shl:1 row_mask:0xf bank_mask:0xf
	v_mul_f32_dpp v95, v95, v95 row_shl:1 row_mask:0xf bank_mask:0xf
	v_mul_f32_dpp v158, v158, v158 row_shl:1 row_mask:0xf bank_mask:0xf
	v_mul_f32_dpp v159, v159, v159 row_shl:1 row_mask:0xf bank_mask:0xf
	v_fmac_f32_dpp v98, v98, v94 row_shl:2 row_mask:0xf bank_mask:0xf
	v_fmac_f32_dpp v99, v99, v95 row_shl:2 row_mask:0xf bank_mask:0xf
	v_fmac_f32_dpp v154, v154, v158 row_shl:2 row_mask:0xf bank_mask:0xf
	v_fmac_f32_dpp v155, v155, v159 row_shl:2 row_mask:0xf bank_mask:0xf
	v_mul_f32_dpp v94, v94, v94 row_shl:2 row_mask:0xf bank_mask:0xf
	v_mul_f32_dpp v95, v95, v95 row_shl:2 row_mask:0xf bank_mask:0xf
	v_mul_f32_dpp v158, v158, v158 row_shl:2 row_mask:0xf bank_mask:0xf
	v_mul_f32_dpp v159, v159, v159 row_shl:2 row_mask:0xf bank_mask:0xf
	v_fmac_f32_dpp v98, v98, v94 row_shl:4 row_mask:0xf bank_mask:0xf
	v_fmac_f32_dpp v99, v99, v95 row_shl:4 row_mask:0xf bank_mask:0xf
	v_fmac_f32_dpp v154, v154, v158 row_shl:4 row_mask:0xf bank_mask:0xf
	v_fmac_f32_dpp v155, v155, v159 row_shl:4 row_mask:0xf bank_mask:0xf
	v_mul_f32_dpp v94, v94, v94 row_shl:4 row_mask:0xf bank_mask:0xf
	v_mul_f32_dpp v95, v95, v95 row_shl:4 row_mask:0xf bank_mask:0xf
	v_mul_f32_dpp v158, v158, v158 row_shl:4 row_mask:0xf bank_mask:0xf
	v_mul_f32_dpp v159, v159, v159 row_shl:4 row_mask:0xf bank_mask:0xf
	v_fmac_f32_dpp v98, v98, v94 row_shl:8 row_mask:0xf bank_mask:0xf
	v_fmac_f32_dpp v99, v99, v95 row_shl:8 row_mask:0xf bank_mask:0xf
	v_fmac_f32_dpp v154, v154, v158 row_shl:8 row_mask:0xf bank_mask:0xf
	v_fmac_f32_dpp v155, v155, v159 row_shl:8 row_mask:0xf bank_mask:0xf
	v_mul_f32_dpp v94, v94, v94 row_shl:8 row_mask:0xf bank_mask:0xf
	v_mul_f32_dpp v95, v95, v95 row_shl:8 row_mask:0xf bank_mask:0xf
	v_mul_f32_dpp v158, v158, v158 row_shl:8 row_mask:0xf bank_mask:0xf
	v_mul_f32_dpp v159, v159, v159 row_shl:8 row_mask:0xf bank_mask:0xf
	s_nop 1
	s_nop 0
	v_pk_fma_f32 v[94:95], v[94:95], v[90:91], v[98:99]
	s_nop 1
	v_mov_b32_dpp v90, v94 row_newbcast:0 row_mask:0xf bank_mask:0xf
	v_pk_add_f32 v[92:93], v[92:93], v[94:95]
	v_mov_b32_dpp v91, v95 row_newbcast:0 row_mask:0xf bank_mask:0xf
	v_pk_fma_f32 v[94:95], v[158:159], v[162:163], v[154:155]
	v_pk_mul_f32 v[98:99], v[160:161], v[92:93]
	v_pk_add_f32 v[96:97], v[96:97], v[94:95]
	v_mov_b32_dpp v92, v94 row_newbcast:0 row_mask:0xf bank_mask:0xf
	v_mov_b32_dpp v93, v95 row_newbcast:0 row_mask:0xf bank_mask:0xf
	v_pk_mul_f32 v[94:95], v[182:183], v[96:97]
	v_cvt_pk_bf16_f32 v96, v98, v99
	v_cvt_pk_bf16_f32 v97, v94, v95
	global_store_dwordx2 v[180:181], v[96:97], off
	ds_read_b128 v[94:97], v222 offset:22528
	ds_read_b128 v[162:165], v223 offset:22528
	s_waitcnt lgkmcnt(1)
	v_mfma_f32_16x16x32_bf16 v[158:161], v[36:39], v[94:97], 0
	v_mfma_f32_16x16x32_bf16 v[94:97], v[52:55], v[94:97], 0
	s_waitcnt lgkmcnt(0)
	v_mfma_f32_16x16x32_bf16 v[158:161], v[40:43], v[162:165], v[158:161]
	v_mfma_f32_16x16x32_bf16 v[94:97], v[56:59], v[162:165], v[94:97]
	ds_read_b128 v[162:165], v224 offset:22528
	s_waitcnt lgkmcnt(0)
	v_mfma_f32_16x16x32_bf16 v[158:161], v[44:47], v[162:165], v[158:161]
	v_mfma_f32_16x16x32_bf16 v[94:97], v[60:63], v[162:165], v[94:97]
	ds_read_b128 v[162:165], v225 offset:22528
	ds_read_b128 v[166:169], v203 offset:39936
	ds_read_b128 v[170:173], v203 offset:40960
	s_waitcnt lgkmcnt(2)
	v_mfma_f32_16x16x32_bf16 v[158:161], v[48:51], v[162:165], v[158:161]
	v_mfma_f32_16x16x32_bf16 v[94:97], v[64:67], v[162:165], v[94:97]
	s_waitcnt lgkmcnt(1)
	s_nop 5
	v_fmamk_f32 v1, v158, 0xbfb8aa3b, v166
	v_exp_f32_e32 v1, v1
	ds_read_b128 v[162:165], v203 offset:41984
	v_fmamk_f32 v98, v159, 0xbfb8aa3b, v167
	v_exp_f32_e32 v98, v98
	s_waitcnt lgkmcnt(1)
	v_fmamk_f32 v94, v94, 0xbfb8aa3b, v170
	v_exp_f32_e32 v94, v94
	v_add_f32_e32 v1, 1.0, v1
	v_fmamk_f32 v95, v95, 0xbfb8aa3b, v171
	v_rcp_f32_e32 v1, v1
	v_exp_f32_e32 v95, v95
	v_add_f32_e32 v94, 1.0, v94
	v_rcp_f32_e32 v99, v94
	v_add_f32_e32 v94, 1.0, v98
	v_rcp_f32_e32 v98, v94
	v_add_f32_e32 v94, 1.0, v95
	s_waitcnt lgkmcnt(0)
; #define LAS __attribute__((address_space(3)))
; template <int PASS> __device__ __forceinline__ void phase_lru(LAS unsigned char* lds, const bf16_t* Z, const bf16_t* WL, float* LSUM, const float* LCAR, bf16_t* RNN,
;                                                               int S, int tid, int lane, int wave, int G) {
;     ...
;                 for (int tt = 0; tt < 4; ++tt) { const int t = 3 - tt;
;                     f32x4 gr = (f32x4){0.f, 0.f, 0.f, 0.f}, gi = gr;
; #pragma unroll
;                     for (int s = 0; s < 4; ++s) { const bf16x8 bfr = *(const LAS bf16x8*)(lds + LRU_XC + off_b(16 * t + c, 4 * s + g4));
;                         gr = __builtin_amdgcn_mfma_f32_16x16x32_bf16(wf[2][s], bfr, gr, 0, 0, 0); gi = __builtin_amdgcn_mfma_f32_16x16x32_bf16(wf[3][s], bfr, gi, 0, 0, 0); }
;                     f32x4 ov;
;                     const f32x4 kba = kc[3 * 64 + lane], kbx = kc[4 * 64 + lane], ksp = kc[5 * 64 + lane];
;                     f32x4 av, hv;
; #pragma unroll
;                     for (int j = 0; j < 4; ++j) {
;                         const float rg = __builtin_amdgcn_rcpf(1.0f + __builtin_amdgcn_exp2f(fmaf(gr[j], -LOG2E, kba[j])));
;                         const float ig = __builtin_amdgcn_rcpf(1.0f + __builtin_amdgcn_exp2f(fmaf(gi[j], -LOG2E, kbx[j])));
;                         const float a_ = __builtin_amdgcn_exp2f(rg * ksp[j]);
;                         av[j] = a_; hv[j] = __builtin_amdgcn_sqrtf(fmaf(-a_, a_, 1.0f)) * (ig * xc[t][j]);
;                     }
;                     lru_scan4_bwd(av, hv);
; #pragma unroll
;                     for (int j = 0; j < 4; ++j) {
;                         const float hfull = fmaf(av[j], Hc[j], hv[j]);
;                         Hc[j] = __shfl(hfull, lane & 48);
;                         if (PASS == 0) Ac[j] *= __shfl(av[j], lane & 48);
;                         if (PASS == 1) { const unsigned rw = j < 2 ? ryr[t].x : ryr[t].y; const float y = (j & 1) ? bfhi(rw) : bflo(rw);
;                             const float ge = y * __builtin_amdgcn_rcpf(1.0f + __builtin_amdgcn_exp2f((-2.3022082f * y) * fmaf(0.044715f * y, y, 1.0f)));
;                             ov[j] = (hf[t][j] + hfull) * ge; }
;                     }
;                     if (PASS == 1) { u32x2 w; w.x = pk2(ov[0], ov[1]); w.y = pk2(ov[2], ov[3]); *(u32x2*)(RNN + (size_t)(t0 + 16 * t + c) * LW + ch0) = w; }
	v_mul_f32_e32 v1, v162, v1
	v_rcp_f32_e32 v101, v94
	v_exp_f32_e32 v94, v1
	v_mul_f32_e32 v95, v163, v98
	v_mul_f32_e32 v1, v152, v99
	v_exp_f32_e32 v95, v95
	v_fma_f32 v98, -v94, v94, 1.0
	v_sqrt_f32_e32 v98, v98
	v_mul_f32_e32 v99, v153, v101
	v_fma_f32 v101, -v95, v95, 1.0
	v_fmamk_f32 v96, v96, 0xbfb8aa3b, v172
	v_mul_f32_e32 v98, v1, v98
	v_fmamk_f32 v1, v160, 0xbfb8aa3b, v168
	v_exp_f32_e32 v1, v1
	v_sqrt_f32_e32 v101, v101
	v_exp_f32_e32 v96, v96
	v_fmac_f32_e32 v169, 0xbfb8aa3b, v161
	v_add_f32_e32 v1, 1.0, v1
	v_rcp_f32_e32 v1, v1
	v_exp_f32_e32 v102, v169
	v_mul_f32_e32 v99, v99, v101
	v_add_f32_e32 v101, 1.0, v96
	v_mul_f32_e32 v1, v164, v1
	v_exp_f32_e32 v96, v1
	v_rcp_f32_e32 v1, v101
	v_add_f32_e32 v101, 1.0, v102
	v_rcp_f32_e32 v101, v101
	v_fmac_f32_e32 v173, 0xbfb8aa3b, v97
	v_exp_f32_e32 v105, v173
	v_fma_f32 v102, -v96, v96, 1.0
	v_mul_f32_e32 v97, v165, v101
	v_exp_f32_e32 v97, v97
	v_sqrt_f32_e32 v101, v102
	v_add_f32_e32 v102, 1.0, v105
	v_rcp_f32_e32 v102, v102
	v_fma_f32 v105, -v97, v97, 1.0
	v_sqrt_f32_e32 v105, v105
	v_mul_f32_e32 v1, v150, v1
	v_mul_f32_e32 v150, v1, v101
	v_mul_f32_e32 v1, v151, v102
	v_mul_f32_e32 v151, v1, v105
	s_nop 1
	v_fmac_f32_dpp v98, v98, v94 row_shl:1 row_mask:0xf bank_mask:0xf
	v_fmac_f32_dpp v99, v99, v95 row_shl:1 row_mask:0xf bank_mask:0xf
	v_fmac_f32_dpp v150, v150, v96 row_shl:1 row_mask:0xf bank_mask:0xf
	v_fmac_f32_dpp v151, v151, v97 row_shl:1 row_mask:0xf bank_mask:0xf
	v_mul_f32_dpp v94, v94, v94 row_shl:1 row_mask:0xf bank_mask:0xf
	v_mul_f32_dpp v95, v95, v95 row_shl:1 row_mask:0xf bank_mask:0xf
	v_mul_f32_dpp v96, v96, v96 row_shl:1 row_mask:0xf bank_mask:0xf
	v_mul_f32_dpp v97, v97, v97 row_shl:1 row_mask:0xf bank_mask:0xf
	v_fmac_f32_dpp v98, v98, v94 row_shl:2 row_mask:0xf bank_mask:0xf
	v_fmac_f32_dpp v99, v99, v95 row_shl:2 row_mask:0xf bank_mask:0xf
	v_fmac_f32_dpp v150, v150, v96 row_shl:2 row_mask:0xf bank_mask:0xf
	v_fmac_f32_dpp v151, v151, v97 row_shl:2 row_mask:0xf bank_mask:0xf
	v_mul_f32_dpp v94, v94, v94 row_shl:2 row_mask:0xf bank_mask:0xf
	v_mul_f32_dpp v95, v95, v95 row_shl:2 row_mask:0xf bank_mask:0xf
	v_mul_f32_dpp v96, v96, v96 row_shl:2 row_mask:0xf bank_mask:0xf
	v_mul_f32_dpp v97, v97, v97 row_shl:2 row_mask:0xf bank_mask:0xf
	v_fmac_f32_dpp v98, v98, v94 row_shl:4 row_mask:0xf bank_mask:0xf
	v_fmac_f32_dpp v99, v99, v95 row_shl:4 row_mask:0xf bank_mask:0xf
	v_fmac_f32_dpp v150, v150, v96 row_shl:4 row_mask:0xf bank_mask:0xf
	v_fmac_f32_dpp v151, v151, v97 row_shl:4 row_mask:0xf bank_mask:0xf
	v_mul_f32_dpp v94, v94, v94 row_shl:4 row_mask:0xf bank_mask:0xf
	v_mul_f32_dpp v95, v95, v95 row_shl:4 row_mask:0xf bank_mask:0xf
	v_mul_f32_dpp v96, v96, v96 row_shl:4 row_mask:0xf bank_mask:0xf
	v_mul_f32_dpp v97, v97, v97 row_shl:4 row_mask:0xf bank_mask:0xf
	v_fmac_f32_dpp v98, v98, v94 row_shl:8 row_mask:0xf bank_mask:0xf
	v_fmac_f32_dpp v99, v99, v95 row_shl:8 row_mask:0xf bank_mask:0xf
	v_fmac_f32_dpp v150, v150, v96 row_shl:8 row_mask:0xf bank_mask:0xf
	v_fmac_f32_dpp v151, v151, v97 row_shl:8 row_mask:0xf bank_mask:0xf
	v_mul_f32_dpp v94, v94, v94 row_shl:8 row_mask:0xf bank_mask:0xf
	v_mul_f32_dpp v95, v95, v95 row_shl:8 row_mask:0xf bank_mask:0xf
	v_mul_f32_dpp v96, v96, v96 row_shl:8 row_mask:0xf bank_mask:0xf
	v_mul_f32_dpp v97, v97, v97 row_shl:8 row_mask:0xf bank_mask:0xf
	s_nop 1
	s_nop 0
	v_pk_fma_f32 v[90:91], v[94:95], v[90:91], v[98:99]
	s_nop 1
	v_mov_b32_dpp v1, v90 row_newbcast:0 row_mask:0xf bank_mask:0xf
	v_pk_add_f32 v[88:89], v[88:89], v[90:91]
	v_mov_b32_dpp v144, v91 row_newbcast:0 row_mask:0xf bank_mask:0xf
	v_pk_mul_f32 v[84:85], v[84:85], v[88:89]
	v_pk_fma_f32 v[88:89], v[96:97], v[92:93], v[150:151]
	v_cvt_pk_bf16_f32 v84, v84, v85
	v_pk_add_f32 v[86:87], v[86:87], v[88:89]
	v_mov_b32_dpp v150, v88 row_newbcast:0 row_mask:0xf bank_mask:0xf
	v_pk_mul_f32 v[82:83], v[82:83], v[86:87]
	v_mov_b32_dpp v151, v89 row_newbcast:0 row_mask:0xf bank_mask:0xf
	v_cvt_pk_bf16_f32 v85, v82, v83
	global_store_dwordx2 v[80:81], v[84:85], off
	ds_read_b128 v[80:83], v222 offset:18432
	ds_read_b128 v[88:91], v223 offset:18432
	s_waitcnt lgkmcnt(1)
	v_mfma_f32_16x16x32_bf16 v[84:87], v[36:39], v[80:83], 0
	ds_read_b128 v[92:95], v225 offset:18432
	v_mfma_f32_16x16x32_bf16 v[80:83], v[52:55], v[80:83], 0
	s_waitcnt lgkmcnt(1)
	v_mfma_f32_16x16x32_bf16 v[84:87], v[40:43], v[88:91], v[84:87]
	v_mfma_f32_16x16x32_bf16 v[80:83], v[56:59], v[88:91], v[80:83]
	ds_read_b128 v[88:91], v224 offset:18432
	s_waitcnt lgkmcnt(0)
	v_mfma_f32_16x16x32_bf16 v[84:87], v[44:47], v[88:91], v[84:87]
	v_mfma_f32_16x16x32_bf16 v[80:83], v[60:63], v[88:91], v[80:83]
	v_mfma_f32_16x16x32_bf16 v[88:91], v[48:51], v[92:95], v[84:87]
	v_mfma_f32_16x16x32_bf16 v[80:83], v[64:67], v[92:95], v[80:83]
	ds_read_b128 v[96:99], v203 offset:39936
	s_nop 3
	ds_read_b128 v[84:87], v203 offset:40960
	ds_read_b128 v[92:95], v203 offset:41984
	s_waitcnt lgkmcnt(2)
	v_fmamk_f32 v88, v88, 0xbfb8aa3b, v96
	v_exp_f32_e32 v88, v88
	s_waitcnt lgkmcnt(1)
	v_fmamk_f32 v80, v80, 0xbfb8aa3b, v84
	v_exp_f32_e32 v80, v80
	v_fmamk_f32 v81, v81, 0xbfb8aa3b, v85
	v_add_f32_e32 v88, 1.0, v88
	v_rcp_f32_e32 v88, v88
	v_add_f32_e32 v80, 1.0, v80
	v_rcp_f32_e32 v80, v80
	v_exp_f32_e32 v81, v81
	s_waitcnt lgkmcnt(0)
; __device__ __forceinline__ unsigned pk2(float lo, float hi) { return pg8::cvt_pk_bf16(lo, hi); }
; __device__ __forceinline__ float bflo(unsigned w) { return __uint_as_float(w << 16); }
; __device__ __forceinline__ float bfhi(unsigned w) { return __uint_as_float(w & 0xffff0000u); }
; template <int PASS> __device__ __forceinline__ void phase_lru(LAS unsigned char* lds, const bf16_t* Z, const bf16_t* WL, float* LSUM, const float* LCAR, bf16_t* RNN,
;                                                               int S, int tid, int lane, int wave, int G) {
;     ...
; #pragma unroll
;                     for (int j = 0; j < 4; ++j) {
;                         const float rg = __builtin_amdgcn_rcpf(1.0f + __builtin_amdgcn_exp2f(fmaf(gr[j], -LOG2E, kba[j])));
;                         const float ig = __builtin_amdgcn_rcpf(1.0f + __builtin_amdgcn_exp2f(fmaf(gi[j], -LOG2E, kbx[j])));
;                         const float a_ = __builtin_amdgcn_exp2f(rg * ksp[j]);
;                         av[j] = a_; hv[j] = __builtin_amdgcn_sqrtf(fmaf(-a_, a_, 1.0f)) * (ig * xc[t][j]);
;                     }
;                     lru_scan4_bwd(av, hv);
; #pragma unroll
;                     for (int j = 0; j < 4; ++j) {
;                         const float hfull = fmaf(av[j], Hc[j], hv[j]);
;                         Hc[j] = __shfl(hfull, lane & 48);
;                         if (PASS == 0) Ac[j] *= __shfl(av[j], lane & 48);
;                         if (PASS == 1) { const unsigned rw = j < 2 ? ryr[t].x : ryr[t].y; const float y = (j & 1) ? bfhi(rw) : bflo(rw);
;                             const float ge = y * __builtin_amdgcn_rcpf(1.0f + __builtin_amdgcn_exp2f((-2.3022082f * y) * fmaf(0.044715f * y, y, 1.0f)));
;                             ov[j] = (hf[t][j] + hfull) * ge; }
;                     }
;                     if (PASS == 1) { u32x2 w; w.x = pk2(ov[0], ov[1]); w.y = pk2(ov[2], ov[3]); *(u32x2*)(RNN + (size_t)(t0 + 16 * t + c) * LW + ch0) = w; }
	v_mul_f32_e32 v84, v92, v88
	v_exp_f32_e32 v84, v84
	v_mul_f32_e32 v80, v148, v80
	v_add_f32_e32 v81, 1.0, v81
	v_rcp_f32_e32 v81, v81
	v_fma_f32 v88, -v84, v84, 1.0
	v_sqrt_f32_e32 v88, v88
	v_fmamk_f32 v82, v82, 0xbfb8aa3b, v86
	v_mul_f32_e32 v81, v149, v81
	v_exp_f32_e32 v82, v82
	v_mul_f32_e32 v106, v80, v88
	v_fmamk_f32 v80, v89, 0xbfb8aa3b, v97
	v_exp_f32_e32 v80, v80
	v_add_f32_e32 v82, 1.0, v82
	v_rcp_f32_e32 v82, v82
	v_fmac_f32_e32 v99, 0xbfb8aa3b, v91
	v_add_f32_e32 v80, 1.0, v80
	v_rcp_f32_e32 v80, v80
	v_mul_f32_e32 v82, v146, v82
	v_fmac_f32_e32 v87, 0xbfb8aa3b, v83
	v_and_b32_e32 v83, 0xffff0000, v145
	v_mul_f32_e32 v80, v93, v80
	v_exp_f32_e32 v80, v80
	s_nop 0
	v_fma_f32 v85, -v80, v80, 1.0
	v_sqrt_f32_e32 v85, v85
	s_nop 0
	v_mul_f32_e32 v105, v81, v85
	v_fmamk_f32 v81, v90, 0xbfb8aa3b, v98
	v_exp_f32_e32 v81, v81
	s_nop 0
	v_add_f32_e32 v81, 1.0, v81
	v_rcp_f32_e32 v81, v81
	s_nop 0
	v_mul_f32_e32 v81, v94, v81
	v_exp_f32_e32 v85, v81
	s_nop 0
	v_fma_f32 v81, -v85, v85, 1.0
	v_sqrt_f32_e32 v81, v81
	s_nop 0
	v_mul_f32_e32 v102, v82, v81
	v_exp_f32_e32 v81, v99
	v_exp_f32_e32 v82, v87
	v_add_f32_e32 v81, 1.0, v81
	v_rcp_f32_e32 v81, v81
	v_add_f32_e32 v82, 1.0, v82
	v_rcp_f32_e32 v82, v82
	v_mul_f32_e32 v81, v95, v81
	v_exp_f32_e32 v86, v81
	v_mul_f32_e32 v82, v147, v82
	v_fma_f32 v81, -v86, v86, 1.0
	v_sqrt_f32_e32 v81, v81
	s_nop 0
	v_mul_f32_e32 v101, v82, v81
	s_nop 1
	v_fmac_f32_dpp v106, v106, v84 row_shl:1 row_mask:0xf bank_mask:0xf
	v_fmac_f32_dpp v105, v105, v80 row_shl:1 row_mask:0xf bank_mask:0xf
	v_fmac_f32_dpp v102, v102, v85 row_shl:1 row_mask:0xf bank_mask:0xf
	v_fmac_f32_dpp v101, v101, v86 row_shl:1 row_mask:0xf bank_mask:0xf
	v_mul_f32_dpp v84, v84, v84 row_shl:1 row_mask:0xf bank_mask:0xf
	v_mul_f32_dpp v80, v80, v80 row_shl:1 row_mask:0xf bank_mask:0xf
	v_mul_f32_dpp v85, v85, v85 row_shl:1 row_mask:0xf bank_mask:0xf
	v_mul_f32_dpp v86, v86, v86 row_shl:1 row_mask:0xf bank_mask:0xf
	v_fmac_f32_dpp v106, v106, v84 row_shl:2 row_mask:0xf bank_mask:0xf
	v_fmac_f32_dpp v105, v105, v80 row_shl:2 row_mask:0xf bank_mask:0xf
	v_fmac_f32_dpp v102, v102, v85 row_shl:2 row_mask:0xf bank_mask:0xf
	v_fmac_f32_dpp v101, v101, v86 row_shl:2 row_mask:0xf bank_mask:0xf
	v_mul_f32_dpp v84, v84, v84 row_shl:2 row_mask:0xf bank_mask:0xf
	v_mul_f32_dpp v80, v80, v80 row_shl:2 row_mask:0xf bank_mask:0xf
	v_mul_f32_dpp v85, v85, v85 row_shl:2 row_mask:0xf bank_mask:0xf
	v_mul_f32_dpp v86, v86, v86 row_shl:2 row_mask:0xf bank_mask:0xf
	v_fmac_f32_dpp v106, v106, v84 row_shl:4 row_mask:0xf bank_mask:0xf
	v_fmac_f32_dpp v105, v105, v80 row_shl:4 row_mask:0xf bank_mask:0xf
	v_fmac_f32_dpp v102, v102, v85 row_shl:4 row_mask:0xf bank_mask:0xf
	v_fmac_f32_dpp v101, v101, v86 row_shl:4 row_mask:0xf bank_mask:0xf
	v_mul_f32_dpp v84, v84, v84 row_shl:4 row_mask:0xf bank_mask:0xf
	v_mul_f32_dpp v80, v80, v80 row_shl:4 row_mask:0xf bank_mask:0xf
	v_mul_f32_dpp v85, v85, v85 row_shl:4 row_mask:0xf bank_mask:0xf
	v_mul_f32_dpp v86, v86, v86 row_shl:4 row_mask:0xf bank_mask:0xf
	v_fmac_f32_dpp v106, v106, v84 row_shl:8 row_mask:0xf bank_mask:0xf
	v_fmac_f32_dpp v105, v105, v80 row_shl:8 row_mask:0xf bank_mask:0xf
	v_fmac_f32_dpp v102, v102, v85 row_shl:8 row_mask:0xf bank_mask:0xf
	v_fmac_f32_dpp v101, v101, v86 row_shl:8 row_mask:0xf bank_mask:0xf
	v_mul_f32_dpp v84, v84, v84 row_shl:8 row_mask:0xf bank_mask:0xf
	v_mul_f32_dpp v80, v80, v80 row_shl:8 row_mask:0xf bank_mask:0xf
	v_mul_f32_dpp v85, v85, v85 row_shl:8 row_mask:0xf bank_mask:0xf
	v_mul_f32_dpp v86, v86, v86 row_shl:8 row_mask:0xf bank_mask:0xf
	s_nop 1
	v_lshlrev_b32_e32 v82, 16, v145
	v_fmac_f32_e32 v106, v84, v1
	v_mul_f32_e32 v84, 0x3d372713, v82
	v_mul_f32_e32 v1, 0xc0135761, v82
	v_fma_f32 v84, v84, v82, 1.0
	v_mul_f32_e32 v1, v1, v84
	v_exp_f32_e32 v1, v1
	v_fmac_f32_e32 v102, v85, v150
	v_mul_f32_e32 v85, 0x3d372713, v83
	v_fma_f32 v85, v85, v83, 1.0
	v_add_f32_e32 v1, 1.0, v1
	v_rcp_f32_e32 v84, v1
	v_mul_f32_e32 v1, 0xc0135761, v83
	v_mul_f32_e32 v1, v1, v85
	v_exp_f32_e32 v1, v1
	v_fmac_f32_e32 v105, v80, v144
	v_fmac_f32_e32 v101, v86, v151
	v_pk_add_f32 v[80:81], v[106:107], v[104:105]
	v_add_f32_e32 v1, 1.0, v1
	v_rcp_f32_e32 v85, v1
	v_pk_mul_f32 v[80:81], v[156:157], v[80:81]
	v_pk_mul_f32 v[82:83], v[84:85], v[82:83]
	v_pk_add_f32 v[84:85], v[102:103], v[100:101]
	v_cvt_pk_bf16_f32 v80, v80, v81
	v_pk_mul_f32 v[82:83], v[82:83], v[84:85]
	s_nop 0
	v_cvt_pk_bf16_f32 v81, v82, v83
	v_lshl_add_u64 v[82:83], s[88:89], 0, v[126:127]
	global_store_dwordx2 v[82:83], v[80:81], off
	s_add_i32 s34, s34, 64
	v_lshl_add_u64 v[2:3], v[2:3], 0, s[50:51]
	v_lshl_add_u64 v[114:115], v[114:115], 0, s[20:21]
	v_lshl_add_u64 v[116:117], v[116:117], 0, s[20:21]
	v_lshl_add_u64 v[118:119], v[118:119], 0, s[20:21]
	v_lshl_add_u64 v[120:121], v[120:121], 0, s[22:23]
	v_lshl_add_u64 v[122:123], v[122:123], 0, s[22:23]
	v_lshl_add_u64 v[124:125], v[124:125], 0, s[22:23]
	v_lshl_add_u64 v[126:127], v[126:127], 0, s[20:21]
	s_cmpk_eq_i32 s34, 0x100
	v_lshl_add_u64 v[128:129], v[128:129], 0, s[22:23]
	s_cbranch_scc1 .LBB0_173

; #define LAS __attribute__((address_space(3)))
; template <int PASS> __device__ __forceinline__ void phase_lru(LAS unsigned char* lds, const bf16_t* Z, const bf16_t* WL, float* LSUM, const float* LCAR, bf16_t* RNN,
;                                                               int S, int tid, int lane, int wave, int G) {
;     ...
;                 for (int t = 0; t < 4; ++t) {
;                     f32x4 gr = (f32x4){0.f, 0.f, 0.f, 0.f}, gi = gr;
; #pragma unroll
;                     for (int s = 0; s < 4; ++s) { const bf16x8 bfr = *(const LAS bf16x8*)(lds + LRU_XC + off_b(16 * t + c, 4 * s + g4));
;                         gr = __builtin_amdgcn_mfma_f32_16x16x32_bf16(wf[0][s], bfr, gr, 0, 0, 0); gi = __builtin_amdgcn_mfma_f32_16x16x32_bf16(wf[1][s], bfr, gi, 0, 0, 0); }
;                     const f32x4 kba = kc[0 * 64 + lane], kbx = kc[1 * 64 + lane], ksp = kc[2 * 64 + lane];
;                     f32x4 av, hv;
; #pragma unroll
;                     for (int j = 0; j < 4; ++j) {
;                         const float rg = __builtin_amdgcn_rcpf(1.0f + __builtin_amdgcn_exp2f(fmaf(gr[j], -LOG2E, kba[j])));
;                         const float ig = __builtin_amdgcn_rcpf(1.0f + __builtin_amdgcn_exp2f(fmaf(gi[j], -LOG2E, kbx[j])));
;                         const float a_ = __builtin_amdgcn_exp2f(rg * ksp[j]);
;                         av[j] = a_; hv[j] = __builtin_amdgcn_sqrtf(fmaf(-a_, a_, 1.0f)) * (ig * xc[t][j]);
;                     }
;                     lru_scan4_fwd(av, hv);
; #pragma unroll
;                     for (int j = 0; j < 4; ++j) {
;                         const float hfull = fmaf(av[j], Hc[j], hv[j]);
;                         if (PASS == 1) hf[t][j] = hfull;
;                         Hc[j] = __shfl(hfull, (lane & 48) | 15);
;                         if (PASS == 0) Ac[j] *= __shfl(av[j], (lane & 48) | 15);
;                     }
.LBB0_233:
	ds_read_b128 v[80:83], v169 offset:18432
	ds_read_b128 v[88:91], v170 offset:18432
	s_waitcnt lgkmcnt(1)
	v_mfma_f32_16x16x32_bf16 v[84:87], v[4:7], v[80:83], 0
	ds_read_b128 v[92:95], v172 offset:18432
	v_mfma_f32_16x16x32_bf16 v[80:83], v[20:23], v[80:83], 0
	s_waitcnt lgkmcnt(1)
	v_mfma_f32_16x16x32_bf16 v[84:87], v[8:11], v[88:91], v[84:87]
	v_mfma_f32_16x16x32_bf16 v[80:83], v[24:27], v[88:91], v[80:83]
	ds_read_b128 v[88:91], v171 offset:18432
	s_waitcnt lgkmcnt(0)
	v_mfma_f32_16x16x32_bf16 v[84:87], v[12:15], v[88:91], v[84:87]
	v_mfma_f32_16x16x32_bf16 v[80:83], v[28:31], v[88:91], v[80:83]
	v_mfma_f32_16x16x32_bf16 v[88:91], v[16:19], v[92:95], v[84:87]
	v_mfma_f32_16x16x32_bf16 v[80:83], v[32:35], v[92:95], v[80:83]
	ds_read_b128 v[96:99], v155 offset:36864
	s_nop 3
	ds_read_b128 v[84:87], v155 offset:37888
	ds_read_b128 v[92:95], v155 offset:38912
	s_waitcnt lgkmcnt(2)
	v_fmamk_f32 v1, v88, 0xbfb8aa3b, v96
	v_exp_f32_e32 v1, v1
	s_waitcnt lgkmcnt(1)
	v_fmamk_f32 v80, v80, 0xbfb8aa3b, v84
	v_exp_f32_e32 v80, v80
	v_fmamk_f32 v81, v81, 0xbfb8aa3b, v85
	v_add_f32_e32 v1, 1.0, v1
	v_rcp_f32_e32 v1, v1
	v_add_f32_e32 v80, 1.0, v80
	v_rcp_f32_e32 v80, v80
	v_exp_f32_e32 v81, v81
	s_waitcnt lgkmcnt(0)
	v_mul_f32_e32 v1, v92, v1
	v_exp_f32_e32 v1, v1
	v_mul_f32_e32 v80, v116, v80
	v_add_f32_e32 v81, 1.0, v81
	v_rcp_f32_e32 v81, v81
	v_fma_f32 v84, -v1, v1, 1.0
	v_sqrt_f32_e32 v84, v84
	v_fmamk_f32 v82, v82, 0xbfb8aa3b, v86
	v_mul_f32_e32 v81, v117, v81
	v_exp_f32_e32 v82, v82
	v_mul_f32_e32 v80, v80, v84
	v_fmamk_f32 v84, v89, 0xbfb8aa3b, v97
	v_exp_f32_e32 v84, v84
	v_add_f32_e32 v82, 1.0, v82
	v_rcp_f32_e32 v82, v82
	v_fmac_f32_e32 v99, 0xbfb8aa3b, v91
	v_add_f32_e32 v84, 1.0, v84
	v_rcp_f32_e32 v84, v84
	v_mul_f32_e32 v82, v114, v82
	v_fmac_f32_e32 v87, 0xbfb8aa3b, v83
	v_exp_f32_e32 v83, v87
	v_mul_f32_e32 v84, v93, v84
	v_exp_f32_e32 v84, v84
	v_add_f32_e32 v83, 1.0, v83
	v_rcp_f32_e32 v83, v83
	v_fma_f32 v85, -v84, v84, 1.0
	v_sqrt_f32_e32 v85, v85
	v_mul_f32_e32 v83, v115, v83
	v_mul_f32_e32 v81, v81, v85
	v_fmamk_f32 v85, v90, 0xbfb8aa3b, v98
	v_exp_f32_e32 v85, v85
	s_nop 0
	v_add_f32_e32 v85, 1.0, v85
	v_rcp_f32_e32 v85, v85
	s_nop 0
	v_mul_f32_e32 v85, v94, v85
	v_exp_f32_e32 v85, v85
	s_nop 0
	v_fma_f32 v86, -v85, v85, 1.0
	v_sqrt_f32_e32 v86, v86
	s_nop 0
	v_mul_f32_e32 v82, v82, v86
	v_exp_f32_e32 v86, v99
	s_nop 0
	v_add_f32_e32 v86, 1.0, v86
	v_rcp_f32_e32 v86, v86
	s_nop 0
	v_mul_f32_e32 v86, v95, v86
	v_exp_f32_e32 v86, v86
	s_nop 0
	v_fma_f32 v87, -v86, v86, 1.0
	v_sqrt_f32_e32 v87, v87
	s_nop 0
	v_mul_f32_e32 v83, v83, v87
	s_nop 1
	v_fmac_f32_dpp v80, v80, v1 row_shr:1 row_mask:0xf bank_mask:0xf
	v_fmac_f32_dpp v81, v81, v84 row_shr:1 row_mask:0xf bank_mask:0xf
	v_fmac_f32_dpp v82, v82, v85 row_shr:1 row_mask:0xf bank_mask:0xf
	v_fmac_f32_dpp v83, v83, v86 row_shr:1 row_mask:0xf bank_mask:0xf
	v_mul_f32_dpp v1, v1, v1 row_shr:1 row_mask:0xf bank_mask:0xf
	v_mul_f32_dpp v84, v84, v84 row_shr:1 row_mask:0xf bank_mask:0xf
	v_mul_f32_dpp v85, v85, v85 row_shr:1 row_mask:0xf bank_mask:0xf
	v_mul_f32_dpp v86, v86, v86 row_shr:1 row_mask:0xf bank_mask:0xf
	v_fmac_f32_dpp v80, v80, v1 row_shr:2 row_mask:0xf bank_mask:0xf
	v_fmac_f32_dpp v81, v81, v84 row_shr:2 row_mask:0xf bank_mask:0xf
	v_fmac_f32_dpp v82, v82, v85 row_shr:2 row_mask:0xf bank_mask:0xf
	v_fmac_f32_dpp v83, v83, v86 row_shr:2 row_mask:0xf bank_mask:0xf
	v_mul_f32_dpp v1, v1, v1 row_shr:2 row_mask:0xf bank_mask:0xf
	v_mul_f32_dpp v84, v84, v84 row_shr:2 row_mask:0xf bank_mask:0xf
	v_mul_f32_dpp v85, v85, v85 row_shr:2 row_mask:0xf bank_mask:0xf
	v_mul_f32_dpp v86, v86, v86 row_shr:2 row_mask:0xf bank_mask:0xf
	v_fmac_f32_dpp v80, v80, v1 row_shr:4 row_mask:0xf bank_mask:0xf
	v_fmac_f32_dpp v81, v81, v84 row_shr:4 row_mask:0xf bank_mask:0xf
	v_fmac_f32_dpp v82, v82, v85 row_shr:4 row_mask:0xf bank_mask:0xf
	v_fmac_f32_dpp v83, v83, v86 row_shr:4 row_mask:0xf bank_mask:0xf
	v_mul_f32_dpp v1, v1, v1 row_shr:4 row_mask:0xf bank_mask:0xf
	v_mul_f32_dpp v84, v84, v84 row_shr:4 row_mask:0xf bank_mask:0xf
	v_mul_f32_dpp v85, v85, v85 row_shr:4 row_mask:0xf bank_mask:0xf
	v_mul_f32_dpp v86, v86, v86 row_shr:4 row_mask:0xf bank_mask:0xf
	v_fmac_f32_dpp v80, v80, v1 row_shr:8 row_mask:0xf bank_mask:0xf
	v_fmac_f32_dpp v81, v81, v84 row_shr:8 row_mask:0xf bank_mask:0xf
	v_fmac_f32_dpp v82, v82, v85 row_shr:8 row_mask:0xf bank_mask:0xf
	v_fmac_f32_dpp v83, v83, v86 row_shr:8 row_mask:0xf bank_mask:0xf
	v_mul_f32_dpp v1, v1, v1 row_shr:8 row_mask:0xf bank_mask:0xf
	v_mul_f32_dpp v84, v84, v84 row_shr:8 row_mask:0xf bank_mask:0xf
	v_mul_f32_dpp v85, v85, v85 row_shr:8 row_mask:0xf bank_mask:0xf
	v_mul_f32_dpp v86, v86, v86 row_shr:8 row_mask:0xf bank_mask:0xf
	s_nop 1
	v_or_b32_e32 v87, v193, v202
	v_lshl_or_b32 v144, v87, 2, 60
	v_fmac_f32_e32 v80, 0, v1
	v_fmac_f32_e32 v81, 0, v84
	v_fmac_f32_e32 v82, 0, v85
	v_fmac_f32_e32 v83, 0, v86
	v_mov_b32_dpp v145, v80 row_newbcast:15 row_mask:0xf bank_mask:0xf
	v_mov_b32_dpp v1, v1 row_newbcast:15 row_mask:0xf bank_mask:0xf
	v_mov_b32_dpp v146, v81 row_newbcast:15 row_mask:0xf bank_mask:0xf
	v_mov_b32_dpp v173, v84 row_newbcast:15 row_mask:0xf bank_mask:0xf
	v_mov_b32_dpp v147, v82 row_newbcast:15 row_mask:0xf bank_mask:0xf
	v_mov_b32_dpp v174, v85 row_newbcast:15 row_mask:0xf bank_mask:0xf
	v_mov_b32_dpp v179, v83 row_newbcast:15 row_mask:0xf bank_mask:0xf
	v_mov_b32_dpp v175, v86 row_newbcast:15 row_mask:0xf bank_mask:0xf
	ds_read_b128 v[80:83], v169 offset:22528
	ds_read_b128 v[88:91], v170 offset:22528
	s_waitcnt lgkmcnt(1)
; #define LAS __attribute__((address_space(3)))
; template <int PASS> __device__ __forceinline__ void phase_lru(LAS unsigned char* lds, const bf16_t* Z, const bf16_t* WL, float* LSUM, const float* LCAR, bf16_t* RNN,
;                                                               int S, int tid, int lane, int wave, int G) {
;     ...
;                 for (int t = 0; t < 4; ++t) {
;                     f32x4 gr = (f32x4){0.f, 0.f, 0.f, 0.f}, gi = gr;
; #pragma unroll
;                     for (int s = 0; s < 4; ++s) { const bf16x8 bfr = *(const LAS bf16x8*)(lds + LRU_XC + off_b(16 * t + c, 4 * s + g4));
;                         gr = __builtin_amdgcn_mfma_f32_16x16x32_bf16(wf[0][s], bfr, gr, 0, 0, 0); gi = __builtin_amdgcn_mfma_f32_16x16x32_bf16(wf[1][s], bfr, gi, 0, 0, 0); }
;                     const f32x4 kba = kc[0 * 64 + lane], kbx = kc[1 * 64 + lane], ksp = kc[2 * 64 + lane];
;                     f32x4 av, hv;
; #pragma unroll
;                     for (int j = 0; j < 4; ++j) {
;                         const float rg = __builtin_amdgcn_rcpf(1.0f + __builtin_amdgcn_exp2f(fmaf(gr[j], -LOG2E, kba[j])));
;                         const float ig = __builtin_amdgcn_rcpf(1.0f + __builtin_amdgcn_exp2f(fmaf(gi[j], -LOG2E, kbx[j])));
;                         const float a_ = __builtin_amdgcn_exp2f(rg * ksp[j]);
;                         av[j] = a_; hv[j] = __builtin_amdgcn_sqrtf(fmaf(-a_, a_, 1.0f)) * (ig * xc[t][j]);
;                     }
;                     lru_scan4_fwd(av, hv);
; #pragma unroll
;                     for (int j = 0; j < 4; ++j) {
;                         const float hfull = fmaf(av[j], Hc[j], hv[j]);
;                         if (PASS == 1) hf[t][j] = hfull;
;                         Hc[j] = __shfl(hfull, (lane & 48) | 15);
;                         if (PASS == 0) Ac[j] *= __shfl(av[j], (lane & 48) | 15);
;                     }
	v_mfma_f32_16x16x32_bf16 v[84:87], v[4:7], v[80:83], 0
	ds_read_b128 v[92:95], v172 offset:22528
	v_mfma_f32_16x16x32_bf16 v[80:83], v[20:23], v[80:83], 0
	s_waitcnt lgkmcnt(1)
	v_mfma_f32_16x16x32_bf16 v[84:87], v[8:11], v[88:91], v[84:87]
	v_mfma_f32_16x16x32_bf16 v[80:83], v[24:27], v[88:91], v[80:83]
	ds_read_b128 v[88:91], v171 offset:22528
	s_waitcnt lgkmcnt(0)
	v_mfma_f32_16x16x32_bf16 v[84:87], v[12:15], v[88:91], v[84:87]
	v_mfma_f32_16x16x32_bf16 v[80:83], v[28:31], v[88:91], v[80:83]
	v_mfma_f32_16x16x32_bf16 v[88:91], v[16:19], v[92:95], v[84:87]
	v_mfma_f32_16x16x32_bf16 v[80:83], v[32:35], v[92:95], v[80:83]
	ds_read_b128 v[96:99], v155 offset:36864
	s_nop 3
	ds_read_b128 v[84:87], v155 offset:37888
	ds_read_b128 v[92:95], v155 offset:38912
	s_waitcnt lgkmcnt(2)
	v_fmamk_f32 v88, v88, 0xbfb8aa3b, v96
	v_exp_f32_e32 v88, v88
	s_waitcnt lgkmcnt(1)
	v_fmamk_f32 v80, v80, 0xbfb8aa3b, v84
	v_exp_f32_e32 v80, v80
	v_fmamk_f32 v81, v81, 0xbfb8aa3b, v85
	v_add_f32_e32 v88, 1.0, v88
	v_rcp_f32_e32 v88, v88
	v_add_f32_e32 v80, 1.0, v80
	v_rcp_f32_e32 v80, v80
	v_exp_f32_e32 v81, v81
	s_waitcnt lgkmcnt(0)
	v_mul_f32_e32 v84, v92, v88
	v_exp_f32_e32 v84, v84
	v_mul_f32_e32 v80, v120, v80
	v_add_f32_e32 v81, 1.0, v81
	v_rcp_f32_e32 v81, v81
	v_fma_f32 v88, -v84, v84, 1.0
	v_sqrt_f32_e32 v88, v88
	v_fmamk_f32 v82, v82, 0xbfb8aa3b, v86
	v_mul_f32_e32 v81, v121, v81
	v_exp_f32_e32 v82, v82
	v_mul_f32_e32 v80, v80, v88
	v_fmamk_f32 v88, v89, 0xbfb8aa3b, v97
	v_exp_f32_e32 v88, v88
	v_add_f32_e32 v82, 1.0, v82
	v_rcp_f32_e32 v82, v82
	v_fmac_f32_e32 v99, 0xbfb8aa3b, v91
	v_add_f32_e32 v88, 1.0, v88
	v_rcp_f32_e32 v88, v88
	v_mul_f32_e32 v82, v118, v82
	v_fmac_f32_e32 v87, 0xbfb8aa3b, v83
	v_exp_f32_e32 v83, v87
	v_mul_f32_e32 v85, v93, v88
	v_exp_f32_e32 v85, v85
	v_add_f32_e32 v83, 1.0, v83
	v_rcp_f32_e32 v83, v83
	v_fma_f32 v88, -v85, v85, 1.0
	v_sqrt_f32_e32 v88, v88
	v_mul_f32_e32 v83, v119, v83
	v_mul_f32_e32 v81, v81, v88
	v_fmamk_f32 v88, v90, 0xbfb8aa3b, v98
	v_exp_f32_e32 v88, v88
	s_nop 0
	v_add_f32_e32 v88, 1.0, v88
	v_rcp_f32_e32 v88, v88
	s_nop 0
	v_mul_f32_e32 v86, v94, v88
	v_exp_f32_e32 v86, v86
	s_nop 0
	v_fma_f32 v88, -v86, v86, 1.0
	v_sqrt_f32_e32 v88, v88
	s_nop 0
	v_mul_f32_e32 v82, v82, v88
	v_exp_f32_e32 v88, v99
	s_nop 0
	v_add_f32_e32 v88, 1.0, v88
	v_rcp_f32_e32 v88, v88
	s_nop 0
	v_mul_f32_e32 v87, v95, v88
	v_exp_f32_e32 v87, v87
	s_nop 0
	v_fma_f32 v88, -v87, v87, 1.0
	v_sqrt_f32_e32 v88, v88
	s_nop 0
	v_mul_f32_e32 v83, v83, v88
	s_nop 1
	v_fmac_f32_dpp v80, v80, v84 row_shr:1 row_mask:0xf bank_mask:0xf
	v_fmac_f32_dpp v81, v81, v85 row_shr:1 row_mask:0xf bank_mask:0xf
	v_fmac_f32_dpp v82, v82, v86 row_shr:1 row_mask:0xf bank_mask:0xf
	v_fmac_f32_dpp v83, v83, v87 row_shr:1 row_mask:0xf bank_mask:0xf
	v_mul_f32_dpp v84, v84, v84 row_shr:1 row_mask:0xf bank_mask:0xf
	v_mul_f32_dpp v85, v85, v85 row_shr:1 row_mask:0xf bank_mask:0xf
	v_mul_f32_dpp v86, v86, v86 row_shr:1 row_mask:0xf bank_mask:0xf
	v_mul_f32_dpp v87, v87, v87 row_shr:1 row_mask:0xf bank_mask:0xf
	v_fmac_f32_dpp v80, v80, v84 row_shr:2 row_mask:0xf bank_mask:0xf
	v_fmac_f32_dpp v81, v81, v85 row_shr:2 row_mask:0xf bank_mask:0xf
	v_fmac_f32_dpp v82, v82, v86 row_shr:2 row_mask:0xf bank_mask:0xf
	v_fmac_f32_dpp v83, v83, v87 row_shr:2 row_mask:0xf bank_mask:0xf
	v_mul_f32_dpp v84, v84, v84 row_shr:2 row_mask:0xf bank_mask:0xf
	v_mul_f32_dpp v85, v85, v85 row_shr:2 row_mask:0xf bank_mask:0xf
	v_mul_f32_dpp v86, v86, v86 row_shr:2 row_mask:0xf bank_mask:0xf
	v_mul_f32_dpp v87, v87, v87 row_shr:2 row_mask:0xf bank_mask:0xf
	v_fmac_f32_dpp v80, v80, v84 row_shr:4 row_mask:0xf bank_mask:0xf
	v_fmac_f32_dpp v81, v81, v85 row_shr:4 row_mask:0xf bank_mask:0xf
	v_fmac_f32_dpp v82, v82, v86 row_shr:4 row_mask:0xf bank_mask:0xf
	v_fmac_f32_dpp v83, v83, v87 row_shr:4 row_mask:0xf bank_mask:0xf
	v_mul_f32_dpp v84, v84, v84 row_shr:4 row_mask:0xf bank_mask:0xf
	v_mul_f32_dpp v85, v85, v85 row_shr:4 row_mask:0xf bank_mask:0xf
	v_mul_f32_dpp v86, v86, v86 row_shr:4 row_mask:0xf bank_mask:0xf
	v_mul_f32_dpp v87, v87, v87 row_shr:4 row_mask:0xf bank_mask:0xf
	v_fmac_f32_dpp v80, v80, v84 row_shr:8 row_mask:0xf bank_mask:0xf
	v_fmac_f32_dpp v81, v81, v85 row_shr:8 row_mask:0xf bank_mask:0xf
	v_fmac_f32_dpp v82, v82, v86 row_shr:8 row_mask:0xf bank_mask:0xf
	v_fmac_f32_dpp v83, v83, v87 row_shr:8 row_mask:0xf bank_mask:0xf
	v_mul_f32_dpp v84, v84, v84 row_shr:8 row_mask:0xf bank_mask:0xf
	v_mul_f32_dpp v85, v85, v85 row_shr:8 row_mask:0xf bank_mask:0xf
	v_mul_f32_dpp v86, v86, v86 row_shr:8 row_mask:0xf bank_mask:0xf
	v_mul_f32_dpp v87, v87, v87 row_shr:8 row_mask:0xf bank_mask:0xf
	s_nop 1
	v_mov_b32_dpp v176, v84 row_newbcast:15 row_mask:0xf bank_mask:0xf
	v_fmac_f32_e32 v80, v84, v145
	v_fmac_f32_e32 v81, v85, v146
	v_fmac_f32_e32 v82, v86, v147
	v_fmac_f32_e32 v83, v87, v179
	v_mov_b32_dpp v145, v80 row_newbcast:15 row_mask:0xf bank_mask:0xf
	v_mov_b32_dpp v146, v81 row_newbcast:15 row_mask:0xf bank_mask:0xf
	v_mov_b32_dpp v177, v85 row_newbcast:15 row_mask:0xf bank_mask:0xf
	v_mov_b32_dpp v147, v82 row_newbcast:15 row_mask:0xf bank_mask:0xf
	v_mov_b32_dpp v178, v86 row_newbcast:15 row_mask:0xf bank_mask:0xf
	v_mov_b32_dpp v183, v83 row_newbcast:15 row_mask:0xf bank_mask:0xf
	v_mov_b32_dpp v179, v87 row_newbcast:15 row_mask:0xf bank_mask:0xf
	ds_read_b128 v[80:83], v169 offset:26624
	ds_read_b128 v[88:91], v170 offset:26624
	s_waitcnt lgkmcnt(1)
	v_mfma_f32_16x16x32_bf16 v[84:87], v[4:7], v[80:83], 0
	ds_read_b128 v[92:95], v172 offset:26624
	v_mfma_f32_16x16x32_bf16 v[80:83], v[20:23], v[80:83], 0
	s_waitcnt lgkmcnt(1)
; #define LAS __attribute__((address_space(3)))
; template <int PASS> __device__ __forceinline__ void phase_lru(LAS unsigned char* lds, const bf16_t* Z, const bf16_t* WL, float* LSUM, const float* LCAR, bf16_t* RNN,
;                                                               int S, int tid, int lane, int wave, int G) {
;     ...
;                 for (int t = 0; t < 4; ++t) {
;                     f32x4 gr = (f32x4){0.f, 0.f, 0.f, 0.f}, gi = gr;
; #pragma unroll
;                     for (int s = 0; s < 4; ++s) { const bf16x8 bfr = *(const LAS bf16x8*)(lds + LRU_XC + off_b(16 * t + c, 4 * s + g4));
;                         gr = __builtin_amdgcn_mfma_f32_16x16x32_bf16(wf[0][s], bfr, gr, 0, 0, 0); gi = __builtin_amdgcn_mfma_f32_16x16x32_bf16(wf[1][s], bfr, gi, 0, 0, 0); }
;                     const f32x4 kba = kc[0 * 64 + lane], kbx = kc[1 * 64 + lane], ksp = kc[2 * 64 + lane];
;                     f32x4 av, hv;
; #pragma unroll
;                     for (int j = 0; j < 4; ++j) {
;                         const float rg = __builtin_amdgcn_rcpf(1.0f + __builtin_amdgcn_exp2f(fmaf(gr[j], -LOG2E, kba[j])));
;                         const float ig = __builtin_amdgcn_rcpf(1.0f + __builtin_amdgcn_exp2f(fmaf(gi[j], -LOG2E, kbx[j])));
;                         const float a_ = __builtin_amdgcn_exp2f(rg * ksp[j]);
;                         av[j] = a_; hv[j] = __builtin_amdgcn_sqrtf(fmaf(-a_, a_, 1.0f)) * (ig * xc[t][j]);
;                     }
;                     lru_scan4_fwd(av, hv);
; #pragma unroll
;                     for (int j = 0; j < 4; ++j) {
;                         const float hfull = fmaf(av[j], Hc[j], hv[j]);
;                         if (PASS == 1) hf[t][j] = hfull;
;                         Hc[j] = __shfl(hfull, (lane & 48) | 15);
;                         if (PASS == 0) Ac[j] *= __shfl(av[j], (lane & 48) | 15);
;                     }
	v_mfma_f32_16x16x32_bf16 v[84:87], v[8:11], v[88:91], v[84:87]
	v_mfma_f32_16x16x32_bf16 v[80:83], v[24:27], v[88:91], v[80:83]
	ds_read_b128 v[88:91], v171 offset:26624
	s_waitcnt lgkmcnt(0)
	v_mfma_f32_16x16x32_bf16 v[84:87], v[12:15], v[88:91], v[84:87]
	v_mfma_f32_16x16x32_bf16 v[80:83], v[28:31], v[88:91], v[80:83]
	v_mfma_f32_16x16x32_bf16 v[88:91], v[16:19], v[92:95], v[84:87]
	v_mfma_f32_16x16x32_bf16 v[80:83], v[32:35], v[92:95], v[80:83]
	ds_read_b128 v[96:99], v155 offset:36864
	s_nop 3
	ds_read_b128 v[84:87], v155 offset:37888
	ds_read_b128 v[92:95], v155 offset:38912
	s_waitcnt lgkmcnt(2)
	v_fmamk_f32 v88, v88, 0xbfb8aa3b, v96
	v_exp_f32_e32 v88, v88
	s_waitcnt lgkmcnt(1)
	v_fmamk_f32 v80, v80, 0xbfb8aa3b, v84
	v_exp_f32_e32 v80, v80
	v_fmamk_f32 v81, v81, 0xbfb8aa3b, v85
	v_add_f32_e32 v88, 1.0, v88
	v_rcp_f32_e32 v88, v88
	v_add_f32_e32 v80, 1.0, v80
	v_rcp_f32_e32 v80, v80
	v_exp_f32_e32 v81, v81
	s_waitcnt lgkmcnt(0)
	v_mul_f32_e32 v84, v92, v88
	v_exp_f32_e32 v84, v84
	v_mul_f32_e32 v80, v124, v80
	v_add_f32_e32 v81, 1.0, v81
	v_rcp_f32_e32 v81, v81
	v_fma_f32 v88, -v84, v84, 1.0
	v_sqrt_f32_e32 v88, v88
	v_fmamk_f32 v82, v82, 0xbfb8aa3b, v86
	v_mul_f32_e32 v81, v125, v81
	v_exp_f32_e32 v82, v82
	v_mul_f32_e32 v80, v80, v88
	v_fmamk_f32 v88, v89, 0xbfb8aa3b, v97
	v_exp_f32_e32 v88, v88
	v_add_f32_e32 v82, 1.0, v82
	v_rcp_f32_e32 v82, v82
	v_fmac_f32_e32 v99, 0xbfb8aa3b, v91
	v_add_f32_e32 v88, 1.0, v88
	v_rcp_f32_e32 v88, v88
	v_mul_f32_e32 v82, v122, v82
	v_fmac_f32_e32 v87, 0xbfb8aa3b, v83
	v_exp_f32_e32 v83, v87
	v_mul_f32_e32 v85, v93, v88
	v_exp_f32_e32 v85, v85
	v_add_f32_e32 v83, 1.0, v83
	v_rcp_f32_e32 v83, v83
	v_fma_f32 v88, -v85, v85, 1.0
	v_sqrt_f32_e32 v88, v88
	v_mul_f32_e32 v83, v123, v83
	v_mul_f32_e32 v81, v81, v88
	v_fmamk_f32 v88, v90, 0xbfb8aa3b, v98
	v_exp_f32_e32 v88, v88
	s_nop 0
	v_add_f32_e32 v88, 1.0, v88
	v_rcp_f32_e32 v88, v88
	s_nop 0
	v_mul_f32_e32 v86, v94, v88
	v_exp_f32_e32 v86, v86
	s_nop 0
	v_fma_f32 v88, -v86, v86, 1.0
	v_sqrt_f32_e32 v88, v88
	s_nop 0
	v_mul_f32_e32 v82, v82, v88
	v_exp_f32_e32 v88, v99
	s_nop 0
	v_add_f32_e32 v88, 1.0, v88
	v_rcp_f32_e32 v88, v88
	s_nop 0
	v_mul_f32_e32 v87, v95, v88
	v_exp_f32_e32 v87, v87
	s_nop 0
	v_fma_f32 v88, -v87, v87, 1.0
	v_sqrt_f32_e32 v88, v88
	s_nop 0
	v_mul_f32_e32 v83, v83, v88
	s_nop 1
	v_fmac_f32_dpp v80, v80, v84 row_shr:1 row_mask:0xf bank_mask:0xf
	v_fmac_f32_dpp v81, v81, v85 row_shr:1 row_mask:0xf bank_mask:0xf
	v_fmac_f32_dpp v82, v82, v86 row_shr:1 row_mask:0xf bank_mask:0xf
	v_fmac_f32_dpp v83, v83, v87 row_shr:1 row_mask:0xf bank_mask:0xf
	v_mul_f32_dpp v84, v84, v84 row_shr:1 row_mask:0xf bank_mask:0xf
	v_mul_f32_dpp v85, v85, v85 row_shr:1 row_mask:0xf bank_mask:0xf
	v_mul_f32_dpp v86, v86, v86 row_shr:1 row_mask:0xf bank_mask:0xf
	v_mul_f32_dpp v87, v87, v87 row_shr:1 row_mask:0xf bank_mask:0xf
	v_fmac_f32_dpp v80, v80, v84 row_shr:2 row_mask:0xf bank_mask:0xf
	v_fmac_f32_dpp v81, v81, v85 row_shr:2 row_mask:0xf bank_mask:0xf
	v_fmac_f32_dpp v82, v82, v86 row_shr:2 row_mask:0xf bank_mask:0xf
	v_fmac_f32_dpp v83, v83, v87 row_shr:2 row_mask:0xf bank_mask:0xf
	v_mul_f32_dpp v84, v84, v84 row_shr:2 row_mask:0xf bank_mask:0xf
	v_mul_f32_dpp v85, v85, v85 row_shr:2 row_mask:0xf bank_mask:0xf
	v_mul_f32_dpp v86, v86, v86 row_shr:2 row_mask:0xf bank_mask:0xf
	v_mul_f32_dpp v87, v87, v87 row_shr:2 row_mask:0xf bank_mask:0xf
	v_fmac_f32_dpp v80, v80, v84 row_shr:4 row_mask:0xf bank_mask:0xf
	v_fmac_f32_dpp v81, v81, v85 row_shr:4 row_mask:0xf bank_mask:0xf
	v_fmac_f32_dpp v82, v82, v86 row_shr:4 row_mask:0xf bank_mask:0xf
	v_fmac_f32_dpp v83, v83, v87 row_shr:4 row_mask:0xf bank_mask:0xf
	v_mul_f32_dpp v84, v84, v84 row_shr:4 row_mask:0xf bank_mask:0xf
	v_mul_f32_dpp v85, v85, v85 row_shr:4 row_mask:0xf bank_mask:0xf
	v_mul_f32_dpp v86, v86, v86 row_shr:4 row_mask:0xf bank_mask:0xf
	v_mul_f32_dpp v87, v87, v87 row_shr:4 row_mask:0xf bank_mask:0xf
	v_fmac_f32_dpp v80, v80, v84 row_shr:8 row_mask:0xf bank_mask:0xf
	v_fmac_f32_dpp v81, v81, v85 row_shr:8 row_mask:0xf bank_mask:0xf
	v_fmac_f32_dpp v82, v82, v86 row_shr:8 row_mask:0xf bank_mask:0xf
	v_fmac_f32_dpp v83, v83, v87 row_shr:8 row_mask:0xf bank_mask:0xf
	v_mul_f32_dpp v84, v84, v84 row_shr:8 row_mask:0xf bank_mask:0xf
	v_mul_f32_dpp v85, v85, v85 row_shr:8 row_mask:0xf bank_mask:0xf
	v_mul_f32_dpp v86, v86, v86 row_shr:8 row_mask:0xf bank_mask:0xf
	v_mul_f32_dpp v87, v87, v87 row_shr:8 row_mask:0xf bank_mask:0xf
	s_nop 1
	v_mov_b32_dpp v180, v84 row_newbcast:15 row_mask:0xf bank_mask:0xf
	v_fmac_f32_e32 v80, v84, v145
	v_fmac_f32_e32 v81, v85, v146
	v_fmac_f32_e32 v82, v86, v147
	v_mov_b32_dpp v145, v80 row_newbcast:15 row_mask:0xf bank_mask:0xf
	v_mov_b32_dpp v146, v81 row_newbcast:15 row_mask:0xf bank_mask:0xf
	v_mov_b32_dpp v181, v85 row_newbcast:15 row_mask:0xf bank_mask:0xf
	v_mov_b32_dpp v147, v82 row_newbcast:15 row_mask:0xf bank_mask:0xf
	v_mov_b32_dpp v182, v86 row_newbcast:15 row_mask:0xf bank_mask:0xf
	v_fmac_f32_e32 v83, v87, v183
	v_mov_b32_dpp v183, v87 row_newbcast:15 row_mask:0xf bank_mask:0xf
	s_nop 1
	v_mov_b32_dpp v184, v83 row_newbcast:15 row_mask:0xf bank_mask:0xf
	ds_read_b128 v[80:83], v169 offset:30720
	ds_read_b128 v[88:91], v170 offset:30720
	s_waitcnt lgkmcnt(1)
	v_mfma_f32_16x16x32_bf16 v[84:87], v[4:7], v[80:83], 0
	ds_read_b128 v[92:95], v172 offset:30720
	v_mfma_f32_16x16x32_bf16 v[80:83], v[20:23], v[80:83], 0
	s_waitcnt lgkmcnt(1)
	v_mfma_f32_16x16x32_bf16 v[84:87], v[8:11], v[88:91], v[84:87]
	v_mfma_f32_16x16x32_bf16 v[80:83], v[24:27], v[88:91], v[80:83]
	ds_read_b128 v[88:91], v171 offset:30720
	s_waitcnt lgkmcnt(0)
; #define LAS __attribute__((address_space(3)))
; template <int PASS> __device__ __forceinline__ void phase_lru(LAS unsigned char* lds, const bf16_t* Z, const bf16_t* WL, float* LSUM, const float* LCAR, bf16_t* RNN,
;                                                               int S, int tid, int lane, int wave, int G) {
;     ...
;                 for (int t = 0; t < 4; ++t) {
;                     f32x4 gr = (f32x4){0.f, 0.f, 0.f, 0.f}, gi = gr;
; #pragma unroll
;                     for (int s = 0; s < 4; ++s) { const bf16x8 bfr = *(const LAS bf16x8*)(lds + LRU_XC + off_b(16 * t + c, 4 * s + g4));
;                         gr = __builtin_amdgcn_mfma_f32_16x16x32_bf16(wf[0][s], bfr, gr, 0, 0, 0); gi = __builtin_amdgcn_mfma_f32_16x16x32_bf16(wf[1][s], bfr, gi, 0, 0, 0); }
;                     const f32x4 kba = kc[0 * 64 + lane], kbx = kc[1 * 64 + lane], ksp = kc[2 * 64 + lane];
;                     f32x4 av, hv;
; #pragma unroll
;                     for (int j = 0; j < 4; ++j) {
;                         const float rg = __builtin_amdgcn_rcpf(1.0f + __builtin_amdgcn_exp2f(fmaf(gr[j], -LOG2E, kba[j])));
;                         const float ig = __builtin_amdgcn_rcpf(1.0f + __builtin_amdgcn_exp2f(fmaf(gi[j], -LOG2E, kbx[j])));
;                         const float a_ = __builtin_amdgcn_exp2f(rg * ksp[j]);
;                         av[j] = a_; hv[j] = __builtin_amdgcn_sqrtf(fmaf(-a_, a_, 1.0f)) * (ig * xc[t][j]);
;                     }
;                     lru_scan4_fwd(av, hv);
; #pragma unroll
;                     for (int j = 0; j < 4; ++j) {
;                         const float hfull = fmaf(av[j], Hc[j], hv[j]);
;                         if (PASS == 1) hf[t][j] = hfull;
;                         Hc[j] = __shfl(hfull, (lane & 48) | 15);
;                         if (PASS == 0) Ac[j] *= __shfl(av[j], (lane & 48) | 15);
;                     }
;                     __builtin_amdgcn_sched_barrier(0);
;                 }
;                 if (PASS == 0 && c == 0) {
; #pragma unroll
;                     for (int j = 0; j < 4; ++j) { float* sp = LSUM + ((size_t)(seg * 2 + 0) * LW + ch0 + j) * 2; sp[0] = Ac[j]; sp[1] = Hc[j]; }
;                 }
	v_mfma_f32_16x16x32_bf16 v[84:87], v[12:15], v[88:91], v[84:87]
	v_mfma_f32_16x16x32_bf16 v[80:83], v[28:31], v[88:91], v[80:83]
	v_mfma_f32_16x16x32_bf16 v[88:91], v[16:19], v[92:95], v[84:87]
	v_mfma_f32_16x16x32_bf16 v[80:83], v[32:35], v[92:95], v[80:83]
	ds_read_b128 v[96:99], v155 offset:36864
	s_nop 3
	ds_read_b128 v[84:87], v155 offset:37888
	ds_read_b128 v[92:95], v155 offset:38912
	s_waitcnt lgkmcnt(2)
	v_fmamk_f32 v88, v88, 0xbfb8aa3b, v96
	v_exp_f32_e32 v88, v88
	s_waitcnt lgkmcnt(1)
	v_fmamk_f32 v80, v80, 0xbfb8aa3b, v84
	v_exp_f32_e32 v80, v80
	v_fmamk_f32 v81, v81, 0xbfb8aa3b, v85
	v_add_f32_e32 v88, 1.0, v88
	v_rcp_f32_e32 v88, v88
	v_add_f32_e32 v80, 1.0, v80
	v_rcp_f32_e32 v80, v80
	v_exp_f32_e32 v81, v81
	s_waitcnt lgkmcnt(0)
	v_mul_f32_e32 v84, v92, v88
	v_exp_f32_e32 v84, v84
	v_mul_f32_e32 v80, v128, v80
	v_add_f32_e32 v81, 1.0, v81
	v_rcp_f32_e32 v81, v81
	v_fma_f32 v88, -v84, v84, 1.0
	v_sqrt_f32_e32 v88, v88
	v_fmamk_f32 v82, v82, 0xbfb8aa3b, v86
	v_mul_f32_e32 v81, v129, v81
	v_exp_f32_e32 v82, v82
	v_mul_f32_e32 v80, v80, v88
	v_fmamk_f32 v88, v89, 0xbfb8aa3b, v97
	v_exp_f32_e32 v88, v88
	v_add_f32_e32 v82, 1.0, v82
	v_rcp_f32_e32 v82, v82
	v_fmac_f32_e32 v99, 0xbfb8aa3b, v91
	v_add_f32_e32 v88, 1.0, v88
	v_rcp_f32_e32 v88, v88
	v_mul_f32_e32 v82, v126, v82
	v_fmac_f32_e32 v87, 0xbfb8aa3b, v83
	v_exp_f32_e32 v83, v87
	v_mul_f32_e32 v85, v93, v88
	v_exp_f32_e32 v88, v85
	v_add_f32_e32 v83, 1.0, v83
	v_rcp_f32_e32 v83, v83
	v_fma_f32 v85, -v88, v88, 1.0
	v_sqrt_f32_e32 v85, v85
	v_mul_f32_e32 v83, v127, v83
	v_mul_f32_e32 v81, v81, v85
	v_fmamk_f32 v85, v90, 0xbfb8aa3b, v98
	v_exp_f32_e32 v85, v85
	s_nop 0
	v_add_f32_e32 v85, 1.0, v85
	v_rcp_f32_e32 v85, v85
	s_nop 0
	v_mul_f32_e32 v85, v94, v85
	v_exp_f32_e32 v89, v85
	s_nop 0
	v_fma_f32 v85, -v89, v89, 1.0
	v_sqrt_f32_e32 v85, v85
	s_nop 0
	v_mul_f32_e32 v82, v82, v85
	v_exp_f32_e32 v85, v99
	s_nop 0
	v_add_f32_e32 v85, 1.0, v85
	v_rcp_f32_e32 v85, v85
	s_nop 0
	v_mul_f32_e32 v85, v95, v85
	v_exp_f32_e32 v90, v85
	s_nop 0
	v_fma_f32 v85, -v90, v90, 1.0
	v_sqrt_f32_e32 v85, v85
	s_nop 0
	v_mul_f32_e32 v91, v83, v85
	s_nop 1
	v_fmac_f32_dpp v80, v80, v84 row_shr:1 row_mask:0xf bank_mask:0xf
	v_fmac_f32_dpp v81, v81, v88 row_shr:1 row_mask:0xf bank_mask:0xf
	v_fmac_f32_dpp v82, v82, v89 row_shr:1 row_mask:0xf bank_mask:0xf
	v_fmac_f32_dpp v91, v91, v90 row_shr:1 row_mask:0xf bank_mask:0xf
	v_mul_f32_dpp v84, v84, v84 row_shr:1 row_mask:0xf bank_mask:0xf
	v_mul_f32_dpp v88, v88, v88 row_shr:1 row_mask:0xf bank_mask:0xf
	v_mul_f32_dpp v89, v89, v89 row_shr:1 row_mask:0xf bank_mask:0xf
	v_mul_f32_dpp v90, v90, v90 row_shr:1 row_mask:0xf bank_mask:0xf
	v_fmac_f32_dpp v80, v80, v84 row_shr:2 row_mask:0xf bank_mask:0xf
	v_fmac_f32_dpp v81, v81, v88 row_shr:2 row_mask:0xf bank_mask:0xf
	v_fmac_f32_dpp v82, v82, v89 row_shr:2 row_mask:0xf bank_mask:0xf
	v_fmac_f32_dpp v91, v91, v90 row_shr:2 row_mask:0xf bank_mask:0xf
	v_mul_f32_dpp v84, v84, v84 row_shr:2 row_mask:0xf bank_mask:0xf
	v_mul_f32_dpp v88, v88, v88 row_shr:2 row_mask:0xf bank_mask:0xf
	v_mul_f32_dpp v89, v89, v89 row_shr:2 row_mask:0xf bank_mask:0xf
	v_mul_f32_dpp v90, v90, v90 row_shr:2 row_mask:0xf bank_mask:0xf
	v_fmac_f32_dpp v80, v80, v84 row_shr:4 row_mask:0xf bank_mask:0xf
	v_fmac_f32_dpp v81, v81, v88 row_shr:4 row_mask:0xf bank_mask:0xf
	v_fmac_f32_dpp v82, v82, v89 row_shr:4 row_mask:0xf bank_mask:0xf
	v_fmac_f32_dpp v91, v91, v90 row_shr:4 row_mask:0xf bank_mask:0xf
	v_mul_f32_dpp v84, v84, v84 row_shr:4 row_mask:0xf bank_mask:0xf
	v_mul_f32_dpp v88, v88, v88 row_shr:4 row_mask:0xf bank_mask:0xf
	v_mul_f32_dpp v89, v89, v89 row_shr:4 row_mask:0xf bank_mask:0xf
	v_mul_f32_dpp v90, v90, v90 row_shr:4 row_mask:0xf bank_mask:0xf
	v_fmac_f32_dpp v80, v80, v84 row_shr:8 row_mask:0xf bank_mask:0xf
	v_fmac_f32_dpp v81, v81, v88 row_shr:8 row_mask:0xf bank_mask:0xf
	v_fmac_f32_dpp v82, v82, v89 row_shr:8 row_mask:0xf bank_mask:0xf
	v_fmac_f32_dpp v91, v91, v90 row_shr:8 row_mask:0xf bank_mask:0xf
	v_mul_f32_dpp v84, v84, v84 row_shr:8 row_mask:0xf bank_mask:0xf
	v_mul_f32_dpp v88, v88, v88 row_shr:8 row_mask:0xf bank_mask:0xf
	v_mul_f32_dpp v89, v89, v89 row_shr:8 row_mask:0xf bank_mask:0xf
	v_mul_f32_dpp v90, v90, v90 row_shr:8 row_mask:0xf bank_mask:0xf
	s_nop 1
	v_mov_b32_dpp v86, v84 row_newbcast:15 row_mask:0xf bank_mask:0xf
	v_fmac_f32_e32 v80, v84, v145
	v_fmac_f32_e32 v81, v88, v146
	v_fmac_f32_e32 v82, v89, v147
	v_fmac_f32_e32 v91, v90, v184
	v_mov_b32_dpp v87, v80 row_newbcast:15 row_mask:0xf bank_mask:0xf
	v_mov_b32_dpp v85, v81 row_newbcast:15 row_mask:0xf bank_mask:0xf
	v_mov_b32_dpp v84, v88 row_newbcast:15 row_mask:0xf bank_mask:0xf
	v_mov_b32_dpp v83, v82 row_newbcast:15 row_mask:0xf bank_mask:0xf
	v_mov_b32_dpp v82, v89 row_newbcast:15 row_mask:0xf bank_mask:0xf
	v_mov_b32_dpp v81, v91 row_newbcast:15 row_mask:0xf bank_mask:0xf
	v_mov_b32_dpp v80, v90 row_newbcast:15 row_mask:0xf bank_mask:0xf
	v_lshl_add_u64 v[146:147], v[2:3], 0, s[0:1]
	v_lshl_add_u64 v[144:145], v[106:107], 0, s[0:1]
	s_and_saveexec_b64 s[18:19], s[40:41]
	s_cbranch_execz .LBB0_235
	v_mul_f32_e32 v88, v175, v179
	v_mul_f32_e32 v88, v88, v183
	s_waitcnt lgkmcnt(0)
	v_mul_f32_e32 v80, v88, v80
	v_mul_f32_e32 v88, v174, v178
	v_mul_f32_e32 v88, v88, v182
	v_mul_f32_e32 v82, v88, v82
	v_mul_f32_e32 v88, v173, v177
	v_mul_f32_e32 v88, v88, v181
	v_mul_f32_e32 v1, v1, v176
	v_mul_f32_e32 v84, v88, v84
	v_mul_f32_e32 v1, v1, v180
	v_add_co_u32_e32 v88, vcc, 0x8300000, v144
	v_mul_f32_e32 v86, v1, v86
	s_nop 0
	v_addc_co_u32_e32 v89, vcc, 0, v145, vcc
	global_store_dwordx2 v[88:89], v[86:87], off
	v_or_b32_e32 v86, 8, v146
	v_mov_b32_e32 v87, v147
	v_lshl_add_u64 v[86:87], s[10:11], 0, v[86:87]
	global_store_dwordx2 v[86:87], v[84:85], off
	v_or_b32_e32 v84, 16, v146
	v_mov_b32_e32 v85, v147
	v_lshl_add_u64 v[84:85], s[10:11], 0, v[84:85]
	global_store_dwordx2 v[84:85], v[82:83], off
	v_or_b32_e32 v82, 24, v146
	v_mov_b32_e32 v83, v147
	v_lshl_add_u64 v[82:83], s[10:11], 0, v[82:83]
	global_store_dwordx2 v[82:83], v[80:81], off
; #define LAS __attribute__((address_space(3)))
; template <int PASS> __device__ __forceinline__ void phase_lru(LAS unsigned char* lds, const bf16_t* Z, const bf16_t* WL, float* LSUM, const float* LCAR, bf16_t* RNN,
;                                                               int S, int tid, int lane, int wave, int G) {
;     ...
;             {
;                 f32x4 Hc = (f32x4){0.f, 0.f, 0.f, 0.f}, Ac = (f32x4){1.f, 1.f, 1.f, 1.f};
;                 if (PASS == 1) Hc = car[1];
; #pragma unroll
;                 for (int tt = 0; tt < 4; ++tt) { const int t = 3 - tt;
;                     f32x4 gr = (f32x4){0.f, 0.f, 0.f, 0.f}, gi = gr;
; #pragma unroll
;                     for (int s = 0; s < 4; ++s) { const bf16x8 bfr = *(const LAS bf16x8*)(lds + LRU_XC + off_b(16 * t + c, 4 * s + g4));
;                         gr = __builtin_amdgcn_mfma_f32_16x16x32_bf16(wf[2][s], bfr, gr, 0, 0, 0); gi = __builtin_amdgcn_mfma_f32_16x16x32_bf16(wf[3][s], bfr, gi, 0, 0, 0); }
;                     f32x4 ov;
;                     const f32x4 kba = kc[3 * 64 + lane], kbx = kc[4 * 64 + lane], ksp = kc[5 * 64 + lane];
;                     f32x4 av, hv;
; #pragma unroll
;                     for (int j = 0; j < 4; ++j) {
;                         const float rg = __builtin_amdgcn_rcpf(1.0f + __builtin_amdgcn_exp2f(fmaf(gr[j], -LOG2E, kba[j])));
;                         const float ig = __builtin_amdgcn_rcpf(1.0f + __builtin_amdgcn_exp2f(fmaf(gi[j], -LOG2E, kbx[j])));
;                         const float a_ = __builtin_amdgcn_exp2f(rg * ksp[j]);
;                         av[j] = a_; hv[j] = __builtin_amdgcn_sqrtf(fmaf(-a_, a_, 1.0f)) * (ig * xc[t][j]);
;                     }
;                     lru_scan4_bwd(av, hv);
; #pragma unroll
;                     for (int j = 0; j < 4; ++j) {
;                         const float hfull = fmaf(av[j], Hc[j], hv[j]);
;                         Hc[j] = __shfl(hfull, lane & 48);
;                         if (PASS == 0) Ac[j] *= __shfl(av[j], lane & 48);
.LBB0_235:
	s_or_b64 exec, exec, s[18:19]
	s_waitcnt lgkmcnt(0)
	ds_read_b128 v[80:83], v169 offset:30720
	ds_read_b128 v[88:91], v170 offset:30720
	s_waitcnt lgkmcnt(1)
	v_mfma_f32_16x16x32_bf16 v[84:87], v[36:39], v[80:83], 0
	ds_read_b128 v[92:95], v172 offset:30720
	v_mfma_f32_16x16x32_bf16 v[80:83], v[52:55], v[80:83], 0
	s_waitcnt lgkmcnt(1)
	v_mfma_f32_16x16x32_bf16 v[84:87], v[40:43], v[88:91], v[84:87]
	v_mfma_f32_16x16x32_bf16 v[80:83], v[56:59], v[88:91], v[80:83]
	ds_read_b128 v[88:91], v171 offset:30720
	s_waitcnt lgkmcnt(0)
	v_mfma_f32_16x16x32_bf16 v[84:87], v[44:47], v[88:91], v[84:87]
	v_mfma_f32_16x16x32_bf16 v[80:83], v[60:63], v[88:91], v[80:83]
	v_mfma_f32_16x16x32_bf16 v[88:91], v[48:51], v[92:95], v[84:87]
	v_mfma_f32_16x16x32_bf16 v[80:83], v[64:67], v[92:95], v[80:83]
	ds_read_b128 v[96:99], v155 offset:39936
	s_nop 3
	ds_read_b128 v[84:87], v155 offset:40960
	ds_read_b128 v[92:95], v155 offset:41984
	s_waitcnt lgkmcnt(2)
	v_fmamk_f32 v1, v88, 0xbfb8aa3b, v96
	v_exp_f32_e32 v1, v1
	s_waitcnt lgkmcnt(1)
	v_fmamk_f32 v80, v80, 0xbfb8aa3b, v84
	v_exp_f32_e32 v80, v80
	v_fmamk_f32 v81, v81, 0xbfb8aa3b, v85
	v_add_f32_e32 v1, 1.0, v1
	v_rcp_f32_e32 v1, v1
	v_add_f32_e32 v80, 1.0, v80
	v_rcp_f32_e32 v80, v80
	v_exp_f32_e32 v81, v81
	s_waitcnt lgkmcnt(0)
	v_mul_f32_e32 v1, v92, v1
	v_exp_f32_e32 v1, v1
	v_mul_f32_e32 v80, v128, v80
	v_add_f32_e32 v81, 1.0, v81
	v_rcp_f32_e32 v81, v81
	v_fma_f32 v84, -v1, v1, 1.0
	v_sqrt_f32_e32 v84, v84
	v_fmamk_f32 v82, v82, 0xbfb8aa3b, v86
	v_mul_f32_e32 v81, v129, v81
	v_exp_f32_e32 v82, v82
	v_mul_f32_e32 v80, v80, v84
	v_fmamk_f32 v84, v89, 0xbfb8aa3b, v97
	v_exp_f32_e32 v84, v84
	v_add_f32_e32 v82, 1.0, v82
	v_rcp_f32_e32 v82, v82
	v_fmac_f32_e32 v99, 0xbfb8aa3b, v91
	v_add_f32_e32 v84, 1.0, v84
	v_rcp_f32_e32 v84, v84
	v_mul_f32_e32 v82, v126, v82
	v_fmac_f32_e32 v87, 0xbfb8aa3b, v83
	v_exp_f32_e32 v83, v87
	v_mul_f32_e32 v84, v93, v84
	v_exp_f32_e32 v84, v84
	v_add_f32_e32 v83, 1.0, v83
	v_rcp_f32_e32 v83, v83
	v_fma_f32 v85, -v84, v84, 1.0
	v_sqrt_f32_e32 v85, v85
	v_mul_f32_e32 v83, v127, v83
	v_mul_f32_e32 v81, v81, v85
	v_fmamk_f32 v85, v90, 0xbfb8aa3b, v98
	v_exp_f32_e32 v85, v85
	s_nop 0
	v_add_f32_e32 v85, 1.0, v85
	v_rcp_f32_e32 v85, v85
	s_nop 0
	v_mul_f32_e32 v85, v94, v85
	v_exp_f32_e32 v85, v85
	s_nop 0
	v_fma_f32 v86, -v85, v85, 1.0
	v_sqrt_f32_e32 v86, v86
	s_nop 0
	v_mul_f32_e32 v82, v82, v86
	v_exp_f32_e32 v86, v99
	s_nop 0
	v_add_f32_e32 v86, 1.0, v86
	v_rcp_f32_e32 v86, v86
	s_nop 0
	v_mul_f32_e32 v86, v95, v86
	v_exp_f32_e32 v86, v86
	s_nop 0
	v_fma_f32 v87, -v86, v86, 1.0
	v_sqrt_f32_e32 v87, v87
	s_nop 0
	v_mul_f32_e32 v83, v83, v87
	s_nop 1
	v_fmac_f32_dpp v80, v80, v1 row_shl:1 row_mask:0xf bank_mask:0xf
	v_fmac_f32_dpp v81, v81, v84 row_shl:1 row_mask:0xf bank_mask:0xf
	v_fmac_f32_dpp v82, v82, v85 row_shl:1 row_mask:0xf bank_mask:0xf
	v_fmac_f32_dpp v83, v83, v86 row_shl:1 row_mask:0xf bank_mask:0xf
	v_mul_f32_dpp v1, v1, v1 row_shl:1 row_mask:0xf bank_mask:0xf
	v_mul_f32_dpp v84, v84, v84 row_shl:1 row_mask:0xf bank_mask:0xf
	v_mul_f32_dpp v85, v85, v85 row_shl:1 row_mask:0xf bank_mask:0xf
	v_mul_f32_dpp v86, v86, v86 row_shl:1 row_mask:0xf bank_mask:0xf
	v_fmac_f32_dpp v80, v80, v1 row_shl:2 row_mask:0xf bank_mask:0xf
	v_fmac_f32_dpp v81, v81, v84 row_shl:2 row_mask:0xf bank_mask:0xf
	v_fmac_f32_dpp v82, v82, v85 row_shl:2 row_mask:0xf bank_mask:0xf
	v_fmac_f32_dpp v83, v83, v86 row_shl:2 row_mask:0xf bank_mask:0xf
	v_mul_f32_dpp v1, v1, v1 row_shl:2 row_mask:0xf bank_mask:0xf
	v_mul_f32_dpp v84, v84, v84 row_shl:2 row_mask:0xf bank_mask:0xf
	v_mul_f32_dpp v85, v85, v85 row_shl:2 row_mask:0xf bank_mask:0xf
	v_mul_f32_dpp v86, v86, v86 row_shl:2 row_mask:0xf bank_mask:0xf
	v_fmac_f32_dpp v80, v80, v1 row_shl:4 row_mask:0xf bank_mask:0xf
	v_fmac_f32_dpp v81, v81, v84 row_shl:4 row_mask:0xf bank_mask:0xf
	v_fmac_f32_dpp v82, v82, v85 row_shl:4 row_mask:0xf bank_mask:0xf
	v_fmac_f32_dpp v83, v83, v86 row_shl:4 row_mask:0xf bank_mask:0xf
	v_mul_f32_dpp v1, v1, v1 row_shl:4 row_mask:0xf bank_mask:0xf
	v_mul_f32_dpp v84, v84, v84 row_shl:4 row_mask:0xf bank_mask:0xf
	v_mul_f32_dpp v85, v85, v85 row_shl:4 row_mask:0xf bank_mask:0xf
	v_mul_f32_dpp v86, v86, v86 row_shl:4 row_mask:0xf bank_mask:0xf
	v_fmac_f32_dpp v80, v80, v1 row_shl:8 row_mask:0xf bank_mask:0xf
	v_fmac_f32_dpp v81, v81, v84 row_shl:8 row_mask:0xf bank_mask:0xf
	v_fmac_f32_dpp v82, v82, v85 row_shl:8 row_mask:0xf bank_mask:0xf
	v_fmac_f32_dpp v83, v83, v86 row_shl:8 row_mask:0xf bank_mask:0xf
	v_mul_f32_dpp v1, v1, v1 row_shl:8 row_mask:0xf bank_mask:0xf
	v_mul_f32_dpp v84, v84, v84 row_shl:8 row_mask:0xf bank_mask:0xf
	v_mul_f32_dpp v85, v85, v85 row_shl:8 row_mask:0xf bank_mask:0xf
	v_mul_f32_dpp v86, v86, v86 row_shl:8 row_mask:0xf bank_mask:0xf
	s_nop 1
	v_mov_b32_dpp v126, v84 row_newbcast:0 row_mask:0xf bank_mask:0xf
	v_fmac_f32_e32 v80, 0, v1
	v_mov_b32_dpp v1, v1 row_newbcast:0 row_mask:0xf bank_mask:0xf
	v_mov_b32_dpp v127, v85 row_newbcast:0 row_mask:0xf bank_mask:0xf
	v_mov_b32_dpp v128, v86 row_newbcast:0 row_mask:0xf bank_mask:0xf
	v_fmac_f32_e32 v81, 0, v84
	v_fmac_f32_e32 v82, 0, v85
	v_fmac_f32_e32 v83, 0, v86
	v_mov_b32_dpp v129, v80 row_newbcast:0 row_mask:0xf bank_mask:0xf
	v_mov_b32_dpp v173, v81 row_newbcast:0 row_mask:0xf bank_mask:0xf
	v_mov_b32_dpp v174, v82 row_newbcast:0 row_mask:0xf bank_mask:0xf
	v_mov_b32_dpp v175, v83 row_newbcast:0 row_mask:0xf bank_mask:0xf
	ds_read_b128 v[80:83], v169 offset:26624
	ds_read_b128 v[88:91], v170 offset:26624
	s_waitcnt lgkmcnt(1)
	v_mfma_f32_16x16x32_bf16 v[84:87], v[36:39], v[80:83], 0
	ds_read_b128 v[92:95], v172 offset:26624
	v_mfma_f32_16x16x32_bf16 v[80:83], v[52:55], v[80:83], 0
	s_waitcnt lgkmcnt(1)
; #define LAS __attribute__((address_space(3)))
; template <int PASS> __device__ __forceinline__ void phase_lru(LAS unsigned char* lds, const bf16_t* Z, const bf16_t* WL, float* LSUM, const float* LCAR, bf16_t* RNN,
;                                                               int S, int tid, int lane, int wave, int G) {
;     ...
;                 for (int tt = 0; tt < 4; ++tt) { const int t = 3 - tt;
;                     f32x4 gr = (f32x4){0.f, 0.f, 0.f, 0.f}, gi = gr;
; #pragma unroll
;                     for (int s = 0; s < 4; ++s) { const bf16x8 bfr = *(const LAS bf16x8*)(lds + LRU_XC + off_b(16 * t + c, 4 * s + g4));
;                         gr = __builtin_amdgcn_mfma_f32_16x16x32_bf16(wf[2][s], bfr, gr, 0, 0, 0); gi = __builtin_amdgcn_mfma_f32_16x16x32_bf16(wf[3][s], bfr, gi, 0, 0, 0); }
;                     f32x4 ov;
;                     const f32x4 kba = kc[3 * 64 + lane], kbx = kc[4 * 64 + lane], ksp = kc[5 * 64 + lane];
;                     f32x4 av, hv;
; #pragma unroll
;                     for (int j = 0; j < 4; ++j) {
;                         const float rg = __builtin_amdgcn_rcpf(1.0f + __builtin_amdgcn_exp2f(fmaf(gr[j], -LOG2E, kba[j])));
;                         const float ig = __builtin_amdgcn_rcpf(1.0f + __builtin_amdgcn_exp2f(fmaf(gi[j], -LOG2E, kbx[j])));
;                         const float a_ = __builtin_amdgcn_exp2f(rg * ksp[j]);
;                         av[j] = a_; hv[j] = __builtin_amdgcn_sqrtf(fmaf(-a_, a_, 1.0f)) * (ig * xc[t][j]);
;                     }
;                     lru_scan4_bwd(av, hv);
; #pragma unroll
;                     for (int j = 0; j < 4; ++j) {
;                         const float hfull = fmaf(av[j], Hc[j], hv[j]);
;                         Hc[j] = __shfl(hfull, lane & 48);
;                         if (PASS == 0) Ac[j] *= __shfl(av[j], lane & 48);
	v_mfma_f32_16x16x32_bf16 v[84:87], v[40:43], v[88:91], v[84:87]
	v_mfma_f32_16x16x32_bf16 v[80:83], v[56:59], v[88:91], v[80:83]
	ds_read_b128 v[88:91], v171 offset:26624
	s_waitcnt lgkmcnt(0)
	v_mfma_f32_16x16x32_bf16 v[84:87], v[44:47], v[88:91], v[84:87]
	v_mfma_f32_16x16x32_bf16 v[80:83], v[60:63], v[88:91], v[80:83]
	v_mfma_f32_16x16x32_bf16 v[88:91], v[48:51], v[92:95], v[84:87]
	v_mfma_f32_16x16x32_bf16 v[80:83], v[64:67], v[92:95], v[80:83]
	ds_read_b128 v[96:99], v155 offset:39936
	s_nop 3
	ds_read_b128 v[84:87], v155 offset:40960
	ds_read_b128 v[92:95], v155 offset:41984
	s_waitcnt lgkmcnt(2)
	v_fmamk_f32 v88, v88, 0xbfb8aa3b, v96
	v_exp_f32_e32 v88, v88
	s_waitcnt lgkmcnt(1)
	v_fmamk_f32 v80, v80, 0xbfb8aa3b, v84
	v_exp_f32_e32 v80, v80
	v_fmamk_f32 v81, v81, 0xbfb8aa3b, v85
	v_add_f32_e32 v88, 1.0, v88
	v_rcp_f32_e32 v88, v88
	v_add_f32_e32 v80, 1.0, v80
	v_rcp_f32_e32 v80, v80
	v_exp_f32_e32 v81, v81
	s_waitcnt lgkmcnt(0)
	v_mul_f32_e32 v84, v92, v88
	v_exp_f32_e32 v84, v84
	v_mul_f32_e32 v80, v124, v80
	v_add_f32_e32 v81, 1.0, v81
	v_rcp_f32_e32 v81, v81
	v_fma_f32 v88, -v84, v84, 1.0
	v_sqrt_f32_e32 v88, v88
	v_fmamk_f32 v82, v82, 0xbfb8aa3b, v86
	v_mul_f32_e32 v81, v125, v81
	v_exp_f32_e32 v82, v82
	v_mul_f32_e32 v80, v80, v88
	v_fmamk_f32 v88, v89, 0xbfb8aa3b, v97
	v_exp_f32_e32 v88, v88
	v_add_f32_e32 v82, 1.0, v82
	v_rcp_f32_e32 v82, v82
	v_fmac_f32_e32 v99, 0xbfb8aa3b, v91
	v_add_f32_e32 v88, 1.0, v88
	v_rcp_f32_e32 v88, v88
	v_mul_f32_e32 v82, v122, v82
	v_fmac_f32_e32 v87, 0xbfb8aa3b, v83
	v_exp_f32_e32 v83, v87
	v_mul_f32_e32 v85, v93, v88
	v_exp_f32_e32 v85, v85
	v_add_f32_e32 v83, 1.0, v83
	v_rcp_f32_e32 v83, v83
	v_fma_f32 v88, -v85, v85, 1.0
	v_sqrt_f32_e32 v88, v88
	v_mul_f32_e32 v83, v123, v83
	v_mul_f32_e32 v81, v81, v88
	v_fmamk_f32 v88, v90, 0xbfb8aa3b, v98
	v_exp_f32_e32 v88, v88
	s_nop 0
	v_add_f32_e32 v88, 1.0, v88
	v_rcp_f32_e32 v88, v88
	s_nop 0
	v_mul_f32_e32 v86, v94, v88
	v_exp_f32_e32 v86, v86
	s_nop 0
	v_fma_f32 v88, -v86, v86, 1.0
	v_sqrt_f32_e32 v88, v88
	s_nop 0
	v_mul_f32_e32 v82, v82, v88
	v_exp_f32_e32 v88, v99
	s_nop 0
	v_add_f32_e32 v88, 1.0, v88
	v_rcp_f32_e32 v88, v88
	s_nop 0
	v_mul_f32_e32 v87, v95, v88
	v_exp_f32_e32 v87, v87
	s_nop 0
	v_fma_f32 v88, -v87, v87, 1.0
	v_sqrt_f32_e32 v88, v88
	s_nop 0
	v_mul_f32_e32 v83, v83, v88
	s_nop 1
	v_fmac_f32_dpp v80, v80, v84 row_shl:1 row_mask:0xf bank_mask:0xf
	v_fmac_f32_dpp v81, v81, v85 row_shl:1 row_mask:0xf bank_mask:0xf
	v_fmac_f32_dpp v82, v82, v86 row_shl:1 row_mask:0xf bank_mask:0xf
	v_fmac_f32_dpp v83, v83, v87 row_shl:1 row_mask:0xf bank_mask:0xf
	v_mul_f32_dpp v84, v84, v84 row_shl:1 row_mask:0xf bank_mask:0xf
	v_mul_f32_dpp v85, v85, v85 row_shl:1 row_mask:0xf bank_mask:0xf
	v_mul_f32_dpp v86, v86, v86 row_shl:1 row_mask:0xf bank_mask:0xf
	v_mul_f32_dpp v87, v87, v87 row_shl:1 row_mask:0xf bank_mask:0xf
	v_fmac_f32_dpp v80, v80, v84 row_shl:2 row_mask:0xf bank_mask:0xf
	v_fmac_f32_dpp v81, v81, v85 row_shl:2 row_mask:0xf bank_mask:0xf
	v_fmac_f32_dpp v82, v82, v86 row_shl:2 row_mask:0xf bank_mask:0xf
	v_fmac_f32_dpp v83, v83, v87 row_shl:2 row_mask:0xf bank_mask:0xf
	v_mul_f32_dpp v84, v84, v84 row_shl:2 row_mask:0xf bank_mask:0xf
	v_mul_f32_dpp v85, v85, v85 row_shl:2 row_mask:0xf bank_mask:0xf
	v_mul_f32_dpp v86, v86, v86 row_shl:2 row_mask:0xf bank_mask:0xf
	v_mul_f32_dpp v87, v87, v87 row_shl:2 row_mask:0xf bank_mask:0xf
	v_fmac_f32_dpp v80, v80, v84 row_shl:4 row_mask:0xf bank_mask:0xf
	v_fmac_f32_dpp v81, v81, v85 row_shl:4 row_mask:0xf bank_mask:0xf
	v_fmac_f32_dpp v82, v82, v86 row_shl:4 row_mask:0xf bank_mask:0xf
	v_fmac_f32_dpp v83, v83, v87 row_shl:4 row_mask:0xf bank_mask:0xf
	v_mul_f32_dpp v84, v84, v84 row_shl:4 row_mask:0xf bank_mask:0xf
	v_mul_f32_dpp v85, v85, v85 row_shl:4 row_mask:0xf bank_mask:0xf
	v_mul_f32_dpp v86, v86, v86 row_shl:4 row_mask:0xf bank_mask:0xf
	v_mul_f32_dpp v87, v87, v87 row_shl:4 row_mask:0xf bank_mask:0xf
	v_fmac_f32_dpp v80, v80, v84 row_shl:8 row_mask:0xf bank_mask:0xf
	v_fmac_f32_dpp v81, v81, v85 row_shl:8 row_mask:0xf bank_mask:0xf
	v_fmac_f32_dpp v82, v82, v86 row_shl:8 row_mask:0xf bank_mask:0xf
	v_fmac_f32_dpp v83, v83, v87 row_shl:8 row_mask:0xf bank_mask:0xf
	v_mul_f32_dpp v84, v84, v84 row_shl:8 row_mask:0xf bank_mask:0xf
	v_mul_f32_dpp v85, v85, v85 row_shl:8 row_mask:0xf bank_mask:0xf
	v_mul_f32_dpp v86, v86, v86 row_shl:8 row_mask:0xf bank_mask:0xf
	v_mul_f32_dpp v87, v87, v87 row_shl:8 row_mask:0xf bank_mask:0xf
	s_nop 1
	v_mov_b32_dpp v122, v84 row_newbcast:0 row_mask:0xf bank_mask:0xf
	v_mov_b32_dpp v123, v85 row_newbcast:0 row_mask:0xf bank_mask:0xf
	v_mov_b32_dpp v124, v86 row_newbcast:0 row_mask:0xf bank_mask:0xf
	v_mov_b32_dpp v125, v87 row_newbcast:0 row_mask:0xf bank_mask:0xf
	v_fmac_f32_e32 v80, v84, v129
	v_fmac_f32_e32 v81, v85, v173
	v_fmac_f32_e32 v82, v86, v174
	v_fmac_f32_e32 v83, v87, v175
	v_mov_b32_dpp v129, v80 row_newbcast:0 row_mask:0xf bank_mask:0xf
	v_mov_b32_dpp v173, v81 row_newbcast:0 row_mask:0xf bank_mask:0xf
	v_mov_b32_dpp v174, v82 row_newbcast:0 row_mask:0xf bank_mask:0xf
	v_mov_b32_dpp v175, v83 row_newbcast:0 row_mask:0xf bank_mask:0xf
	ds_read_b128 v[80:83], v169 offset:22528
	ds_read_b128 v[88:91], v170 offset:22528
	s_waitcnt lgkmcnt(1)
	v_mfma_f32_16x16x32_bf16 v[84:87], v[36:39], v[80:83], 0
	ds_read_b128 v[92:95], v172 offset:22528
	v_mfma_f32_16x16x32_bf16 v[80:83], v[52:55], v[80:83], 0
	s_waitcnt lgkmcnt(1)
	v_mfma_f32_16x16x32_bf16 v[84:87], v[40:43], v[88:91], v[84:87]
	v_mfma_f32_16x16x32_bf16 v[80:83], v[56:59], v[88:91], v[80:83]
	ds_read_b128 v[88:91], v171 offset:22528
	s_waitcnt lgkmcnt(0)
; #define LAS __attribute__((address_space(3)))
; template <int PASS> __device__ __forceinline__ void phase_lru(LAS unsigned char* lds, const bf16_t* Z, const bf16_t* WL, float* LSUM, const float* LCAR, bf16_t* RNN,
;                                                               int S, int tid, int lane, int wave, int G) {
;     ...
;                 for (int tt = 0; tt < 4; ++tt) { const int t = 3 - tt;
;                     f32x4 gr = (f32x4){0.f, 0.f, 0.f, 0.f}, gi = gr;
; #pragma unroll
;                     for (int s = 0; s < 4; ++s) { const bf16x8 bfr = *(const LAS bf16x8*)(lds + LRU_XC + off_b(16 * t + c, 4 * s + g4));
;                         gr = __builtin_amdgcn_mfma_f32_16x16x32_bf16(wf[2][s], bfr, gr, 0, 0, 0); gi = __builtin_amdgcn_mfma_f32_16x16x32_bf16(wf[3][s], bfr, gi, 0, 0, 0); }
;                     f32x4 ov;
;                     const f32x4 kba = kc[3 * 64 + lane], kbx = kc[4 * 64 + lane], ksp = kc[5 * 64 + lane];
;                     f32x4 av, hv;
; #pragma unroll
;                     for (int j = 0; j < 4; ++j) {
;                         const float rg = __builtin_amdgcn_rcpf(1.0f + __builtin_amdgcn_exp2f(fmaf(gr[j], -LOG2E, kba[j])));
;                         const float ig = __builtin_amdgcn_rcpf(1.0f + __builtin_amdgcn_exp2f(fmaf(gi[j], -LOG2E, kbx[j])));
;                         const float a_ = __builtin_amdgcn_exp2f(rg * ksp[j]);
;                         av[j] = a_; hv[j] = __builtin_amdgcn_sqrtf(fmaf(-a_, a_, 1.0f)) * (ig * xc[t][j]);
;                     }
;                     lru_scan4_bwd(av, hv);
; #pragma unroll
;                     for (int j = 0; j < 4; ++j) {
;                         const float hfull = fmaf(av[j], Hc[j], hv[j]);
;                         Hc[j] = __shfl(hfull, lane & 48);
;                         if (PASS == 0) Ac[j] *= __shfl(av[j], lane & 48);
	v_mfma_f32_16x16x32_bf16 v[84:87], v[44:47], v[88:91], v[84:87]
	v_mfma_f32_16x16x32_bf16 v[80:83], v[60:63], v[88:91], v[80:83]
	v_mfma_f32_16x16x32_bf16 v[88:91], v[48:51], v[92:95], v[84:87]
	v_mfma_f32_16x16x32_bf16 v[80:83], v[64:67], v[92:95], v[80:83]
	ds_read_b128 v[96:99], v155 offset:39936
	s_nop 3
	ds_read_b128 v[84:87], v155 offset:40960
	ds_read_b128 v[92:95], v155 offset:41984
	s_waitcnt lgkmcnt(2)
	v_fmamk_f32 v88, v88, 0xbfb8aa3b, v96
	v_exp_f32_e32 v88, v88
	s_waitcnt lgkmcnt(1)
	v_fmamk_f32 v80, v80, 0xbfb8aa3b, v84
	v_exp_f32_e32 v80, v80
	v_fmamk_f32 v81, v81, 0xbfb8aa3b, v85
	v_add_f32_e32 v88, 1.0, v88
	v_rcp_f32_e32 v88, v88
	v_add_f32_e32 v80, 1.0, v80
	v_rcp_f32_e32 v80, v80
	v_exp_f32_e32 v81, v81
	s_waitcnt lgkmcnt(0)
	v_mul_f32_e32 v84, v92, v88
	v_exp_f32_e32 v84, v84
	v_mul_f32_e32 v80, v120, v80
	v_add_f32_e32 v81, 1.0, v81
	v_rcp_f32_e32 v81, v81
	v_fma_f32 v88, -v84, v84, 1.0
	v_sqrt_f32_e32 v88, v88
	v_fmamk_f32 v82, v82, 0xbfb8aa3b, v86
	v_mul_f32_e32 v81, v121, v81
	v_exp_f32_e32 v82, v82
	v_mul_f32_e32 v80, v80, v88
	v_fmamk_f32 v88, v89, 0xbfb8aa3b, v97
	v_exp_f32_e32 v88, v88
	v_add_f32_e32 v82, 1.0, v82
	v_rcp_f32_e32 v82, v82
	v_fmac_f32_e32 v99, 0xbfb8aa3b, v91
	v_add_f32_e32 v88, 1.0, v88
	v_rcp_f32_e32 v88, v88
	v_mul_f32_e32 v82, v118, v82
	v_fmac_f32_e32 v87, 0xbfb8aa3b, v83
	v_exp_f32_e32 v83, v87
	v_mul_f32_e32 v85, v93, v88
	v_exp_f32_e32 v85, v85
	v_add_f32_e32 v83, 1.0, v83
	v_rcp_f32_e32 v83, v83
	v_fma_f32 v88, -v85, v85, 1.0
	v_sqrt_f32_e32 v88, v88
	v_mul_f32_e32 v83, v119, v83
	v_mul_f32_e32 v81, v81, v88
	v_fmamk_f32 v88, v90, 0xbfb8aa3b, v98
	v_exp_f32_e32 v88, v88
	s_nop 0
	v_add_f32_e32 v88, 1.0, v88
	v_rcp_f32_e32 v88, v88
	s_nop 0
	v_mul_f32_e32 v86, v94, v88
	v_exp_f32_e32 v86, v86
	s_nop 0
	v_fma_f32 v88, -v86, v86, 1.0
	v_sqrt_f32_e32 v88, v88
	s_nop 0
	v_mul_f32_e32 v82, v82, v88
	v_exp_f32_e32 v88, v99
	s_nop 0
	v_add_f32_e32 v88, 1.0, v88
	v_rcp_f32_e32 v88, v88
	s_nop 0
	v_mul_f32_e32 v87, v95, v88
	v_exp_f32_e32 v87, v87
	s_nop 0
	v_fma_f32 v88, -v87, v87, 1.0
	v_sqrt_f32_e32 v88, v88
	s_nop 0
	v_mul_f32_e32 v83, v83, v88
	s_nop 1
	v_fmac_f32_dpp v80, v80, v84 row_shl:1 row_mask:0xf bank_mask:0xf
	v_fmac_f32_dpp v81, v81, v85 row_shl:1 row_mask:0xf bank_mask:0xf
	v_fmac_f32_dpp v82, v82, v86 row_shl:1 row_mask:0xf bank_mask:0xf
	v_fmac_f32_dpp v83, v83, v87 row_shl:1 row_mask:0xf bank_mask:0xf
	v_mul_f32_dpp v84, v84, v84 row_shl:1 row_mask:0xf bank_mask:0xf
	v_mul_f32_dpp v85, v85, v85 row_shl:1 row_mask:0xf bank_mask:0xf
	v_mul_f32_dpp v86, v86, v86 row_shl:1 row_mask:0xf bank_mask:0xf
	v_mul_f32_dpp v87, v87, v87 row_shl:1 row_mask:0xf bank_mask:0xf
	v_fmac_f32_dpp v80, v80, v84 row_shl:2 row_mask:0xf bank_mask:0xf
	v_fmac_f32_dpp v81, v81, v85 row_shl:2 row_mask:0xf bank_mask:0xf
	v_fmac_f32_dpp v82, v82, v86 row_shl:2 row_mask:0xf bank_mask:0xf
	v_fmac_f32_dpp v83, v83, v87 row_shl:2 row_mask:0xf bank_mask:0xf
	v_mul_f32_dpp v84, v84, v84 row_shl:2 row_mask:0xf bank_mask:0xf
	v_mul_f32_dpp v85, v85, v85 row_shl:2 row_mask:0xf bank_mask:0xf
	v_mul_f32_dpp v86, v86, v86 row_shl:2 row_mask:0xf bank_mask:0xf
	v_mul_f32_dpp v87, v87, v87 row_shl:2 row_mask:0xf bank_mask:0xf
	v_fmac_f32_dpp v80, v80, v84 row_shl:4 row_mask:0xf bank_mask:0xf
	v_fmac_f32_dpp v81, v81, v85 row_shl:4 row_mask:0xf bank_mask:0xf
	v_fmac_f32_dpp v82, v82, v86 row_shl:4 row_mask:0xf bank_mask:0xf
	v_fmac_f32_dpp v83, v83, v87 row_shl:4 row_mask:0xf bank_mask:0xf
	v_mul_f32_dpp v84, v84, v84 row_shl:4 row_mask:0xf bank_mask:0xf
	v_mul_f32_dpp v85, v85, v85 row_shl:4 row_mask:0xf bank_mask:0xf
	v_mul_f32_dpp v86, v86, v86 row_shl:4 row_mask:0xf bank_mask:0xf
	v_mul_f32_dpp v87, v87, v87 row_shl:4 row_mask:0xf bank_mask:0xf
	v_fmac_f32_dpp v80, v80, v84 row_shl:8 row_mask:0xf bank_mask:0xf
	v_fmac_f32_dpp v81, v81, v85 row_shl:8 row_mask:0xf bank_mask:0xf
	v_fmac_f32_dpp v82, v82, v86 row_shl:8 row_mask:0xf bank_mask:0xf
	v_fmac_f32_dpp v83, v83, v87 row_shl:8 row_mask:0xf bank_mask:0xf
	v_mul_f32_dpp v84, v84, v84 row_shl:8 row_mask:0xf bank_mask:0xf
	v_mul_f32_dpp v85, v85, v85 row_shl:8 row_mask:0xf bank_mask:0xf
	v_mul_f32_dpp v86, v86, v86 row_shl:8 row_mask:0xf bank_mask:0xf
	v_mul_f32_dpp v87, v87, v87 row_shl:8 row_mask:0xf bank_mask:0xf
	s_nop 1
	v_mov_b32_dpp v118, v84 row_newbcast:0 row_mask:0xf bank_mask:0xf
	v_mov_b32_dpp v119, v85 row_newbcast:0 row_mask:0xf bank_mask:0xf
	v_mov_b32_dpp v120, v86 row_newbcast:0 row_mask:0xf bank_mask:0xf
	v_mov_b32_dpp v121, v87 row_newbcast:0 row_mask:0xf bank_mask:0xf
	v_fmac_f32_e32 v80, v84, v129
	v_fmac_f32_e32 v81, v85, v173
	v_fmac_f32_e32 v82, v86, v174
	v_fmac_f32_e32 v83, v87, v175
	v_mov_b32_dpp v129, v80 row_newbcast:0 row_mask:0xf bank_mask:0xf
	v_mov_b32_dpp v173, v81 row_newbcast:0 row_mask:0xf bank_mask:0xf
	v_mov_b32_dpp v174, v82 row_newbcast:0 row_mask:0xf bank_mask:0xf
	v_mov_b32_dpp v175, v83 row_newbcast:0 row_mask:0xf bank_mask:0xf
	ds_read_b128 v[80:83], v169 offset:18432
	ds_read_b128 v[88:91], v170 offset:18432
	s_waitcnt lgkmcnt(1)
	v_mfma_f32_16x16x32_bf16 v[84:87], v[36:39], v[80:83], 0
	ds_read_b128 v[92:95], v172 offset:18432
	v_mfma_f32_16x16x32_bf16 v[80:83], v[52:55], v[80:83], 0
	s_waitcnt lgkmcnt(1)
	v_mfma_f32_16x16x32_bf16 v[84:87], v[40:43], v[88:91], v[84:87]
	v_mfma_f32_16x16x32_bf16 v[80:83], v[56:59], v[88:91], v[80:83]
	ds_read_b128 v[88:91], v171 offset:18432
	s_waitcnt lgkmcnt(0)
	v_mfma_f32_16x16x32_bf16 v[84:87], v[44:47], v[88:91], v[84:87]
	v_mfma_f32_16x16x32_bf16 v[80:83], v[60:63], v[88:91], v[80:83]
	v_mfma_f32_16x16x32_bf16 v[88:91], v[48:51], v[92:95], v[84:87]
	v_mfma_f32_16x16x32_bf16 v[80:83], v[64:67], v[92:95], v[80:83]
	ds_read_b128 v[96:99], v155 offset:39936
	s_nop 3
	ds_read_b128 v[84:87], v155 offset:40960
	ds_read_b128 v[92:95], v155 offset:41984
	s_waitcnt lgkmcnt(2)
; template <int PASS> __device__ __forceinline__ void phase_lru(LAS unsigned char* lds, const bf16_t* Z, const bf16_t* WL, float* LSUM, const float* LCAR, bf16_t* RNN,
;                                                               int S, int tid, int lane, int wave, int G) {
;     ...
;                 for (int tt = 0; tt < 4; ++tt) { const int t = 3 - tt;
;                     f32x4 gr = (f32x4){0.f, 0.f, 0.f, 0.f}, gi = gr;
; #pragma unroll
;                     for (int s = 0; s < 4; ++s) { const bf16x8 bfr = *(const LAS bf16x8*)(lds + LRU_XC + off_b(16 * t + c, 4 * s + g4));
;                         gr = __builtin_amdgcn_mfma_f32_16x16x32_bf16(wf[2][s], bfr, gr, 0, 0, 0); gi = __builtin_amdgcn_mfma_f32_16x16x32_bf16(wf[3][s], bfr, gi, 0, 0, 0); }
;                     f32x4 ov;
;                     const f32x4 kba = kc[3 * 64 + lane], kbx = kc[4 * 64 + lane], ksp = kc[5 * 64 + lane];
;                     f32x4 av, hv;
; #pragma unroll
;                     for (int j = 0; j < 4; ++j) {
;                         const float rg = __builtin_amdgcn_rcpf(1.0f + __builtin_amdgcn_exp2f(fmaf(gr[j], -LOG2E, kba[j])));
;                         const float ig = __builtin_amdgcn_rcpf(1.0f + __builtin_amdgcn_exp2f(fmaf(gi[j], -LOG2E, kbx[j])));
;                         const float a_ = __builtin_amdgcn_exp2f(rg * ksp[j]);
;                         av[j] = a_; hv[j] = __builtin_amdgcn_sqrtf(fmaf(-a_, a_, 1.0f)) * (ig * xc[t][j]);
;                     }
;                     lru_scan4_bwd(av, hv);
; #pragma unroll
;                     for (int j = 0; j < 4; ++j) {
;                         const float hfull = fmaf(av[j], Hc[j], hv[j]);
;                         Hc[j] = __shfl(hfull, lane & 48);
;                         if (PASS == 0) Ac[j] *= __shfl(av[j], lane & 48);
;                         if (PASS == 1) { const unsigned rw = j < 2 ? ryr[t].x : ryr[t].y; const float y = (j & 1) ? bfhi(rw) : bflo(rw);
;                             const float ge = y * __builtin_amdgcn_rcpf(1.0f + __builtin_amdgcn_exp2f((-2.3022082f * y) * fmaf(0.044715f * y, y, 1.0f)));
;                             ov[j] = (hf[t][j] + hfull) * ge; }
;                     }
;                     if (PASS == 1) { u32x2 w; w.x = pk2(ov[0], ov[1]); w.y = pk2(ov[2], ov[3]); *(u32x2*)(RNN + (size_t)(t0 + 16 * t + c) * LW + ch0) = w; }
;                     __builtin_amdgcn_sched_barrier(0);
	v_fmamk_f32 v88, v88, 0xbfb8aa3b, v96
	v_exp_f32_e32 v88, v88
	s_waitcnt lgkmcnt(1)
	v_fmamk_f32 v80, v80, 0xbfb8aa3b, v84
	v_exp_f32_e32 v80, v80
	v_fmamk_f32 v81, v81, 0xbfb8aa3b, v85
	v_add_f32_e32 v88, 1.0, v88
	v_rcp_f32_e32 v88, v88
	v_add_f32_e32 v80, 1.0, v80
	v_rcp_f32_e32 v80, v80
	v_exp_f32_e32 v81, v81
	s_waitcnt lgkmcnt(0)
	v_mul_f32_e32 v84, v92, v88
	v_exp_f32_e32 v84, v84
	v_mul_f32_e32 v80, v116, v80
	v_add_f32_e32 v81, 1.0, v81
	v_rcp_f32_e32 v81, v81
	v_fma_f32 v88, -v84, v84, 1.0
	v_sqrt_f32_e32 v88, v88
	v_fmamk_f32 v82, v82, 0xbfb8aa3b, v86
	v_mul_f32_e32 v81, v117, v81
	v_exp_f32_e32 v82, v82
	v_mul_f32_e32 v80, v80, v88
	v_fmamk_f32 v88, v89, 0xbfb8aa3b, v97
	v_exp_f32_e32 v88, v88
	v_add_f32_e32 v82, 1.0, v82
	v_rcp_f32_e32 v82, v82
	v_fmac_f32_e32 v99, 0xbfb8aa3b, v91
	v_add_f32_e32 v88, 1.0, v88
	v_rcp_f32_e32 v88, v88
	v_mul_f32_e32 v82, v114, v82
	v_fmac_f32_e32 v87, 0xbfb8aa3b, v83
	v_exp_f32_e32 v83, v87
	v_mul_f32_e32 v85, v93, v88
	v_exp_f32_e32 v88, v85
	v_add_f32_e32 v83, 1.0, v83
	v_rcp_f32_e32 v83, v83
	v_fma_f32 v85, -v88, v88, 1.0
	v_sqrt_f32_e32 v85, v85
	v_mul_f32_e32 v83, v115, v83
	v_mul_f32_e32 v81, v81, v85
	v_fmamk_f32 v85, v90, 0xbfb8aa3b, v98
	v_exp_f32_e32 v85, v85
	s_nop 0
	v_add_f32_e32 v85, 1.0, v85
	v_rcp_f32_e32 v85, v85
	s_nop 0
	v_mul_f32_e32 v85, v94, v85
	v_exp_f32_e32 v89, v85
	s_nop 0
	v_fma_f32 v85, -v89, v89, 1.0
	v_sqrt_f32_e32 v85, v85
	s_nop 0
	v_mul_f32_e32 v82, v82, v85
	v_exp_f32_e32 v85, v99
	s_nop 0
	v_add_f32_e32 v85, 1.0, v85
	v_rcp_f32_e32 v85, v85
	s_nop 0
	v_mul_f32_e32 v85, v95, v85
	v_exp_f32_e32 v90, v85
	s_nop 0
	v_fma_f32 v85, -v90, v90, 1.0
	v_sqrt_f32_e32 v85, v85
	s_nop 0
	v_mul_f32_e32 v91, v83, v85
	s_nop 1
	v_fmac_f32_dpp v80, v80, v84 row_shl:1 row_mask:0xf bank_mask:0xf
	v_fmac_f32_dpp v81, v81, v88 row_shl:1 row_mask:0xf bank_mask:0xf
	v_fmac_f32_dpp v82, v82, v89 row_shl:1 row_mask:0xf bank_mask:0xf
	v_fmac_f32_dpp v91, v91, v90 row_shl:1 row_mask:0xf bank_mask:0xf
	v_mul_f32_dpp v84, v84, v84 row_shl:1 row_mask:0xf bank_mask:0xf
	v_mul_f32_dpp v88, v88, v88 row_shl:1 row_mask:0xf bank_mask:0xf
	v_mul_f32_dpp v89, v89, v89 row_shl:1 row_mask:0xf bank_mask:0xf
	v_mul_f32_dpp v90, v90, v90 row_shl:1 row_mask:0xf bank_mask:0xf
	v_fmac_f32_dpp v80, v80, v84 row_shl:2 row_mask:0xf bank_mask:0xf
	v_fmac_f32_dpp v81, v81, v88 row_shl:2 row_mask:0xf bank_mask:0xf
	v_fmac_f32_dpp v82, v82, v89 row_shl:2 row_mask:0xf bank_mask:0xf
	v_fmac_f32_dpp v91, v91, v90 row_shl:2 row_mask:0xf bank_mask:0xf
	v_mul_f32_dpp v84, v84, v84 row_shl:2 row_mask:0xf bank_mask:0xf
	v_mul_f32_dpp v88, v88, v88 row_shl:2 row_mask:0xf bank_mask:0xf
	v_mul_f32_dpp v89, v89, v89 row_shl:2 row_mask:0xf bank_mask:0xf
	v_mul_f32_dpp v90, v90, v90 row_shl:2 row_mask:0xf bank_mask:0xf
	v_fmac_f32_dpp v80, v80, v84 row_shl:4 row_mask:0xf bank_mask:0xf
	v_fmac_f32_dpp v81, v81, v88 row_shl:4 row_mask:0xf bank_mask:0xf
	v_fmac_f32_dpp v82, v82, v89 row_shl:4 row_mask:0xf bank_mask:0xf
	v_fmac_f32_dpp v91, v91, v90 row_shl:4 row_mask:0xf bank_mask:0xf
	v_mul_f32_dpp v84, v84, v84 row_shl:4 row_mask:0xf bank_mask:0xf
	v_mul_f32_dpp v88, v88, v88 row_shl:4 row_mask:0xf bank_mask:0xf
	v_mul_f32_dpp v89, v89, v89 row_shl:4 row_mask:0xf bank_mask:0xf
	v_mul_f32_dpp v90, v90, v90 row_shl:4 row_mask:0xf bank_mask:0xf
	v_fmac_f32_dpp v80, v80, v84 row_shl:8 row_mask:0xf bank_mask:0xf
	v_fmac_f32_dpp v81, v81, v88 row_shl:8 row_mask:0xf bank_mask:0xf
	v_fmac_f32_dpp v82, v82, v89 row_shl:8 row_mask:0xf bank_mask:0xf
	v_fmac_f32_dpp v91, v91, v90 row_shl:8 row_mask:0xf bank_mask:0xf
	v_mul_f32_dpp v84, v84, v84 row_shl:8 row_mask:0xf bank_mask:0xf
	v_mul_f32_dpp v88, v88, v88 row_shl:8 row_mask:0xf bank_mask:0xf
	v_mul_f32_dpp v89, v89, v89 row_shl:8 row_mask:0xf bank_mask:0xf
	v_mul_f32_dpp v90, v90, v90 row_shl:8 row_mask:0xf bank_mask:0xf
	s_nop 1
	v_mov_b32_dpp v86, v84 row_newbcast:0 row_mask:0xf bank_mask:0xf
	v_fmac_f32_e32 v80, v84, v129
	v_fmac_f32_e32 v81, v88, v173
	v_fmac_f32_e32 v82, v89, v174
	v_fmac_f32_e32 v91, v90, v175
	v_mov_b32_dpp v87, v80 row_newbcast:0 row_mask:0xf bank_mask:0xf
	v_mov_b32_dpp v85, v81 row_newbcast:0 row_mask:0xf bank_mask:0xf
	v_mov_b32_dpp v84, v88 row_newbcast:0 row_mask:0xf bank_mask:0xf
	v_mov_b32_dpp v83, v82 row_newbcast:0 row_mask:0xf bank_mask:0xf
	v_mov_b32_dpp v82, v89 row_newbcast:0 row_mask:0xf bank_mask:0xf
	v_mov_b32_dpp v81, v91 row_newbcast:0 row_mask:0xf bank_mask:0xf
	v_mov_b32_dpp v80, v90 row_newbcast:0 row_mask:0xf bank_mask:0xf
	s_and_saveexec_b64 s[18:19], s[40:41]
	s_cbranch_execz .LBB0_220
	v_mul_f32_e32 v88, v128, v125
	v_mul_f32_e32 v88, v88, v121
	s_waitcnt lgkmcnt(0)
	v_mul_f32_e32 v80, v88, v80
	v_mul_f32_e32 v88, v127, v124
	v_mul_f32_e32 v88, v88, v120
	v_mul_f32_e32 v82, v88, v82
	v_mul_f32_e32 v88, v126, v123
	v_mul_f32_e32 v1, v1, v122
	v_mul_f32_e32 v88, v88, v119
	v_mul_f32_e32 v1, v1, v118
	v_add_co_u32_e32 v90, vcc, 0x8303000, v144
	v_mul_f32_e32 v84, v88, v84
	v_mul_f32_e32 v86, v1, v86
	v_lshl_add_u64 v[88:89], v[146:147], 0, s[50:51]
	v_addc_co_u32_e32 v91, vcc, 0, v145, vcc
	global_store_dwordx2 v[90:91], v[86:87], off
	v_or_b32_e32 v86, 8, v88
	v_mov_b32_e32 v87, v89
	v_lshl_add_u64 v[86:87], s[10:11], 0, v[86:87]
	global_store_dwordx2 v[86:87], v[84:85], off
	v_or_b32_e32 v84, 16, v88
	v_mov_b32_e32 v85, v89
	v_lshl_add_u64 v[84:85], s[10:11], 0, v[84:85]
	v_or_b32_e32 v88, 24, v88
	global_store_dwordx2 v[84:85], v[82:83], off
	v_lshl_add_u64 v[82:83], s[10:11], 0, v[88:89]
	global_store_dwordx2 v[82:83], v[80:81], off
	s_branch .LBB0_220

; #define PG8_STAGE(bufoff, gbase, voff) do { _Pragma("unroll") for (int _i = 0; _i < 2; ++_i) \
;         __builtin_amdgcn_global_load_lds((const unsigned*)((const char*)(gbase) + (voff)[_i]), (PG8_LAS unsigned*)(lds + (bufoff) + ldsw + _i * 8192), 16, 0, 0); } while (0)
; #define PG8_LDA(dst, b, h) do { _Pragma("unroll") for (int m = 0; m < 4; ++m) _Pragma("unroll") for (int k = 0; k < 2; ++k) dst[m][k] = *(const PG8_LAS bf16x8*)(lds + PG8_SA(b, h) + aoff + m * 2048 + k * 1024); } while (0)
; #define PG8_LDB(dst, b, h) do { _Pragma("unroll") for (int n = 0; n < 2; ++n) _Pragma("unroll") for (int k = 0; k < 2; ++k) dst[n][k] = *(const PG8_LAS bf16x8*)(lds + PG8_SB(b, h) + boff + n * 2048 + k * 1024); } while (0)
; #define PG8_MMA(ai, bj, At, Bt) do { __builtin_amdgcn_s_setprio(1); _Pragma("unroll") for (int m = 0; m < 4; ++m) _Pragma("unroll") for (int n = 0; n < 2; ++n) _Pragma("unroll") for (int k = 0; k < 2; ++k) \
;         acc[ai][bj][m][n] = __builtin_amdgcn_mfma_f32_16x16x32_bf16(Bt[n][k], At[m][k], acc[ai][bj][m][n], 0, 0, 0); __builtin_amdgcn_s_setprio(0); } while (0)
; #define PG8_WAIT_V(n) asm volatile("s_waitcnt vmcnt(" #n ")" ::: "memory")
; #define PG8_BAR __builtin_amdgcn_s_barrier()
; template <class Epi, class Sched, bool ALIGN_EPI = false, bool SP2 = false>
; __device__ __forceinline__ void gemm_phase(PG8_LAS unsigned char* lds, const Gemm g, const Sched& S, const Epi& E) {
;     ...
;         for (int t = 0; t < nt; t += 2) {
;             const bool last = (t == nt - 2);
;             const char* a1 = cA + (size_t)(t + 1) * kstep;
;             const char* a2 = last ? nA : cA + (size_t)(t + 2) * kstep; const char* b2 = last ? nB : cB + (size_t)(t + 2) * kstep;
;             const char* a3 = a2 + kstep; const char* b3 = b2 + kstep;
;             if (last && has_next) S.a_ready(nxt);
;             if constexpr (SP2) {
;             PG8_LDB(B0, 0, 0); PG8_LDB(B1, 0, 1); PG8_SCHED; PG8_LDA(At, 0, 0); PG8_STAGE(PG8_SA(1, 1), a1 + hstep, voffA);
;             PG8_WAIT_V(8); PG8_WAIT_L(0); PG8_BAR; PG8_MMA(0, 0, At, B0); PG8_MMA(0, 1, At, B1); PG8_BAR; PG8_SCHED;
;             PG8_LDA(At, 0, 1); PG8_STAGE(PG8_SB(0, 0), b2, voffB); PG8_STAGE(PG8_SB(0, 1), b2 + hstep, voffB); PG8_STAGE(PG8_SA(0, 0), a2, voffA);
;             PG8_WAIT_V(8); PG8_WAIT_L(0); PG8_BAR; PG8_MMA(1, 0, At, B0); PG8_MMA(1, 1, At, B1); PG8_BAR; PG8_SCHED;
.LBB0_281:
	s_add_u32 s18, s36, 0xfff80080
	s_addc_u32 s19, s37, -1
	s_add_i32 s73, 0, 0x10000
	s_cmp_eq_u32 s67, 28
	s_cselect_b32 s43, s9, s19
	s_cselect_b32 s42, s59, s18
	v_add_u32_e32 v163, s73, v160
	s_cselect_b32 s19, s7, s63
	s_cselect_b32 s18, s60, s62
	s_add_i32 s76, 0, 0x14000
	ds_read_b128 v[156:159], v163
	ds_read_b128 v[164:167], v163 offset:1024
	ds_read_b128 v[168:171], v163 offset:2048
	ds_read_b128 v[172:175], v163 offset:3072
	v_add_u32_e32 v163, s76, v160
	ds_read_b128 v[176:179], v163
	ds_read_b128 v[180:183], v163 offset:1024
	ds_read_b128 v[184:187], v163 offset:2048
	ds_read_b128 v[204:207], v163 offset:3072
	v_lshl_add_u64 v[240:241], s[36:37], 0, v[152:153]
	s_add_i32 m0, s30, 0xc000
	ds_read_b128 v[208:211], v162
	ds_read_b128 v[212:215], v162 offset:1024
	ds_read_b128 v[216:219], v162 offset:2048
	ds_read_b128 v[220:223], v162 offset:3072
	ds_read_b128 v[224:227], v162 offset:4096
	ds_read_b128 v[228:231], v162 offset:5120
	ds_read_b128 v[232:235], v162 offset:6144
	ds_read_b128 v[236:239], v162 offset:7168
	global_load_lds_dwordx4 v[240:241], off
	v_lshl_add_u64 v[240:241], s[36:37], 0, v[154:155]
	s_add_i32 m0, s30, 0xe000
	s_nop 0
	global_load_lds_dwordx4 v[240:241], off
	s_nop 0
	s_waitcnt vmcnt(8)
	s_waitcnt lgkmcnt(0)
	s_barrier
	s_setprio 1
	v_mfma_f32_16x16x32_bf16 v[126:129], v[156:159], v[208:211], v[126:129]
	v_mfma_f32_16x16x32_bf16 v[122:125], v[168:171], v[208:211], v[122:125]
	v_mfma_f32_16x16x32_bf16 v[110:113], v[156:159], v[216:219], v[110:113]
	v_mfma_f32_16x16x32_bf16 v[106:109], v[168:171], v[216:219], v[106:109]
	v_mfma_f32_16x16x32_bf16 v[94:97], v[156:159], v[224:227], v[94:97]
	v_mfma_f32_16x16x32_bf16 v[90:93], v[168:171], v[224:227], v[90:93]
	v_mfma_f32_16x16x32_bf16 v[78:81], v[156:159], v[232:235], v[78:81]
	v_mfma_f32_16x16x32_bf16 v[74:77], v[168:171], v[232:235], v[74:77]
	s_setprio 0
	s_setprio 1
	v_mfma_f32_16x16x32_bf16 v[126:129], v[164:167], v[212:215], v[126:129]
	v_mfma_f32_16x16x32_bf16 v[122:125], v[172:175], v[212:215], v[122:125]
	v_mfma_f32_16x16x32_bf16 v[110:113], v[164:167], v[220:223], v[110:113]
	v_mfma_f32_16x16x32_bf16 v[106:109], v[172:175], v[220:223], v[106:109]
	v_mfma_f32_16x16x32_bf16 v[94:97], v[164:167], v[228:231], v[94:97]
	v_mfma_f32_16x16x32_bf16 v[90:93], v[172:175], v[228:231], v[90:93]
	v_mfma_f32_16x16x32_bf16 v[78:81], v[164:167], v[236:239], v[78:81]
	v_mfma_f32_16x16x32_bf16 v[74:77], v[172:175], v[236:239], v[74:77]
	s_setprio 0
	s_setprio 1
	v_mfma_f32_16x16x32_bf16 v[118:121], v[176:179], v[208:211], v[118:121]
	v_mfma_f32_16x16x32_bf16 v[114:117], v[184:187], v[208:211], v[114:117]
	v_mfma_f32_16x16x32_bf16 v[102:105], v[176:179], v[216:219], v[102:105]
	v_mfma_f32_16x16x32_bf16 v[98:101], v[184:187], v[216:219], v[98:101]
	v_mfma_f32_16x16x32_bf16 v[86:89], v[176:179], v[224:227], v[86:89]
	v_mfma_f32_16x16x32_bf16 v[82:85], v[184:187], v[224:227], v[82:85]
	v_mfma_f32_16x16x32_bf16 v[70:73], v[176:179], v[232:235], v[70:73]
	v_mfma_f32_16x16x32_bf16 v[66:69], v[184:187], v[232:235], v[66:69]
	s_setprio 0
	s_setprio 1
	v_mfma_f32_16x16x32_bf16 v[118:121], v[180:183], v[212:215], v[118:121]
	v_mfma_f32_16x16x32_bf16 v[114:117], v[204:207], v[212:215], v[114:117]
	v_mfma_f32_16x16x32_bf16 v[102:105], v[180:183], v[220:223], v[102:105]
	v_mfma_f32_16x16x32_bf16 v[98:101], v[204:207], v[220:223], v[98:101]
	v_mfma_f32_16x16x32_bf16 v[86:89], v[180:183], v[228:231], v[86:89]
	v_mfma_f32_16x16x32_bf16 v[82:85], v[204:207], v[228:231], v[82:85]
	v_mfma_f32_16x16x32_bf16 v[70:73], v[180:183], v[236:239], v[70:73]
	v_mfma_f32_16x16x32_bf16 v[66:69], v[204:207], v[236:239], v[66:69]
	s_setprio 0
	s_barrier
	s_add_i32 s73, s73, s28
	v_lshl_add_u64 v[240:241], s[18:19], 0, v[146:147]
	s_mov_b32 m0, s73
	ds_read_b128 v[208:211], v162 offset:16384
	ds_read_b128 v[212:215], v162 offset:17408
	ds_read_b128 v[216:219], v162 offset:18432
	ds_read_b128 v[220:223], v162 offset:19456
	ds_read_b128 v[224:227], v162 offset:20480
	ds_read_b128 v[228:231], v162 offset:21504
	ds_read_b128 v[232:235], v162 offset:22528
	ds_read_b128 v[236:239], v162 offset:23552
	global_load_lds_dwordx4 v[240:241], off
	s_add_i32 m0, s73, 0x2000
	s_add_u32 s78, s18, 0x80000
	v_lshl_add_u64 v[242:243], s[18:19], 0, v[142:143]
	s_addc_u32 s79, s19, 0
	s_add_i32 s73, s76, s28
	global_load_lds_dwordx4 v[242:243], off
	v_lshl_add_u64 v[244:245], s[78:79], 0, v[146:147]
	s_mov_b32 m0, s73
	v_lshl_add_u64 v[246:247], s[42:43], 0, v[144:145]
	global_load_lds_dwordx4 v[244:245], off
	v_lshl_add_u64 v[244:245], s[78:79], 0, v[142:143]
	s_add_i32 m0, s73, 0x2000
	s_nop 0
	global_load_lds_dwordx4 v[244:245], off
	v_lshl_add_u64 v[244:245], s[42:43], 0, v[148:149]
	s_mov_b32 m0, s30
	s_nop 0
	global_load_lds_dwordx4 v[244:245], off
	s_mov_b32 m0, s34
	s_nop 0
	global_load_lds_dwordx4 v[246:247], off
	s_waitcnt vmcnt(8)
	s_waitcnt lgkmcnt(0)
	s_barrier
; #define PG8_STAGE(bufoff, gbase, voff) do { _Pragma("unroll") for (int _i = 0; _i < 2; ++_i) \
;         __builtin_amdgcn_global_load_lds((const unsigned*)((const char*)(gbase) + (voff)[_i]), (PG8_LAS unsigned*)(lds + (bufoff) + ldsw + _i * 8192), 16, 0, 0); } while (0)
; #define PG8_LDA(dst, b, h) do { _Pragma("unroll") for (int m = 0; m < 4; ++m) _Pragma("unroll") for (int k = 0; k < 2; ++k) dst[m][k] = *(const PG8_LAS bf16x8*)(lds + PG8_SA(b, h) + aoff + m * 2048 + k * 1024); } while (0)
; #define PG8_LDB(dst, b, h) do { _Pragma("unroll") for (int n = 0; n < 2; ++n) _Pragma("unroll") for (int k = 0; k < 2; ++k) dst[n][k] = *(const PG8_LAS bf16x8*)(lds + PG8_SB(b, h) + boff + n * 2048 + k * 1024); } while (0)
; #define PG8_MMA(ai, bj, At, Bt) do { __builtin_amdgcn_s_setprio(1); _Pragma("unroll") for (int m = 0; m < 4; ++m) _Pragma("unroll") for (int n = 0; n < 2; ++n) _Pragma("unroll") for (int k = 0; k < 2; ++k) \
;         acc[ai][bj][m][n] = __builtin_amdgcn_mfma_f32_16x16x32_bf16(Bt[n][k], At[m][k], acc[ai][bj][m][n], 0, 0, 0); __builtin_amdgcn_s_setprio(0); } while (0)
; #define PG8_WAIT_V(n) asm volatile("s_waitcnt vmcnt(" #n ")" ::: "memory")
; #define PG8_WAIT_L(n) asm volatile("s_waitcnt lgkmcnt(" #n ")" ::: "memory")
; #define PG8_BAR __builtin_amdgcn_s_barrier()
; #define PG8_SCHED __builtin_amdgcn_sched_barrier(0)
; template <class Epi, class Sched, bool ALIGN_EPI = false, bool SP2 = false>
; __device__ __forceinline__ void gemm_phase(PG8_LAS unsigned char* lds, const Gemm g, const Sched& S, const Epi& E) {
;     ...
;             PG8_WAIT_V(8); PG8_WAIT_L(0); PG8_BAR; PG8_MMA(1, 0, At, B0); PG8_MMA(1, 1, At, B1); PG8_BAR; PG8_SCHED;
;             PG8_LDB(B0, 1, 0); PG8_LDB(B1, 1, 1); PG8_SCHED; PG8_LDA(At, 1, 0); PG8_STAGE(PG8_SA(0, 1), a2 + hstep, voffA);
;             PG8_WAIT_V(8); PG8_WAIT_L(0); PG8_BAR; PG8_MMA(0, 0, At, B0); PG8_MMA(0, 1, At, B1); PG8_BAR; PG8_SCHED;
	s_setprio 1
	v_mfma_f32_16x16x32_bf16 v[62:65], v[156:159], v[208:211], v[62:65]
	v_mfma_f32_16x16x32_bf16 v[58:61], v[168:171], v[208:211], v[58:61]
	v_mfma_f32_16x16x32_bf16 v[46:49], v[156:159], v[216:219], v[46:49]
	v_mfma_f32_16x16x32_bf16 v[42:45], v[168:171], v[216:219], v[42:45]
	v_mfma_f32_16x16x32_bf16 v[30:33], v[156:159], v[224:227], v[30:33]
	v_mfma_f32_16x16x32_bf16 v[26:29], v[168:171], v[224:227], v[26:29]
	v_mfma_f32_16x16x32_bf16 v[14:17], v[156:159], v[232:235], v[14:17]
	v_mfma_f32_16x16x32_bf16 v[10:13], v[168:171], v[232:235], v[10:13]
	s_setprio 0
	s_setprio 1
	v_mfma_f32_16x16x32_bf16 v[62:65], v[164:167], v[212:215], v[62:65]
	v_mfma_f32_16x16x32_bf16 v[58:61], v[172:175], v[212:215], v[58:61]
	v_mfma_f32_16x16x32_bf16 v[46:49], v[164:167], v[220:223], v[46:49]
	v_mfma_f32_16x16x32_bf16 v[42:45], v[172:175], v[220:223], v[42:45]
	v_mfma_f32_16x16x32_bf16 v[30:33], v[164:167], v[228:231], v[30:33]
	v_mfma_f32_16x16x32_bf16 v[26:29], v[172:175], v[228:231], v[26:29]
	v_mfma_f32_16x16x32_bf16 v[14:17], v[164:167], v[236:239], v[14:17]
	v_mfma_f32_16x16x32_bf16 v[10:13], v[172:175], v[236:239], v[10:13]
	s_setprio 0
	s_setprio 1
	v_mfma_f32_16x16x32_bf16 v[54:57], v[176:179], v[208:211], v[54:57]
	v_mfma_f32_16x16x32_bf16 v[50:53], v[184:187], v[208:211], v[50:53]
	v_mfma_f32_16x16x32_bf16 v[38:41], v[176:179], v[216:219], v[38:41]
	v_mfma_f32_16x16x32_bf16 v[34:37], v[184:187], v[216:219], v[34:37]
	v_mfma_f32_16x16x32_bf16 v[22:25], v[176:179], v[224:227], v[22:25]
	v_mfma_f32_16x16x32_bf16 v[18:21], v[184:187], v[224:227], v[18:21]
	v_mfma_f32_16x16x32_bf16 v[6:9], v[176:179], v[232:235], v[6:9]
	v_mfma_f32_16x16x32_bf16 v[2:5], v[184:187], v[232:235], v[2:5]
	s_setprio 0
	s_setprio 1
	v_mfma_f32_16x16x32_bf16 v[54:57], v[180:183], v[212:215], v[54:57]
	v_mfma_f32_16x16x32_bf16 v[50:53], v[204:207], v[212:215], v[50:53]
	v_mfma_f32_16x16x32_bf16 v[38:41], v[180:183], v[220:223], v[38:41]
	v_mfma_f32_16x16x32_bf16 v[34:37], v[204:207], v[220:223], v[34:37]
	v_mfma_f32_16x16x32_bf16 v[22:25], v[180:183], v[228:231], v[22:25]
	v_mfma_f32_16x16x32_bf16 v[18:21], v[204:207], v[228:231], v[18:21]
	v_mfma_f32_16x16x32_bf16 v[6:9], v[180:183], v[236:239], v[6:9]
	v_mfma_f32_16x16x32_bf16 v[2:5], v[204:207], v[236:239], v[2:5]
	s_setprio 0
	s_barrier
	s_add_i32 s73, 0, 0x18000
	v_add_u32_e32 v163, s73, v160
	s_add_i32 s76, 0, 0x1c000
	ds_read_b128 v[156:159], v163
	ds_read_b128 v[164:167], v163 offset:1024
	ds_read_b128 v[168:171], v163 offset:2048
	ds_read_b128 v[172:175], v163 offset:3072
	v_add_u32_e32 v163, s76, v160
	ds_read_b128 v[176:179], v163
	ds_read_b128 v[180:183], v163 offset:1024
	ds_read_b128 v[184:187], v163 offset:2048
	ds_read_b128 v[204:207], v163 offset:3072
	s_add_u32 s42, s42, 0x80000
	s_addc_u32 s43, s43, 0
	s_mov_b32 m0, s44
	v_lshl_add_u64 v[248:249], s[42:43], 0, v[148:149]
	ds_read_b128 v[208:211], v162 offset:32768
	ds_read_b128 v[212:215], v162 offset:33792
	ds_read_b128 v[216:219], v162 offset:34816
	ds_read_b128 v[220:223], v162 offset:35840
	ds_read_b128 v[224:227], v162 offset:36864
	ds_read_b128 v[228:231], v162 offset:37888
	ds_read_b128 v[232:235], v162 offset:38912
	ds_read_b128 v[236:239], v162 offset:39936
	global_load_lds_dwordx4 v[248:249], off
	v_lshl_add_u64 v[248:249], s[42:43], 0, v[144:145]
	s_mov_b32 m0, s45
	s_nop 0
	global_load_lds_dwordx4 v[248:249], off
	s_waitcnt vmcnt(8)
	s_waitcnt lgkmcnt(0)
	s_barrier
	s_setprio 1
	v_mfma_f32_16x16x32_bf16 v[126:129], v[156:159], v[208:211], v[126:129]
	v_mfma_f32_16x16x32_bf16 v[122:125], v[168:171], v[208:211], v[122:125]
	v_mfma_f32_16x16x32_bf16 v[110:113], v[156:159], v[216:219], v[110:113]
	v_mfma_f32_16x16x32_bf16 v[106:109], v[168:171], v[216:219], v[106:109]
	v_mfma_f32_16x16x32_bf16 v[94:97], v[156:159], v[224:227], v[94:97]
	v_mfma_f32_16x16x32_bf16 v[90:93], v[168:171], v[224:227], v[90:93]
	v_mfma_f32_16x16x32_bf16 v[78:81], v[156:159], v[232:235], v[78:81]
	v_mfma_f32_16x16x32_bf16 v[74:77], v[168:171], v[232:235], v[74:77]
	s_setprio 0
	s_setprio 1
	v_mfma_f32_16x16x32_bf16 v[126:129], v[164:167], v[212:215], v[126:129]
	v_mfma_f32_16x16x32_bf16 v[122:125], v[172:175], v[212:215], v[122:125]
	v_mfma_f32_16x16x32_bf16 v[110:113], v[164:167], v[220:223], v[110:113]
	v_mfma_f32_16x16x32_bf16 v[106:109], v[172:175], v[220:223], v[106:109]
	v_mfma_f32_16x16x32_bf16 v[94:97], v[164:167], v[228:231], v[94:97]
	v_mfma_f32_16x16x32_bf16 v[90:93], v[172:175], v[228:231], v[90:93]
	v_mfma_f32_16x16x32_bf16 v[78:81], v[164:167], v[236:239], v[78:81]
	v_mfma_f32_16x16x32_bf16 v[74:77], v[172:175], v[236:239], v[74:77]
	s_setprio 0
	s_setprio 1
	v_mfma_f32_16x16x32_bf16 v[118:121], v[176:179], v[208:211], v[118:121]
	v_mfma_f32_16x16x32_bf16 v[114:117], v[184:187], v[208:211], v[114:117]
	v_mfma_f32_16x16x32_bf16 v[102:105], v[176:179], v[216:219], v[102:105]
	v_mfma_f32_16x16x32_bf16 v[98:101], v[184:187], v[216:219], v[98:101]
	v_mfma_f32_16x16x32_bf16 v[86:89], v[176:179], v[224:227], v[86:89]
	v_mfma_f32_16x16x32_bf16 v[82:85], v[184:187], v[224:227], v[82:85]
	v_mfma_f32_16x16x32_bf16 v[70:73], v[176:179], v[232:235], v[70:73]
	v_mfma_f32_16x16x32_bf16 v[66:69], v[184:187], v[232:235], v[66:69]
	s_setprio 0
	s_setprio 1
	v_mfma_f32_16x16x32_bf16 v[118:121], v[180:183], v[212:215], v[118:121]
	v_mfma_f32_16x16x32_bf16 v[114:117], v[204:207], v[212:215], v[114:117]
	v_mfma_f32_16x16x32_bf16 v[102:105], v[180:183], v[220:223], v[102:105]
	v_mfma_f32_16x16x32_bf16 v[98:101], v[204:207], v[220:223], v[98:101]
	v_mfma_f32_16x16x32_bf16 v[86:89], v[180:183], v[228:231], v[86:89]
	v_mfma_f32_16x16x32_bf16 v[82:85], v[204:207], v[228:231], v[82:85]
	v_mfma_f32_16x16x32_bf16 v[70:73], v[180:183], v[236:239], v[70:73]
	v_mfma_f32_16x16x32_bf16 v[66:69], v[204:207], v[236:239], v[66:69]
	s_setprio 0
	s_barrier
; #define PG8_STAGE(bufoff, gbase, voff) do { _Pragma("unroll") for (int _i = 0; _i < 2; ++_i) \
;         __builtin_amdgcn_global_load_lds((const unsigned*)((const char*)(gbase) + (voff)[_i]), (PG8_LAS unsigned*)(lds + (bufoff) + ldsw + _i * 8192), 16, 0, 0); } while (0)
; #define PG8_LDA(dst, b, h) do { _Pragma("unroll") for (int m = 0; m < 4; ++m) _Pragma("unroll") for (int k = 0; k < 2; ++k) dst[m][k] = *(const PG8_LAS bf16x8*)(lds + PG8_SA(b, h) + aoff + m * 2048 + k * 1024); } while (0)
; #define PG8_MMA(ai, bj, At, Bt) do { __builtin_amdgcn_s_setprio(1); _Pragma("unroll") for (int m = 0; m < 4; ++m) _Pragma("unroll") for (int n = 0; n < 2; ++n) _Pragma("unroll") for (int k = 0; k < 2; ++k) \
;         acc[ai][bj][m][n] = __builtin_amdgcn_mfma_f32_16x16x32_bf16(Bt[n][k], At[m][k], acc[ai][bj][m][n], 0, 0, 0); __builtin_amdgcn_s_setprio(0); } while (0)
; #define PG8_WAIT_V(n) asm volatile("s_waitcnt vmcnt(" #n ")" ::: "memory")
; #define PG8_WAIT_L(n) asm volatile("s_waitcnt lgkmcnt(" #n ")" ::: "memory")
; #define PG8_BAR __builtin_amdgcn_s_barrier()
; #define PG8_SCHED __builtin_amdgcn_sched_barrier(0)
; template <class Epi, class Sched, bool ALIGN_EPI = false, bool SP2 = false>
; __device__ __forceinline__ void gemm_phase(PG8_LAS unsigned char* lds, const Gemm g, const Sched& S, const Epi& E) {
;     ...
;         for (int t = 0; t < nt; t += 2) {
;             const bool last = (t == nt - 2);
;             const char* a1 = cA + (size_t)(t + 1) * kstep;
;             const char* a2 = last ? nA : cA + (size_t)(t + 2) * kstep; const char* b2 = last ? nB : cB + (size_t)(t + 2) * kstep;
;     ...
;             PG8_LDA(At, 1, 1); PG8_STAGE(PG8_SB(1, 0), b3, voffB); PG8_STAGE(PG8_SB(1, 1), b3 + hstep, voffB); PG8_STAGE(PG8_SA(1, 0), a3, voffA);
;             PG8_WAIT_V(8); PG8_WAIT_L(0); PG8_BAR; PG8_MMA(1, 0, At, B0); PG8_MMA(1, 1, At, B1); PG8_BAR; PG8_SCHED;
	s_add_i32 s42, s73, s28
	v_lshl_add_u64 v[240:241], v[240:241], 0, s[68:69]
	s_mov_b32 m0, s42
	ds_read_b128 v[208:211], v162 offset:49152
	ds_read_b128 v[212:215], v162 offset:50176
	ds_read_b128 v[216:219], v162 offset:51200
	ds_read_b128 v[220:223], v162 offset:52224
	ds_read_b128 v[224:227], v162 offset:53248
	ds_read_b128 v[228:231], v162 offset:54272
	ds_read_b128 v[232:235], v162 offset:55296
	ds_read_b128 v[236:239], v162 offset:56320
	global_load_lds_dwordx4 v[240:241], off
	s_add_i32 m0, s42, 0x2000
	s_add_u32 s18, s18, 0x80080
	v_lshl_add_u64 v[240:241], v[242:243], 0, s[68:69]
	s_addc_u32 s19, s19, 0
	s_add_i32 s42, s76, s28
	global_load_lds_dwordx4 v[240:241], off
	v_lshl_add_u64 v[240:241], s[18:19], 0, v[146:147]
	s_mov_b32 m0, s42
	s_nop 0
	global_load_lds_dwordx4 v[240:241], off
	v_lshl_add_u64 v[240:241], s[18:19], 0, v[142:143]
	s_add_i32 m0, s42, 0x2000
	s_nop 0
	global_load_lds_dwordx4 v[240:241], off
	v_lshl_add_u64 v[240:241], v[244:245], 0, s[68:69]
	s_mov_b32 m0, s46
	s_nop 0
	global_load_lds_dwordx4 v[240:241], off
	v_lshl_add_u64 v[240:241], v[246:247], 0, s[68:69]
	s_mov_b32 m0, s47
	s_nop 0
	global_load_lds_dwordx4 v[240:241], off
	s_nop 0
	s_waitcnt vmcnt(8)
	s_waitcnt lgkmcnt(0)
	s_barrier
	s_setprio 1
	v_mfma_f32_16x16x32_bf16 v[62:65], v[156:159], v[208:211], v[62:65]
	v_mfma_f32_16x16x32_bf16 v[58:61], v[168:171], v[208:211], v[58:61]
	v_mfma_f32_16x16x32_bf16 v[46:49], v[156:159], v[216:219], v[46:49]
	v_mfma_f32_16x16x32_bf16 v[42:45], v[168:171], v[216:219], v[42:45]
	v_mfma_f32_16x16x32_bf16 v[30:33], v[156:159], v[224:227], v[30:33]
	v_mfma_f32_16x16x32_bf16 v[26:29], v[168:171], v[224:227], v[26:29]
	v_mfma_f32_16x16x32_bf16 v[14:17], v[156:159], v[232:235], v[14:17]
	v_mfma_f32_16x16x32_bf16 v[10:13], v[168:171], v[232:235], v[10:13]
	s_setprio 0
	s_setprio 1
	v_mfma_f32_16x16x32_bf16 v[62:65], v[164:167], v[212:215], v[62:65]
	v_mfma_f32_16x16x32_bf16 v[58:61], v[172:175], v[212:215], v[58:61]
	v_mfma_f32_16x16x32_bf16 v[46:49], v[164:167], v[220:223], v[46:49]
	v_mfma_f32_16x16x32_bf16 v[42:45], v[172:175], v[220:223], v[42:45]
	v_mfma_f32_16x16x32_bf16 v[30:33], v[164:167], v[228:231], v[30:33]
	v_mfma_f32_16x16x32_bf16 v[26:29], v[172:175], v[228:231], v[26:29]
	v_mfma_f32_16x16x32_bf16 v[14:17], v[164:167], v[236:239], v[14:17]
	v_mfma_f32_16x16x32_bf16 v[10:13], v[172:175], v[236:239], v[10:13]
	s_setprio 0
	s_setprio 1
	v_mfma_f32_16x16x32_bf16 v[54:57], v[176:179], v[208:211], v[54:57]
	v_mfma_f32_16x16x32_bf16 v[50:53], v[184:187], v[208:211], v[50:53]
	v_mfma_f32_16x16x32_bf16 v[38:41], v[176:179], v[216:219], v[38:41]
	v_mfma_f32_16x16x32_bf16 v[34:37], v[184:187], v[216:219], v[34:37]
	v_mfma_f32_16x16x32_bf16 v[22:25], v[176:179], v[224:227], v[22:25]
	v_mfma_f32_16x16x32_bf16 v[18:21], v[184:187], v[224:227], v[18:21]
	v_mfma_f32_16x16x32_bf16 v[6:9], v[176:179], v[232:235], v[6:9]
	v_mfma_f32_16x16x32_bf16 v[2:5], v[184:187], v[232:235], v[2:5]
	s_setprio 0
	s_setprio 1
	v_mfma_f32_16x16x32_bf16 v[54:57], v[180:183], v[212:215], v[54:57]
	v_mfma_f32_16x16x32_bf16 v[50:53], v[204:207], v[212:215], v[50:53]
	v_mfma_f32_16x16x32_bf16 v[38:41], v[180:183], v[220:223], v[38:41]
	v_mfma_f32_16x16x32_bf16 v[34:37], v[204:207], v[220:223], v[34:37]
	v_mfma_f32_16x16x32_bf16 v[22:25], v[180:183], v[228:231], v[22:25]
	v_mfma_f32_16x16x32_bf16 v[18:21], v[204:207], v[228:231], v[18:21]
	v_mfma_f32_16x16x32_bf16 v[6:9], v[180:183], v[236:239], v[6:9]
	v_mfma_f32_16x16x32_bf16 v[2:5], v[204:207], v[236:239], v[2:5]
	s_setprio 0
	s_barrier
	s_add_i32 s67, s67, 2
	s_add_u32 s36, s36, 0x100
	s_addc_u32 s37, s37, 0
	s_add_u32 s62, s62, 0x100
	s_addc_u32 s63, s63, 0
	s_cmp_gt_u32 s67, 29
	s_cbranch_scc0 .LBB0_281
	s_and_b64 vcc, exec, s[4:5]
	s_cbranch_vccnz .LBB0_286
	s_cmp_lt_i32 s57, 30
	s_mov_b64 s[18:19], -1
	s_cbranch_scc1 .LBB0_287
